# sc0 hint also on the POST-epilogue streamed loads and the final-normalisation row loads
# speedup vs baseline: 1.0048x; 1.0003x over previous
; __device__ __forceinline__ float bf2f(u16 h) { return __uint_as_float(((unsigned)h) << 16); }
; template <int EPI> ...
;     ...
;     } else {
;       const int hh = nt * 2 + wn;
;       const u16* P = (const u16*)(p.ws + O_P);
;       u16* Y = (u16*)(p.ws + O_Y);
;       const float* bs = (const float*)(p.ws + O_BS);
;       const int ch0 = hh * 64 + (lane & 31), ch1 = ch0 + 32;
;       const float gg0 = p.in[20][ch0], gg1 = p.in[20][ch1];
;       const float gb0 = p.in[21][ch0], gb1 = p.in[21][ch1];
;       const float mu0 = p.in[11][1536 + ch0], mu1 = p.in[11][1536 + ch1];
; #pragma unroll 16
;       for (int i = 0; i < 16; i++) {
;         const int rl = rbase + (i & 3) + 8 * (i >> 2);
;         const int row = m0 + rl;
;         float o0 = bf2f(Y[(size_t)row * 1024 + 256 + ch0]);
;         float o1 = bf2f(Y[(size_t)row * 1024 + 256 + ch1]);
;         float mean = hsum32(o0 + o1) * (1.0f / 64.0f);
;         float d0 = o0 - mean, d1 = o1 - mean;
;         float var = hsum32(d0 * d0 + d1 * d1) * (1.0f / 64.0f);
;         float rstd = rsqrtf(var + 64e-5f);
;         float pv0 = bf2f(P[(size_t)row * 2816 + 256 + 1536 + ch0]);
;         float pv1 = bf2f(P[(size_t)row * 2816 + 256 + 1536 + ch1]);
;         float pp0 = prevP(p, P, row, 1536 + ch0), pp1 = prevP(p, P, row, 1536 + ch1);
;         float vv0 = pv0 + (pp0 - pv0) * mu0, vv1 = pv1 + (pp1 - pv1) * mu1;
;         float b = bs[((size_t)row * 12 + hh) * 4 + 2];
.Lgc_epi_post:
	s_lshl_b32 s11, s6, 8
	s_lshl_b32 s12, s4, 6
	s_add_u32 s11, s11, s12
	v_add_u32_e32 v238, s11, v248
	s_lshl_b32 s11, s7, 7
	v_lshl_add_u32 v239, v249, 3, s11
	v_lshlrev_b32_e32 v233, 2, v239
	v_lshlrev_b32_e32 v230, 11, v238
	v_lshl_add_u32 v230, v239, 1, v230
	v_add_u32_e32 v230, 0x200, v230
	v_mul_u32_u24_e32 v231, 0x1600, v238
	v_lshl_add_u32 v231, v239, 1, v231
	v_add_u32_e32 v231, 0x7108f00, v231
	v_mul_u32_u24_e32 v232, 0xc0, v238
	s_lshl_b32 s11, s7, 5
	s_add_u32 s11, s11, 0x47c8108
	v_add_u32_e32 v232, s11, v232
	s_cmp_ge_u32 s6, 64
	s_cbranch_scc1 .Lpo_sample
	global_load_dwordx4 v[130:133], v233, s[2:3] offset:0 sc0
	global_load_dwordx4 v[134:137], v233, s[2:3] offset:16 sc0
	global_load_dwordx4 v[138:141], v233, s[2:3] offset:128 sc0
	global_load_dwordx4 v[142:145], v233, s[2:3] offset:144 sc0
	global_load_dwordx4 v[146:149], v233, s[16:17] offset:0 sc0
	global_load_dwordx4 v[150:153], v233, s[16:17] offset:16 sc0
	global_load_dwordx4 v[154:157], v233, s[16:17] offset:128 sc0
	global_load_dwordx4 v[158:161], v233, s[16:17] offset:144 sc0
	global_load_dwordx4 v[162:165], v233, s[0:1] offset:0 sc0
	global_load_dwordx4 v[166:169], v233, s[0:1] offset:16 sc0
	global_load_dwordx4 v[170:173], v233, s[0:1] offset:128 sc0
	global_load_dwordx4 v[174:177], v233, s[0:1] offset:144 sc0
	v_add_u32_e32 v236, 0x0, v230
	v_add_u32_e32 v237, 0x0, v231
	v_subrev_u32_e32 v240, 0x1600, v237
	global_load_dwordx4 v[178:181], v236, s[22:23] offset:0 sc0
	global_load_dwordx4 v[182:185], v236, s[22:23] offset:64 sc0
	global_load_dwordx4 v[186:189], v237, s[96:97] offset:0 sc0
	global_load_dwordx4 v[190:193], v237, s[96:97] offset:64 sc0
	global_load_dwordx4 v[194:197], v240, s[96:97] offset:0 sc0
	global_load_dwordx4 v[198:201], v240, s[96:97] offset:64 sc0
	v_add_u32_e32 v236, 0x0, v232
	s_nop 0
	global_load_dword v234, v236, s[96:97] offset:0
	v_add_u32_e32 v236, 0x8000, v230
	v_add_u32_e32 v237, 0x16000, v231
	v_subrev_u32_e32 v240, 0x1600, v237
	global_load_dwordx4 v[202:205], v236, s[22:23] offset:0 sc0
	global_load_dwordx4 v[206:209], v236, s[22:23] offset:64 sc0
	global_load_dwordx4 v[210:213], v237, s[96:97] offset:0 sc0
	global_load_dwordx4 v[214:217], v237, s[96:97] offset:64 sc0
	global_load_dwordx4 v[218:221], v240, s[96:97] offset:0 sc0
	global_load_dwordx4 v[222:225], v240, s[96:97] offset:64 sc0
	v_add_u32_e32 v236, 0xc00, v232
	s_nop 0
	global_load_dword v235, v236, s[96:97] offset:0
	s_waitcnt vmcnt(14)
	s_waitcnt vmcnt(7)
	s_and_b32 s18, s6, 7
	s_or_b32 s18, s18, s4
	s_cmp_lg_u32 s18, 0
	s_cbranch_scc1 .Lpo_nostart_p0
	v_cmp_eq_u32_e32 vcc, 0, v248
	s_nop 1
	v_cndmask_b32_e64 v194, v194, 0, vcc
	v_cndmask_b32_e64 v195, v195, 0, vcc
	v_cndmask_b32_e64 v196, v196, 0, vcc
	v_cndmask_b32_e64 v197, v197, 0, vcc
	v_cndmask_b32_e64 v198, v198, 0, vcc
	v_cndmask_b32_e64 v199, v199, 0, vcc
	v_cndmask_b32_e64 v200, v200, 0, vcc
	v_cndmask_b32_e64 v201, v201, 0, vcc
.Lpo_nostart_p0:
	v_lshlrev_b32_e32 v240, 16, v178
	v_and_b32_e32 v241, 0xffff0000, v178
	v_add_f32_e32 v244, v240, v241
	v_lshlrev_b32_e32 v240, 16, v179
	v_and_b32_e32 v241, 0xffff0000, v179
	v_add_f32_e32 v244, v244, v240
	v_add_f32_e32 v244, v244, v241
	v_lshlrev_b32_e32 v240, 16, v180
	v_and_b32_e32 v241, 0xffff0000, v180
	v_add_f32_e32 v244, v244, v240
	v_add_f32_e32 v244, v244, v241
	v_lshlrev_b32_e32 v240, 16, v181
	v_and_b32_e32 v241, 0xffff0000, v181
	v_add_f32_e32 v244, v244, v240
	v_add_f32_e32 v244, v244, v241
	v_lshlrev_b32_e32 v240, 16, v182
	v_and_b32_e32 v241, 0xffff0000, v182
	v_add_f32_e32 v244, v244, v240
	v_add_f32_e32 v244, v244, v241
	v_lshlrev_b32_e32 v240, 16, v183
	v_and_b32_e32 v241, 0xffff0000, v183
	v_add_f32_e32 v244, v244, v240
	v_add_f32_e32 v244, v244, v241
	v_lshlrev_b32_e32 v240, 16, v184
	v_and_b32_e32 v241, 0xffff0000, v184
	v_add_f32_e32 v244, v244, v240
	v_add_f32_e32 v244, v244, v241
	v_lshlrev_b32_e32 v240, 16, v185
	v_and_b32_e32 v241, 0xffff0000, v185
	v_add_f32_e32 v244, v244, v240
	v_add_f32_e32 v244, v244, v241
	v_mov_b32_e32 v240, v244
	s_nop 1
	v_permlane16_swap_b32_e32 v240, v244
	v_add_f32_e32 v244, v244, v240
	v_mov_b32_e32 v240, v244
	s_nop 1
	v_permlane32_swap_b32_e32 v240, v244
	v_add_f32_e32 v244, v244, v240
	v_mul_f32_e32 v238, 0x3c800000, v244
	v_lshlrev_b32_e32 v240, 16, v178
	v_and_b32_e32 v241, 0xffff0000, v178
	v_sub_f32_e32 v240, v240, v238
	v_sub_f32_e32 v241, v241, v238
	v_mul_f32_e32 v245, v240, v240
	v_fmac_f32_e32 v245, v241, v241
	v_lshlrev_b32_e32 v240, 16, v179
	v_and_b32_e32 v241, 0xffff0000, v179
	v_sub_f32_e32 v240, v240, v238
	v_sub_f32_e32 v241, v241, v238
	v_fmac_f32_e32 v245, v240, v240
	v_fmac_f32_e32 v245, v241, v241
	v_lshlrev_b32_e32 v240, 16, v180
	v_and_b32_e32 v241, 0xffff0000, v180
	v_sub_f32_e32 v240, v240, v238
	v_sub_f32_e32 v241, v241, v238
	v_fmac_f32_e32 v245, v240, v240
	v_fmac_f32_e32 v245, v241, v241
	v_lshlrev_b32_e32 v240, 16, v181
	v_and_b32_e32 v241, 0xffff0000, v181
	v_sub_f32_e32 v240, v240, v238
	v_sub_f32_e32 v241, v241, v238
	v_fmac_f32_e32 v245, v240, v240
	v_fmac_f32_e32 v245, v241, v241
	v_lshlrev_b32_e32 v240, 16, v182
	v_and_b32_e32 v241, 0xffff0000, v182
	v_sub_f32_e32 v240, v240, v238
	v_sub_f32_e32 v241, v241, v238
	v_fmac_f32_e32 v245, v240, v240
	v_fmac_f32_e32 v245, v241, v241
	v_lshlrev_b32_e32 v240, 16, v183
	v_and_b32_e32 v241, 0xffff0000, v183
	v_sub_f32_e32 v240, v240, v238
	v_sub_f32_e32 v241, v241, v238
	v_fmac_f32_e32 v245, v240, v240
	v_fmac_f32_e32 v245, v241, v241
	v_lshlrev_b32_e32 v240, 16, v184
	v_and_b32_e32 v241, 0xffff0000, v184
	v_sub_f32_e32 v240, v240, v238
	v_sub_f32_e32 v241, v241, v238
	v_fmac_f32_e32 v245, v240, v240
; __device__ __forceinline__ float bf2f(u16 h) { return __uint_as_float(((unsigned)h) << 16); }
; template <int EPI> ...
;     ...
; #pragma unroll 16
;       for (int i = 0; i < 16; i++) {
;         const int rl = rbase + (i & 3) + 8 * (i >> 2);
;         const int row = m0 + rl;
;         float o0 = bf2f(Y[(size_t)row * 1024 + 256 + ch0]);
;         float o1 = bf2f(Y[(size_t)row * 1024 + 256 + ch1]);
;         float mean = hsum32(o0 + o1) * (1.0f / 64.0f);
;         float d0 = o0 - mean, d1 = o1 - mean;
;         float var = hsum32(d0 * d0 + d1 * d1) * (1.0f / 64.0f);
;         float rstd = rsqrtf(var + 64e-5f);
;         float pv0 = bf2f(P[(size_t)row * 2816 + 256 + 1536 + ch0]);
;         float pv1 = bf2f(P[(size_t)row * 2816 + 256 + 1536 + ch1]);
;         float pp0 = prevP(p, P, row, 1536 + ch0), pp1 = prevP(p, P, row, 1536 + ch1);
;         float vv0 = pv0 + (pp0 - pv0) * mu0, vv1 = pv1 + (pp1 - pv1) * mu1;
;         float b = bs[((size_t)row * 12 + hh) * 4 + 2];
;         float y0 = (d0 * rstd * gg0 + gb0 + b * vv0) * acc0[i];
;         float y1 = (d1 * rstd * gg1 + gb1 + b * vv1) * acc1[i];
;         Y[(size_t)row * 1024 + 256 + ch0] = f2bf(y0);
;         Y[(size_t)row * 1024 + 256 + ch1] = f2bf(y1);
;       }
	v_fmac_f32_e32 v245, v241, v241
	v_lshlrev_b32_e32 v240, 16, v185
	v_and_b32_e32 v241, 0xffff0000, v185
	v_sub_f32_e32 v240, v240, v238
	v_sub_f32_e32 v241, v241, v238
	v_fmac_f32_e32 v245, v240, v240
	v_fmac_f32_e32 v245, v241, v241
	v_mov_b32_e32 v240, v245
	s_nop 1
	v_permlane16_swap_b32_e32 v240, v245
	v_add_f32_e32 v245, v245, v240
	v_mov_b32_e32 v240, v245
	s_nop 1
	v_permlane32_swap_b32_e32 v240, v245
	v_add_f32_e32 v245, v245, v240
	v_mov_b32_e32 v240, 0x3a27c5ac
	v_fmamk_f32 v245, v245, 0x3c800000, v240
	v_rsq_f32_e32 v239, v245
	v_add_u32_e32 v247, 0x0, v230
	v_lshlrev_b32_e32 v240, 16, v178
	v_and_b32_e32 v244, 0xffff0000, v178
	v_sub_f32_e32 v240, v240, v238
	v_sub_f32_e32 v244, v244, v238
	v_mul_f32_e32 v240, v240, v239
	v_mul_f32_e32 v244, v244, v239
	v_fma_f32 v240, v130, v240, v146
	v_fma_f32 v244, v131, v244, v147
	v_lshlrev_b32_e32 v241, 16, v186
	v_and_b32_e32 v245, 0xffff0000, v186
	v_lshlrev_b32_e32 v243, 16, v194
	v_and_b32_e32 v246, 0xffff0000, v194
	v_sub_f32_e32 v243, v243, v241
	v_sub_f32_e32 v246, v246, v245
	v_fmac_f32_e32 v241, v162, v243
	v_fmac_f32_e32 v245, v163, v246
	v_fmac_f32_e32 v240, v234, v241
	v_fmac_f32_e32 v244, v234, v245
	v_mul_f32_e32 v0, v0, v240
	v_mul_f32_e32 v1, v1, v244
	v_lshlrev_b32_e32 v240, 16, v179
	v_and_b32_e32 v244, 0xffff0000, v179
	v_sub_f32_e32 v240, v240, v238
	v_sub_f32_e32 v244, v244, v238
	v_mul_f32_e32 v240, v240, v239
	v_mul_f32_e32 v244, v244, v239
	v_fma_f32 v240, v132, v240, v148
	v_fma_f32 v244, v133, v244, v149
	v_lshlrev_b32_e32 v241, 16, v187
	v_and_b32_e32 v245, 0xffff0000, v187
	v_lshlrev_b32_e32 v243, 16, v195
	v_and_b32_e32 v246, 0xffff0000, v195
	v_sub_f32_e32 v243, v243, v241
	v_sub_f32_e32 v246, v246, v245
	v_fmac_f32_e32 v241, v164, v243
	v_fmac_f32_e32 v245, v165, v246
	v_fmac_f32_e32 v240, v234, v241
	v_fmac_f32_e32 v244, v234, v245
	v_mul_f32_e32 v2, v2, v240
	v_mul_f32_e32 v3, v3, v244
	v_lshlrev_b32_e32 v240, 16, v180
	v_and_b32_e32 v244, 0xffff0000, v180
	v_sub_f32_e32 v240, v240, v238
	v_sub_f32_e32 v244, v244, v238
	v_mul_f32_e32 v240, v240, v239
	v_mul_f32_e32 v244, v244, v239
	v_fma_f32 v240, v134, v240, v150
	v_fma_f32 v244, v135, v244, v151
	v_lshlrev_b32_e32 v241, 16, v188
	v_and_b32_e32 v245, 0xffff0000, v188
	v_lshlrev_b32_e32 v243, 16, v196
	v_and_b32_e32 v246, 0xffff0000, v196
	v_sub_f32_e32 v243, v243, v241
	v_sub_f32_e32 v246, v246, v245
	v_fmac_f32_e32 v241, v166, v243
	v_fmac_f32_e32 v245, v167, v246
	v_fmac_f32_e32 v240, v234, v241
	v_fmac_f32_e32 v244, v234, v245
	v_mul_f32_e32 v4, v4, v240
	v_mul_f32_e32 v5, v5, v244
	v_lshlrev_b32_e32 v240, 16, v181
	v_and_b32_e32 v244, 0xffff0000, v181
	v_sub_f32_e32 v240, v240, v238
	v_sub_f32_e32 v244, v244, v238
	v_mul_f32_e32 v240, v240, v239
	v_mul_f32_e32 v244, v244, v239
	v_fma_f32 v240, v136, v240, v152
	v_fma_f32 v244, v137, v244, v153
	v_lshlrev_b32_e32 v241, 16, v189
	v_and_b32_e32 v245, 0xffff0000, v189
	v_lshlrev_b32_e32 v243, 16, v197
	v_and_b32_e32 v246, 0xffff0000, v197
	v_sub_f32_e32 v243, v243, v241
	v_sub_f32_e32 v246, v246, v245
	v_fmac_f32_e32 v241, v168, v243
	v_fmac_f32_e32 v245, v169, v246
	v_fmac_f32_e32 v240, v234, v241
	v_fmac_f32_e32 v244, v234, v245
	v_mul_f32_e32 v6, v6, v240
	v_mul_f32_e32 v7, v7, v244
	v_cvt_pk_bf16_f32 v0, v0, v1
	v_cvt_pk_bf16_f32 v1, v2, v3
	v_cvt_pk_bf16_f32 v2, v4, v5
	v_cvt_pk_bf16_f32 v3, v6, v7
	global_store_dwordx4 v247, v[0:3], s[22:23] offset:0
	v_lshlrev_b32_e32 v240, 16, v182
	v_and_b32_e32 v244, 0xffff0000, v182
	v_sub_f32_e32 v240, v240, v238
	v_sub_f32_e32 v244, v244, v238
	v_mul_f32_e32 v240, v240, v239
	v_mul_f32_e32 v244, v244, v239
	v_fma_f32 v240, v138, v240, v154
	v_fma_f32 v244, v139, v244, v155
	v_lshlrev_b32_e32 v241, 16, v190
	v_and_b32_e32 v245, 0xffff0000, v190
	v_lshlrev_b32_e32 v243, 16, v198
	v_and_b32_e32 v246, 0xffff0000, v198
	v_sub_f32_e32 v243, v243, v241
	v_sub_f32_e32 v246, v246, v245
	v_fmac_f32_e32 v241, v170, v243
	v_fmac_f32_e32 v245, v171, v246
	v_fmac_f32_e32 v240, v234, v241
	v_fmac_f32_e32 v244, v234, v245
	v_mul_f32_e32 v8, v8, v240
	v_mul_f32_e32 v9, v9, v244
	v_lshlrev_b32_e32 v240, 16, v183
	v_and_b32_e32 v244, 0xffff0000, v183
	v_sub_f32_e32 v240, v240, v238
	v_sub_f32_e32 v244, v244, v238
	v_mul_f32_e32 v240, v240, v239
	v_mul_f32_e32 v244, v244, v239
	v_fma_f32 v240, v140, v240, v156
	v_fma_f32 v244, v141, v244, v157
	v_lshlrev_b32_e32 v241, 16, v191
	v_and_b32_e32 v245, 0xffff0000, v191
	v_lshlrev_b32_e32 v243, 16, v199
	v_and_b32_e32 v246, 0xffff0000, v199
	v_sub_f32_e32 v243, v243, v241
	v_sub_f32_e32 v246, v246, v245
	v_fmac_f32_e32 v241, v172, v243
	v_fmac_f32_e32 v245, v173, v246
	v_fmac_f32_e32 v240, v234, v241
	v_fmac_f32_e32 v244, v234, v245
	v_mul_f32_e32 v10, v10, v240
	v_mul_f32_e32 v11, v11, v244
	v_lshlrev_b32_e32 v240, 16, v184
	v_and_b32_e32 v244, 0xffff0000, v184
	v_sub_f32_e32 v240, v240, v238
	v_sub_f32_e32 v244, v244, v238
	v_mul_f32_e32 v240, v240, v239
	v_mul_f32_e32 v244, v244, v239
	v_fma_f32 v240, v142, v240, v158
	v_fma_f32 v244, v143, v244, v159
	v_lshlrev_b32_e32 v241, 16, v192
	v_and_b32_e32 v245, 0xffff0000, v192
	v_lshlrev_b32_e32 v243, 16, v200
	v_and_b32_e32 v246, 0xffff0000, v200
	v_sub_f32_e32 v243, v243, v241
	v_sub_f32_e32 v246, v246, v245
	v_fmac_f32_e32 v241, v174, v243
	v_fmac_f32_e32 v245, v175, v246
	v_fmac_f32_e32 v240, v234, v241
	v_fmac_f32_e32 v244, v234, v245
	v_mul_f32_e32 v12, v12, v240
	v_mul_f32_e32 v13, v13, v244
	v_lshlrev_b32_e32 v240, 16, v185
	v_and_b32_e32 v244, 0xffff0000, v185
	v_sub_f32_e32 v240, v240, v238
	v_sub_f32_e32 v244, v244, v238
	v_mul_f32_e32 v240, v240, v239
	v_mul_f32_e32 v244, v244, v239
	v_fma_f32 v240, v144, v240, v160
	v_fma_f32 v244, v145, v244, v161
	v_lshlrev_b32_e32 v241, 16, v193
	v_and_b32_e32 v245, 0xffff0000, v193
	v_lshlrev_b32_e32 v243, 16, v201
	v_and_b32_e32 v246, 0xffff0000, v201
	v_sub_f32_e32 v243, v243, v241
	v_sub_f32_e32 v246, v246, v245
	v_fmac_f32_e32 v241, v176, v243
	v_fmac_f32_e32 v245, v177, v246
	v_fmac_f32_e32 v240, v234, v241
	v_fmac_f32_e32 v244, v234, v245
	v_mul_f32_e32 v14, v14, v240
	v_mul_f32_e32 v15, v15, v244
	v_cvt_pk_bf16_f32 v8, v8, v9
	v_cvt_pk_bf16_f32 v9, v10, v11
	v_cvt_pk_bf16_f32 v10, v12, v13
	v_cvt_pk_bf16_f32 v11, v14, v15
	global_store_dwordx4 v247, v[8:11], s[22:23] offset:64
	v_add_u32_e32 v236, 0x10000, v230
	v_add_u32_e32 v237, 0x2c000, v231
	v_subrev_u32_e32 v240, 0x1600, v237
	global_load_dwordx4 v[178:181], v236, s[22:23] offset:0 sc0
	global_load_dwordx4 v[182:185], v236, s[22:23] offset:64 sc0
	global_load_dwordx4 v[186:189], v237, s[96:97] offset:0 sc0
	global_load_dwordx4 v[190:193], v237, s[96:97] offset:64 sc0
	global_load_dwordx4 v[194:197], v240, s[96:97] offset:0 sc0
	global_load_dwordx4 v[198:201], v240, s[96:97] offset:64 sc0
	v_add_u32_e32 v236, 0x1800, v232
	s_nop 0
	global_load_dword v234, v236, s[96:97] offset:0
	s_waitcnt vmcnt(9)
; __device__ __forceinline__ float bf2f(u16 h) { return __uint_as_float(((unsigned)h) << 16); }
; template <int EPI> ...
;     ...
; #pragma unroll 16
;       for (int i = 0; i < 16; i++) {
;         const int rl = rbase + (i & 3) + 8 * (i >> 2);
;         const int row = m0 + rl;
;         float o0 = bf2f(Y[(size_t)row * 1024 + 256 + ch0]);
;         float o1 = bf2f(Y[(size_t)row * 1024 + 256 + ch1]);
;         float mean = hsum32(o0 + o1) * (1.0f / 64.0f);
;         float d0 = o0 - mean, d1 = o1 - mean;
;         float var = hsum32(d0 * d0 + d1 * d1) * (1.0f / 64.0f);
;         float rstd = rsqrtf(var + 64e-5f);
;         float pv0 = bf2f(P[(size_t)row * 2816 + 256 + 1536 + ch0]);
;         float pv1 = bf2f(P[(size_t)row * 2816 + 256 + 1536 + ch1]);
;         float pp0 = prevP(p, P, row, 1536 + ch0), pp1 = prevP(p, P, row, 1536 + ch1);
;         float vv0 = pv0 + (pp0 - pv0) * mu0, vv1 = pv1 + (pp1 - pv1) * mu1;
;         float b = bs[((size_t)row * 12 + hh) * 4 + 2];
;         float y0 = (d0 * rstd * gg0 + gb0 + b * vv0) * acc0[i];
;         float y1 = (d1 * rstd * gg1 + gb1 + b * vv1) * acc1[i];
;         Y[(size_t)row * 1024 + 256 + ch0] = f2bf(y0);
;         Y[(size_t)row * 1024 + 256 + ch1] = f2bf(y1);
;       }
	v_lshlrev_b32_e32 v240, 16, v202
	v_and_b32_e32 v241, 0xffff0000, v202
	v_add_f32_e32 v244, v240, v241
	v_lshlrev_b32_e32 v240, 16, v203
	v_and_b32_e32 v241, 0xffff0000, v203
	v_add_f32_e32 v244, v244, v240
	v_add_f32_e32 v244, v244, v241
	v_lshlrev_b32_e32 v240, 16, v204
	v_and_b32_e32 v241, 0xffff0000, v204
	v_add_f32_e32 v244, v244, v240
	v_add_f32_e32 v244, v244, v241
	v_lshlrev_b32_e32 v240, 16, v205
	v_and_b32_e32 v241, 0xffff0000, v205
	v_add_f32_e32 v244, v244, v240
	v_add_f32_e32 v244, v244, v241
	v_lshlrev_b32_e32 v240, 16, v206
	v_and_b32_e32 v241, 0xffff0000, v206
	v_add_f32_e32 v244, v244, v240
	v_add_f32_e32 v244, v244, v241
	v_lshlrev_b32_e32 v240, 16, v207
	v_and_b32_e32 v241, 0xffff0000, v207
	v_add_f32_e32 v244, v244, v240
	v_add_f32_e32 v244, v244, v241
	v_lshlrev_b32_e32 v240, 16, v208
	v_and_b32_e32 v241, 0xffff0000, v208
	v_add_f32_e32 v244, v244, v240
	v_add_f32_e32 v244, v244, v241
	v_lshlrev_b32_e32 v240, 16, v209
	v_and_b32_e32 v241, 0xffff0000, v209
	v_add_f32_e32 v244, v244, v240
	v_add_f32_e32 v244, v244, v241
	v_mov_b32_e32 v240, v244
	s_nop 1
	v_permlane16_swap_b32_e32 v240, v244
	v_add_f32_e32 v244, v244, v240
	v_mov_b32_e32 v240, v244
	s_nop 1
	v_permlane32_swap_b32_e32 v240, v244
	v_add_f32_e32 v244, v244, v240
	v_mul_f32_e32 v238, 0x3c800000, v244
	v_lshlrev_b32_e32 v240, 16, v202
	v_and_b32_e32 v241, 0xffff0000, v202
	v_sub_f32_e32 v240, v240, v238
	v_sub_f32_e32 v241, v241, v238
	v_mul_f32_e32 v245, v240, v240
	v_fmac_f32_e32 v245, v241, v241
	v_lshlrev_b32_e32 v240, 16, v203
	v_and_b32_e32 v241, 0xffff0000, v203
	v_sub_f32_e32 v240, v240, v238
	v_sub_f32_e32 v241, v241, v238
	v_fmac_f32_e32 v245, v240, v240
	v_fmac_f32_e32 v245, v241, v241
	v_lshlrev_b32_e32 v240, 16, v204
	v_and_b32_e32 v241, 0xffff0000, v204
	v_sub_f32_e32 v240, v240, v238
	v_sub_f32_e32 v241, v241, v238
	v_fmac_f32_e32 v245, v240, v240
	v_fmac_f32_e32 v245, v241, v241
	v_lshlrev_b32_e32 v240, 16, v205
	v_and_b32_e32 v241, 0xffff0000, v205
	v_sub_f32_e32 v240, v240, v238
	v_sub_f32_e32 v241, v241, v238
	v_fmac_f32_e32 v245, v240, v240
	v_fmac_f32_e32 v245, v241, v241
	v_lshlrev_b32_e32 v240, 16, v206
	v_and_b32_e32 v241, 0xffff0000, v206
	v_sub_f32_e32 v240, v240, v238
	v_sub_f32_e32 v241, v241, v238
	v_fmac_f32_e32 v245, v240, v240
	v_fmac_f32_e32 v245, v241, v241
	v_lshlrev_b32_e32 v240, 16, v207
	v_and_b32_e32 v241, 0xffff0000, v207
	v_sub_f32_e32 v240, v240, v238
	v_sub_f32_e32 v241, v241, v238
	v_fmac_f32_e32 v245, v240, v240
	v_fmac_f32_e32 v245, v241, v241
	v_lshlrev_b32_e32 v240, 16, v208
	v_and_b32_e32 v241, 0xffff0000, v208
	v_sub_f32_e32 v240, v240, v238
	v_sub_f32_e32 v241, v241, v238
	v_fmac_f32_e32 v245, v240, v240
	v_fmac_f32_e32 v245, v241, v241
	v_lshlrev_b32_e32 v240, 16, v209
	v_and_b32_e32 v241, 0xffff0000, v209
	v_sub_f32_e32 v240, v240, v238
	v_sub_f32_e32 v241, v241, v238
	v_fmac_f32_e32 v245, v240, v240
	v_fmac_f32_e32 v245, v241, v241
	v_mov_b32_e32 v240, v245
	s_nop 1
	v_permlane16_swap_b32_e32 v240, v245
	v_add_f32_e32 v245, v245, v240
	v_mov_b32_e32 v240, v245
	s_nop 1
	v_permlane32_swap_b32_e32 v240, v245
	v_add_f32_e32 v245, v245, v240
	v_mov_b32_e32 v240, 0x3a27c5ac
	v_fmamk_f32 v245, v245, 0x3c800000, v240
	v_rsq_f32_e32 v239, v245
	v_add_u32_e32 v247, 0x8000, v230
	v_lshlrev_b32_e32 v240, 16, v202
	v_and_b32_e32 v244, 0xffff0000, v202
	v_sub_f32_e32 v240, v240, v238
	v_sub_f32_e32 v244, v244, v238
	v_mul_f32_e32 v240, v240, v239
	v_mul_f32_e32 v244, v244, v239
	v_fma_f32 v240, v130, v240, v146
	v_fma_f32 v244, v131, v244, v147
	v_lshlrev_b32_e32 v241, 16, v210
	v_and_b32_e32 v245, 0xffff0000, v210
	v_lshlrev_b32_e32 v243, 16, v218
	v_and_b32_e32 v246, 0xffff0000, v218
	v_sub_f32_e32 v243, v243, v241
	v_sub_f32_e32 v246, v246, v245
	v_fmac_f32_e32 v241, v162, v243
	v_fmac_f32_e32 v245, v163, v246
	v_fmac_f32_e32 v240, v235, v241
	v_fmac_f32_e32 v244, v235, v245
	v_mul_f32_e32 v32, v32, v240
	v_mul_f32_e32 v33, v33, v244
	v_lshlrev_b32_e32 v240, 16, v203
	v_and_b32_e32 v244, 0xffff0000, v203
	v_sub_f32_e32 v240, v240, v238
	v_sub_f32_e32 v244, v244, v238
	v_mul_f32_e32 v240, v240, v239
	v_mul_f32_e32 v244, v244, v239
	v_fma_f32 v240, v132, v240, v148
	v_fma_f32 v244, v133, v244, v149
	v_lshlrev_b32_e32 v241, 16, v211
	v_and_b32_e32 v245, 0xffff0000, v211
	v_lshlrev_b32_e32 v243, 16, v219
	v_and_b32_e32 v246, 0xffff0000, v219
	v_sub_f32_e32 v243, v243, v241
	v_sub_f32_e32 v246, v246, v245
	v_fmac_f32_e32 v241, v164, v243
	v_fmac_f32_e32 v245, v165, v246
	v_fmac_f32_e32 v240, v235, v241
	v_fmac_f32_e32 v244, v235, v245
	v_mul_f32_e32 v34, v34, v240
	v_mul_f32_e32 v35, v35, v244
	v_lshlrev_b32_e32 v240, 16, v204
	v_and_b32_e32 v244, 0xffff0000, v204
	v_sub_f32_e32 v240, v240, v238
	v_sub_f32_e32 v244, v244, v238
	v_mul_f32_e32 v240, v240, v239
	v_mul_f32_e32 v244, v244, v239
	v_fma_f32 v240, v134, v240, v150
	v_fma_f32 v244, v135, v244, v151
	v_lshlrev_b32_e32 v241, 16, v212
	v_and_b32_e32 v245, 0xffff0000, v212
	v_lshlrev_b32_e32 v243, 16, v220
	v_and_b32_e32 v246, 0xffff0000, v220
	v_sub_f32_e32 v243, v243, v241
	v_sub_f32_e32 v246, v246, v245
	v_fmac_f32_e32 v241, v166, v243
	v_fmac_f32_e32 v245, v167, v246
	v_fmac_f32_e32 v240, v235, v241
	v_fmac_f32_e32 v244, v235, v245
	v_mul_f32_e32 v36, v36, v240
	v_mul_f32_e32 v37, v37, v244
	v_lshlrev_b32_e32 v240, 16, v205
	v_and_b32_e32 v244, 0xffff0000, v205
	v_sub_f32_e32 v240, v240, v238
	v_sub_f32_e32 v244, v244, v238
	v_mul_f32_e32 v240, v240, v239
	v_mul_f32_e32 v244, v244, v239
	v_fma_f32 v240, v136, v240, v152
	v_fma_f32 v244, v137, v244, v153
	v_lshlrev_b32_e32 v241, 16, v213
	v_and_b32_e32 v245, 0xffff0000, v213
	v_lshlrev_b32_e32 v243, 16, v221
; __device__ __forceinline__ float bf2f(u16 h) { return __uint_as_float(((unsigned)h) << 16); }
; template <int EPI> ...
;     ...
; #pragma unroll 16
;       for (int i = 0; i < 16; i++) {
;         const int rl = rbase + (i & 3) + 8 * (i >> 2);
;         const int row = m0 + rl;
;         float o0 = bf2f(Y[(size_t)row * 1024 + 256 + ch0]);
;         float o1 = bf2f(Y[(size_t)row * 1024 + 256 + ch1]);
;         float mean = hsum32(o0 + o1) * (1.0f / 64.0f);
;         float d0 = o0 - mean, d1 = o1 - mean;
;         float var = hsum32(d0 * d0 + d1 * d1) * (1.0f / 64.0f);
;         float rstd = rsqrtf(var + 64e-5f);
;         float pv0 = bf2f(P[(size_t)row * 2816 + 256 + 1536 + ch0]);
;         float pv1 = bf2f(P[(size_t)row * 2816 + 256 + 1536 + ch1]);
;         float pp0 = prevP(p, P, row, 1536 + ch0), pp1 = prevP(p, P, row, 1536 + ch1);
;         float vv0 = pv0 + (pp0 - pv0) * mu0, vv1 = pv1 + (pp1 - pv1) * mu1;
;         float b = bs[((size_t)row * 12 + hh) * 4 + 2];
;         float y0 = (d0 * rstd * gg0 + gb0 + b * vv0) * acc0[i];
;         float y1 = (d1 * rstd * gg1 + gb1 + b * vv1) * acc1[i];
;         Y[(size_t)row * 1024 + 256 + ch0] = f2bf(y0);
;         Y[(size_t)row * 1024 + 256 + ch1] = f2bf(y1);
;       }
	v_and_b32_e32 v246, 0xffff0000, v221
	v_sub_f32_e32 v243, v243, v241
	v_sub_f32_e32 v246, v246, v245
	v_fmac_f32_e32 v241, v168, v243
	v_fmac_f32_e32 v245, v169, v246
	v_fmac_f32_e32 v240, v235, v241
	v_fmac_f32_e32 v244, v235, v245
	v_mul_f32_e32 v38, v38, v240
	v_mul_f32_e32 v39, v39, v244
	v_cvt_pk_bf16_f32 v32, v32, v33
	v_cvt_pk_bf16_f32 v33, v34, v35
	v_cvt_pk_bf16_f32 v34, v36, v37
	v_cvt_pk_bf16_f32 v35, v38, v39
	global_store_dwordx4 v247, v[32:35], s[22:23] offset:0
	v_lshlrev_b32_e32 v240, 16, v206
	v_and_b32_e32 v244, 0xffff0000, v206
	v_sub_f32_e32 v240, v240, v238
	v_sub_f32_e32 v244, v244, v238
	v_mul_f32_e32 v240, v240, v239
	v_mul_f32_e32 v244, v244, v239
	v_fma_f32 v240, v138, v240, v154
	v_fma_f32 v244, v139, v244, v155
	v_lshlrev_b32_e32 v241, 16, v214
	v_and_b32_e32 v245, 0xffff0000, v214
	v_lshlrev_b32_e32 v243, 16, v222
	v_and_b32_e32 v246, 0xffff0000, v222
	v_sub_f32_e32 v243, v243, v241
	v_sub_f32_e32 v246, v246, v245
	v_fmac_f32_e32 v241, v170, v243
	v_fmac_f32_e32 v245, v171, v246
	v_fmac_f32_e32 v240, v235, v241
	v_fmac_f32_e32 v244, v235, v245
	v_mul_f32_e32 v40, v40, v240
	v_mul_f32_e32 v41, v41, v244
	v_lshlrev_b32_e32 v240, 16, v207
	v_and_b32_e32 v244, 0xffff0000, v207
	v_sub_f32_e32 v240, v240, v238
	v_sub_f32_e32 v244, v244, v238
	v_mul_f32_e32 v240, v240, v239
	v_mul_f32_e32 v244, v244, v239
	v_fma_f32 v240, v140, v240, v156
	v_fma_f32 v244, v141, v244, v157
	v_lshlrev_b32_e32 v241, 16, v215
	v_and_b32_e32 v245, 0xffff0000, v215
	v_lshlrev_b32_e32 v243, 16, v223
	v_and_b32_e32 v246, 0xffff0000, v223
	v_sub_f32_e32 v243, v243, v241
	v_sub_f32_e32 v246, v246, v245
	v_fmac_f32_e32 v241, v172, v243
	v_fmac_f32_e32 v245, v173, v246
	v_fmac_f32_e32 v240, v235, v241
	v_fmac_f32_e32 v244, v235, v245
	v_mul_f32_e32 v42, v42, v240
	v_mul_f32_e32 v43, v43, v244
	v_lshlrev_b32_e32 v240, 16, v208
	v_and_b32_e32 v244, 0xffff0000, v208
	v_sub_f32_e32 v240, v240, v238
	v_sub_f32_e32 v244, v244, v238
	v_mul_f32_e32 v240, v240, v239
	v_mul_f32_e32 v244, v244, v239
	v_fma_f32 v240, v142, v240, v158
	v_fma_f32 v244, v143, v244, v159
	v_lshlrev_b32_e32 v241, 16, v216
	v_and_b32_e32 v245, 0xffff0000, v216
	v_lshlrev_b32_e32 v243, 16, v224
	v_and_b32_e32 v246, 0xffff0000, v224
	v_sub_f32_e32 v243, v243, v241
	v_sub_f32_e32 v246, v246, v245
	v_fmac_f32_e32 v241, v174, v243
	v_fmac_f32_e32 v245, v175, v246
	v_fmac_f32_e32 v240, v235, v241
	v_fmac_f32_e32 v244, v235, v245
	v_mul_f32_e32 v44, v44, v240
	v_mul_f32_e32 v45, v45, v244
	v_lshlrev_b32_e32 v240, 16, v209
	v_and_b32_e32 v244, 0xffff0000, v209
	v_sub_f32_e32 v240, v240, v238
	v_sub_f32_e32 v244, v244, v238
	v_mul_f32_e32 v240, v240, v239
	v_mul_f32_e32 v244, v244, v239
	v_fma_f32 v240, v144, v240, v160
	v_fma_f32 v244, v145, v244, v161
	v_lshlrev_b32_e32 v241, 16, v217
	v_and_b32_e32 v245, 0xffff0000, v217
	v_lshlrev_b32_e32 v243, 16, v225
	v_and_b32_e32 v246, 0xffff0000, v225
	v_sub_f32_e32 v243, v243, v241
	v_sub_f32_e32 v246, v246, v245
	v_fmac_f32_e32 v241, v176, v243
	v_fmac_f32_e32 v245, v177, v246
	v_fmac_f32_e32 v240, v235, v241
	v_fmac_f32_e32 v244, v235, v245
	v_mul_f32_e32 v46, v46, v240
	v_mul_f32_e32 v47, v47, v244
	v_cvt_pk_bf16_f32 v40, v40, v41
	v_cvt_pk_bf16_f32 v41, v42, v43
	v_cvt_pk_bf16_f32 v42, v44, v45
	v_cvt_pk_bf16_f32 v43, v46, v47
	global_store_dwordx4 v247, v[40:43], s[22:23] offset:64
	v_add_u32_e32 v236, 0x18000, v230
	v_add_u32_e32 v237, 0x42000, v231
	v_subrev_u32_e32 v240, 0x1600, v237
	global_load_dwordx4 v[202:205], v236, s[22:23] offset:0 sc0
	global_load_dwordx4 v[206:209], v236, s[22:23] offset:64 sc0
	global_load_dwordx4 v[210:213], v237, s[96:97] offset:0 sc0
	global_load_dwordx4 v[214:217], v237, s[96:97] offset:64 sc0
	global_load_dwordx4 v[218:221], v240, s[96:97] offset:0 sc0
	global_load_dwordx4 v[222:225], v240, s[96:97] offset:64 sc0
	v_add_u32_e32 v236, 0x2400, v232
	s_nop 0
	global_load_dword v235, v236, s[96:97] offset:0
	s_waitcnt vmcnt(9)
	v_lshlrev_b32_e32 v240, 16, v178
	v_and_b32_e32 v241, 0xffff0000, v178
	v_add_f32_e32 v244, v240, v241
	v_lshlrev_b32_e32 v240, 16, v179
	v_and_b32_e32 v241, 0xffff0000, v179
	v_add_f32_e32 v244, v244, v240
	v_add_f32_e32 v244, v244, v241
	v_lshlrev_b32_e32 v240, 16, v180
	v_and_b32_e32 v241, 0xffff0000, v180
	v_add_f32_e32 v244, v244, v240
	v_add_f32_e32 v244, v244, v241
	v_lshlrev_b32_e32 v240, 16, v181
	v_and_b32_e32 v241, 0xffff0000, v181
	v_add_f32_e32 v244, v244, v240
	v_add_f32_e32 v244, v244, v241
	v_lshlrev_b32_e32 v240, 16, v182
	v_and_b32_e32 v241, 0xffff0000, v182
	v_add_f32_e32 v244, v244, v240
	v_add_f32_e32 v244, v244, v241
	v_lshlrev_b32_e32 v240, 16, v183
	v_and_b32_e32 v241, 0xffff0000, v183
	v_add_f32_e32 v244, v244, v240
	v_add_f32_e32 v244, v244, v241
	v_lshlrev_b32_e32 v240, 16, v184
	v_and_b32_e32 v241, 0xffff0000, v184
	v_add_f32_e32 v244, v244, v240
	v_add_f32_e32 v244, v244, v241
	v_lshlrev_b32_e32 v240, 16, v185
	v_and_b32_e32 v241, 0xffff0000, v185
	v_add_f32_e32 v244, v244, v240
	v_add_f32_e32 v244, v244, v241
	v_mov_b32_e32 v240, v244
	s_nop 1
	v_permlane16_swap_b32_e32 v240, v244
	v_add_f32_e32 v244, v244, v240
	v_mov_b32_e32 v240, v244
	s_nop 1
	v_permlane32_swap_b32_e32 v240, v244
	v_add_f32_e32 v244, v244, v240
	v_mul_f32_e32 v238, 0x3c800000, v244
	v_lshlrev_b32_e32 v240, 16, v178
	v_and_b32_e32 v241, 0xffff0000, v178
	v_sub_f32_e32 v240, v240, v238
	v_sub_f32_e32 v241, v241, v238
	v_mul_f32_e32 v245, v240, v240
	v_fmac_f32_e32 v245, v241, v241
	v_lshlrev_b32_e32 v240, 16, v179
	v_and_b32_e32 v241, 0xffff0000, v179
	v_sub_f32_e32 v240, v240, v238
	v_sub_f32_e32 v241, v241, v238
	v_fmac_f32_e32 v245, v240, v240
	v_fmac_f32_e32 v245, v241, v241
; __device__ __forceinline__ float bf2f(u16 h) { return __uint_as_float(((unsigned)h) << 16); }
; template <int EPI> ...
;     ...
; #pragma unroll 16
;       for (int i = 0; i < 16; i++) {
;         const int rl = rbase + (i & 3) + 8 * (i >> 2);
;         const int row = m0 + rl;
;         float o0 = bf2f(Y[(size_t)row * 1024 + 256 + ch0]);
;         float o1 = bf2f(Y[(size_t)row * 1024 + 256 + ch1]);
;         float mean = hsum32(o0 + o1) * (1.0f / 64.0f);
;         float d0 = o0 - mean, d1 = o1 - mean;
;         float var = hsum32(d0 * d0 + d1 * d1) * (1.0f / 64.0f);
;         float rstd = rsqrtf(var + 64e-5f);
;         float pv0 = bf2f(P[(size_t)row * 2816 + 256 + 1536 + ch0]);
;         float pv1 = bf2f(P[(size_t)row * 2816 + 256 + 1536 + ch1]);
;         float pp0 = prevP(p, P, row, 1536 + ch0), pp1 = prevP(p, P, row, 1536 + ch1);
;         float vv0 = pv0 + (pp0 - pv0) * mu0, vv1 = pv1 + (pp1 - pv1) * mu1;
;         float b = bs[((size_t)row * 12 + hh) * 4 + 2];
;         float y0 = (d0 * rstd * gg0 + gb0 + b * vv0) * acc0[i];
;         float y1 = (d1 * rstd * gg1 + gb1 + b * vv1) * acc1[i];
;         Y[(size_t)row * 1024 + 256 + ch0] = f2bf(y0);
;         Y[(size_t)row * 1024 + 256 + ch1] = f2bf(y1);
;       }
	v_lshlrev_b32_e32 v240, 16, v180
	v_and_b32_e32 v241, 0xffff0000, v180
	v_sub_f32_e32 v240, v240, v238
	v_sub_f32_e32 v241, v241, v238
	v_fmac_f32_e32 v245, v240, v240
	v_fmac_f32_e32 v245, v241, v241
	v_lshlrev_b32_e32 v240, 16, v181
	v_and_b32_e32 v241, 0xffff0000, v181
	v_sub_f32_e32 v240, v240, v238
	v_sub_f32_e32 v241, v241, v238
	v_fmac_f32_e32 v245, v240, v240
	v_fmac_f32_e32 v245, v241, v241
	v_lshlrev_b32_e32 v240, 16, v182
	v_and_b32_e32 v241, 0xffff0000, v182
	v_sub_f32_e32 v240, v240, v238
	v_sub_f32_e32 v241, v241, v238
	v_fmac_f32_e32 v245, v240, v240
	v_fmac_f32_e32 v245, v241, v241
	v_lshlrev_b32_e32 v240, 16, v183
	v_and_b32_e32 v241, 0xffff0000, v183
	v_sub_f32_e32 v240, v240, v238
	v_sub_f32_e32 v241, v241, v238
	v_fmac_f32_e32 v245, v240, v240
	v_fmac_f32_e32 v245, v241, v241
	v_lshlrev_b32_e32 v240, 16, v184
	v_and_b32_e32 v241, 0xffff0000, v184
	v_sub_f32_e32 v240, v240, v238
	v_sub_f32_e32 v241, v241, v238
	v_fmac_f32_e32 v245, v240, v240
	v_fmac_f32_e32 v245, v241, v241
	v_lshlrev_b32_e32 v240, 16, v185
	v_and_b32_e32 v241, 0xffff0000, v185
	v_sub_f32_e32 v240, v240, v238
	v_sub_f32_e32 v241, v241, v238
	v_fmac_f32_e32 v245, v240, v240
	v_fmac_f32_e32 v245, v241, v241
	v_mov_b32_e32 v240, v245
	s_nop 1
	v_permlane16_swap_b32_e32 v240, v245
	v_add_f32_e32 v245, v245, v240
	v_mov_b32_e32 v240, v245
	s_nop 1
	v_permlane32_swap_b32_e32 v240, v245
	v_add_f32_e32 v245, v245, v240
	v_mov_b32_e32 v240, 0x3a27c5ac
	v_fmamk_f32 v245, v245, 0x3c800000, v240
	v_rsq_f32_e32 v239, v245
	v_add_u32_e32 v247, 0x10000, v230
	v_lshlrev_b32_e32 v240, 16, v178
	v_and_b32_e32 v244, 0xffff0000, v178
	v_sub_f32_e32 v240, v240, v238
	v_sub_f32_e32 v244, v244, v238
	v_mul_f32_e32 v240, v240, v239
	v_mul_f32_e32 v244, v244, v239
	v_fma_f32 v240, v130, v240, v146
	v_fma_f32 v244, v131, v244, v147
	v_lshlrev_b32_e32 v241, 16, v186
	v_and_b32_e32 v245, 0xffff0000, v186
	v_lshlrev_b32_e32 v243, 16, v194
	v_and_b32_e32 v246, 0xffff0000, v194
	v_sub_f32_e32 v243, v243, v241
	v_sub_f32_e32 v246, v246, v245
	v_fmac_f32_e32 v241, v162, v243
	v_fmac_f32_e32 v245, v163, v246
	v_fmac_f32_e32 v240, v234, v241
	v_fmac_f32_e32 v244, v234, v245
	v_mul_f32_e32 v64, v64, v240
	v_mul_f32_e32 v65, v65, v244
	v_lshlrev_b32_e32 v240, 16, v179
	v_and_b32_e32 v244, 0xffff0000, v179
	v_sub_f32_e32 v240, v240, v238
	v_sub_f32_e32 v244, v244, v238
	v_mul_f32_e32 v240, v240, v239
	v_mul_f32_e32 v244, v244, v239
	v_fma_f32 v240, v132, v240, v148
	v_fma_f32 v244, v133, v244, v149
	v_lshlrev_b32_e32 v241, 16, v187
	v_and_b32_e32 v245, 0xffff0000, v187
	v_lshlrev_b32_e32 v243, 16, v195
	v_and_b32_e32 v246, 0xffff0000, v195
	v_sub_f32_e32 v243, v243, v241
	v_sub_f32_e32 v246, v246, v245
	v_fmac_f32_e32 v241, v164, v243
	v_fmac_f32_e32 v245, v165, v246
	v_fmac_f32_e32 v240, v234, v241
	v_fmac_f32_e32 v244, v234, v245
	v_mul_f32_e32 v66, v66, v240
	v_mul_f32_e32 v67, v67, v244
	v_lshlrev_b32_e32 v240, 16, v180
	v_and_b32_e32 v244, 0xffff0000, v180
	v_sub_f32_e32 v240, v240, v238
	v_sub_f32_e32 v244, v244, v238
	v_mul_f32_e32 v240, v240, v239
	v_mul_f32_e32 v244, v244, v239
	v_fma_f32 v240, v134, v240, v150
	v_fma_f32 v244, v135, v244, v151
	v_lshlrev_b32_e32 v241, 16, v188
	v_and_b32_e32 v245, 0xffff0000, v188
	v_lshlrev_b32_e32 v243, 16, v196
	v_and_b32_e32 v246, 0xffff0000, v196
	v_sub_f32_e32 v243, v243, v241
	v_sub_f32_e32 v246, v246, v245
	v_fmac_f32_e32 v241, v166, v243
	v_fmac_f32_e32 v245, v167, v246
	v_fmac_f32_e32 v240, v234, v241
	v_fmac_f32_e32 v244, v234, v245
	v_mul_f32_e32 v68, v68, v240
	v_mul_f32_e32 v69, v69, v244
	v_lshlrev_b32_e32 v240, 16, v181
	v_and_b32_e32 v244, 0xffff0000, v181
	v_sub_f32_e32 v240, v240, v238
	v_sub_f32_e32 v244, v244, v238
	v_mul_f32_e32 v240, v240, v239
	v_mul_f32_e32 v244, v244, v239
	v_fma_f32 v240, v136, v240, v152
	v_fma_f32 v244, v137, v244, v153
	v_lshlrev_b32_e32 v241, 16, v189
	v_and_b32_e32 v245, 0xffff0000, v189
	v_lshlrev_b32_e32 v243, 16, v197
	v_and_b32_e32 v246, 0xffff0000, v197
	v_sub_f32_e32 v243, v243, v241
	v_sub_f32_e32 v246, v246, v245
	v_fmac_f32_e32 v241, v168, v243
	v_fmac_f32_e32 v245, v169, v246
	v_fmac_f32_e32 v240, v234, v241
	v_fmac_f32_e32 v244, v234, v245
	v_mul_f32_e32 v70, v70, v240
	v_mul_f32_e32 v71, v71, v244
	v_cvt_pk_bf16_f32 v64, v64, v65
	v_cvt_pk_bf16_f32 v65, v66, v67
	v_cvt_pk_bf16_f32 v66, v68, v69
	v_cvt_pk_bf16_f32 v67, v70, v71
	global_store_dwordx4 v247, v[64:67], s[22:23] offset:0
	v_lshlrev_b32_e32 v240, 16, v182
	v_and_b32_e32 v244, 0xffff0000, v182
	v_sub_f32_e32 v240, v240, v238
	v_sub_f32_e32 v244, v244, v238
	v_mul_f32_e32 v240, v240, v239
	v_mul_f32_e32 v244, v244, v239
	v_fma_f32 v240, v138, v240, v154
	v_fma_f32 v244, v139, v244, v155
	v_lshlrev_b32_e32 v241, 16, v190
	v_and_b32_e32 v245, 0xffff0000, v190
	v_lshlrev_b32_e32 v243, 16, v198
	v_and_b32_e32 v246, 0xffff0000, v198
	v_sub_f32_e32 v243, v243, v241
	v_sub_f32_e32 v246, v246, v245
	v_fmac_f32_e32 v241, v170, v243
	v_fmac_f32_e32 v245, v171, v246
	v_fmac_f32_e32 v240, v234, v241
	v_fmac_f32_e32 v244, v234, v245
	v_mul_f32_e32 v72, v72, v240
	v_mul_f32_e32 v73, v73, v244
	v_lshlrev_b32_e32 v240, 16, v183
	v_and_b32_e32 v244, 0xffff0000, v183
	v_sub_f32_e32 v240, v240, v238
	v_sub_f32_e32 v244, v244, v238
	v_mul_f32_e32 v240, v240, v239
	v_mul_f32_e32 v244, v244, v239
	v_fma_f32 v240, v140, v240, v156
	v_fma_f32 v244, v141, v244, v157
	v_lshlrev_b32_e32 v241, 16, v191
	v_and_b32_e32 v245, 0xffff0000, v191
	v_lshlrev_b32_e32 v243, 16, v199
	v_and_b32_e32 v246, 0xffff0000, v199
	v_sub_f32_e32 v243, v243, v241
	v_sub_f32_e32 v246, v246, v245
	v_fmac_f32_e32 v241, v172, v243
	v_fmac_f32_e32 v245, v173, v246
; __device__ __forceinline__ float bf2f(u16 h) { return __uint_as_float(((unsigned)h) << 16); }
; template <int EPI> ...
;     ...
; #pragma unroll 16
;       for (int i = 0; i < 16; i++) {
;         const int rl = rbase + (i & 3) + 8 * (i >> 2);
;         const int row = m0 + rl;
;         float o0 = bf2f(Y[(size_t)row * 1024 + 256 + ch0]);
;         float o1 = bf2f(Y[(size_t)row * 1024 + 256 + ch1]);
;         float mean = hsum32(o0 + o1) * (1.0f / 64.0f);
;         float d0 = o0 - mean, d1 = o1 - mean;
;         float var = hsum32(d0 * d0 + d1 * d1) * (1.0f / 64.0f);
;         float rstd = rsqrtf(var + 64e-5f);
;         float pv0 = bf2f(P[(size_t)row * 2816 + 256 + 1536 + ch0]);
;         float pv1 = bf2f(P[(size_t)row * 2816 + 256 + 1536 + ch1]);
;         float pp0 = prevP(p, P, row, 1536 + ch0), pp1 = prevP(p, P, row, 1536 + ch1);
;         float vv0 = pv0 + (pp0 - pv0) * mu0, vv1 = pv1 + (pp1 - pv1) * mu1;
;         float b = bs[((size_t)row * 12 + hh) * 4 + 2];
;         float y0 = (d0 * rstd * gg0 + gb0 + b * vv0) * acc0[i];
;         float y1 = (d1 * rstd * gg1 + gb1 + b * vv1) * acc1[i];
;         Y[(size_t)row * 1024 + 256 + ch0] = f2bf(y0);
;         Y[(size_t)row * 1024 + 256 + ch1] = f2bf(y1);
;       }
	v_fmac_f32_e32 v240, v234, v241
	v_fmac_f32_e32 v244, v234, v245
	v_mul_f32_e32 v74, v74, v240
	v_mul_f32_e32 v75, v75, v244
	v_lshlrev_b32_e32 v240, 16, v184
	v_and_b32_e32 v244, 0xffff0000, v184
	v_sub_f32_e32 v240, v240, v238
	v_sub_f32_e32 v244, v244, v238
	v_mul_f32_e32 v240, v240, v239
	v_mul_f32_e32 v244, v244, v239
	v_fma_f32 v240, v142, v240, v158
	v_fma_f32 v244, v143, v244, v159
	v_lshlrev_b32_e32 v241, 16, v192
	v_and_b32_e32 v245, 0xffff0000, v192
	v_lshlrev_b32_e32 v243, 16, v200
	v_and_b32_e32 v246, 0xffff0000, v200
	v_sub_f32_e32 v243, v243, v241
	v_sub_f32_e32 v246, v246, v245
	v_fmac_f32_e32 v241, v174, v243
	v_fmac_f32_e32 v245, v175, v246
	v_fmac_f32_e32 v240, v234, v241
	v_fmac_f32_e32 v244, v234, v245
	v_mul_f32_e32 v76, v76, v240
	v_mul_f32_e32 v77, v77, v244
	v_lshlrev_b32_e32 v240, 16, v185
	v_and_b32_e32 v244, 0xffff0000, v185
	v_sub_f32_e32 v240, v240, v238
	v_sub_f32_e32 v244, v244, v238
	v_mul_f32_e32 v240, v240, v239
	v_mul_f32_e32 v244, v244, v239
	v_fma_f32 v240, v144, v240, v160
	v_fma_f32 v244, v145, v244, v161
	v_lshlrev_b32_e32 v241, 16, v193
	v_and_b32_e32 v245, 0xffff0000, v193
	v_lshlrev_b32_e32 v243, 16, v201
	v_and_b32_e32 v246, 0xffff0000, v201
	v_sub_f32_e32 v243, v243, v241
	v_sub_f32_e32 v246, v246, v245
	v_fmac_f32_e32 v241, v176, v243
	v_fmac_f32_e32 v245, v177, v246
	v_fmac_f32_e32 v240, v234, v241
	v_fmac_f32_e32 v244, v234, v245
	v_mul_f32_e32 v78, v78, v240
	v_mul_f32_e32 v79, v79, v244
	v_cvt_pk_bf16_f32 v72, v72, v73
	v_cvt_pk_bf16_f32 v73, v74, v75
	v_cvt_pk_bf16_f32 v74, v76, v77
	v_cvt_pk_bf16_f32 v75, v78, v79
	global_store_dwordx4 v247, v[72:75], s[22:23] offset:64
	v_add_u32_e32 v236, 0x0, v230
	v_add_u32_e32 v237, 0x0, v231
	v_subrev_u32_e32 v240, 0x1600, v237
	global_load_dwordx4 v[178:181], v236, s[22:23] offset:128 sc0
	global_load_dwordx4 v[182:185], v236, s[22:23] offset:192 sc0
	global_load_dwordx4 v[186:189], v237, s[96:97] offset:128 sc0
	global_load_dwordx4 v[190:193], v237, s[96:97] offset:192 sc0
	global_load_dwordx4 v[194:197], v240, s[96:97] offset:128 sc0
	global_load_dwordx4 v[198:201], v240, s[96:97] offset:192 sc0
	v_add_u32_e32 v236, 0x0, v232
	s_nop 0
	global_load_dword v234, v236, s[96:97] offset:16
	s_waitcnt vmcnt(9)
	v_lshlrev_b32_e32 v240, 16, v202
	v_and_b32_e32 v241, 0xffff0000, v202
	v_add_f32_e32 v244, v240, v241
	v_lshlrev_b32_e32 v240, 16, v203
	v_and_b32_e32 v241, 0xffff0000, v203
	v_add_f32_e32 v244, v244, v240
	v_add_f32_e32 v244, v244, v241
	v_lshlrev_b32_e32 v240, 16, v204
	v_and_b32_e32 v241, 0xffff0000, v204
	v_add_f32_e32 v244, v244, v240
	v_add_f32_e32 v244, v244, v241
	v_lshlrev_b32_e32 v240, 16, v205
	v_and_b32_e32 v241, 0xffff0000, v205
	v_add_f32_e32 v244, v244, v240
	v_add_f32_e32 v244, v244, v241
	v_lshlrev_b32_e32 v240, 16, v206
	v_and_b32_e32 v241, 0xffff0000, v206
	v_add_f32_e32 v244, v244, v240
	v_add_f32_e32 v244, v244, v241
	v_lshlrev_b32_e32 v240, 16, v207
	v_and_b32_e32 v241, 0xffff0000, v207
	v_add_f32_e32 v244, v244, v240
	v_add_f32_e32 v244, v244, v241
	v_lshlrev_b32_e32 v240, 16, v208
	v_and_b32_e32 v241, 0xffff0000, v208
	v_add_f32_e32 v244, v244, v240
	v_add_f32_e32 v244, v244, v241
	v_lshlrev_b32_e32 v240, 16, v209
	v_and_b32_e32 v241, 0xffff0000, v209
	v_add_f32_e32 v244, v244, v240
	v_add_f32_e32 v244, v244, v241
	v_mov_b32_e32 v240, v244
	s_nop 1
	v_permlane16_swap_b32_e32 v240, v244
	v_add_f32_e32 v244, v244, v240
	v_mov_b32_e32 v240, v244
	s_nop 1
	v_permlane32_swap_b32_e32 v240, v244
	v_add_f32_e32 v244, v244, v240
	v_mul_f32_e32 v238, 0x3c800000, v244
	v_lshlrev_b32_e32 v240, 16, v202
	v_and_b32_e32 v241, 0xffff0000, v202
	v_sub_f32_e32 v240, v240, v238
	v_sub_f32_e32 v241, v241, v238
	v_mul_f32_e32 v245, v240, v240
	v_fmac_f32_e32 v245, v241, v241
	v_lshlrev_b32_e32 v240, 16, v203
	v_and_b32_e32 v241, 0xffff0000, v203
	v_sub_f32_e32 v240, v240, v238
	v_sub_f32_e32 v241, v241, v238
	v_fmac_f32_e32 v245, v240, v240
	v_fmac_f32_e32 v245, v241, v241
	v_lshlrev_b32_e32 v240, 16, v204
	v_and_b32_e32 v241, 0xffff0000, v204
	v_sub_f32_e32 v240, v240, v238
	v_sub_f32_e32 v241, v241, v238
	v_fmac_f32_e32 v245, v240, v240
	v_fmac_f32_e32 v245, v241, v241
	v_lshlrev_b32_e32 v240, 16, v205
	v_and_b32_e32 v241, 0xffff0000, v205
	v_sub_f32_e32 v240, v240, v238
	v_sub_f32_e32 v241, v241, v238
	v_fmac_f32_e32 v245, v240, v240
	v_fmac_f32_e32 v245, v241, v241
	v_lshlrev_b32_e32 v240, 16, v206
	v_and_b32_e32 v241, 0xffff0000, v206
	v_sub_f32_e32 v240, v240, v238
	v_sub_f32_e32 v241, v241, v238
	v_fmac_f32_e32 v245, v240, v240
	v_fmac_f32_e32 v245, v241, v241
	v_lshlrev_b32_e32 v240, 16, v207
	v_and_b32_e32 v241, 0xffff0000, v207
	v_sub_f32_e32 v240, v240, v238
	v_sub_f32_e32 v241, v241, v238
	v_fmac_f32_e32 v245, v240, v240
	v_fmac_f32_e32 v245, v241, v241
	v_lshlrev_b32_e32 v240, 16, v208
	v_and_b32_e32 v241, 0xffff0000, v208
	v_sub_f32_e32 v240, v240, v238
	v_sub_f32_e32 v241, v241, v238
	v_fmac_f32_e32 v245, v240, v240
	v_fmac_f32_e32 v245, v241, v241
	v_lshlrev_b32_e32 v240, 16, v209
	v_and_b32_e32 v241, 0xffff0000, v209
	v_sub_f32_e32 v240, v240, v238
	v_sub_f32_e32 v241, v241, v238
	v_fmac_f32_e32 v245, v240, v240
	v_fmac_f32_e32 v245, v241, v241
	v_mov_b32_e32 v240, v245
	s_nop 1
	v_permlane16_swap_b32_e32 v240, v245
	v_add_f32_e32 v245, v245, v240
	v_mov_b32_e32 v240, v245
	s_nop 1
	v_permlane32_swap_b32_e32 v240, v245
	v_add_f32_e32 v245, v245, v240
	v_mov_b32_e32 v240, 0x3a27c5ac
	v_fmamk_f32 v245, v245, 0x3c800000, v240
	v_rsq_f32_e32 v239, v245
	v_add_u32_e32 v247, 0x18000, v230
	v_lshlrev_b32_e32 v240, 16, v202
	v_and_b32_e32 v244, 0xffff0000, v202
	v_sub_f32_e32 v240, v240, v238
	v_sub_f32_e32 v244, v244, v238
; __device__ __forceinline__ float bf2f(u16 h) { return __uint_as_float(((unsigned)h) << 16); }
; template <int EPI> ...
;     ...
;     } else {
;       const int hh = nt * 2 + wn;
;       const u16* P = (const u16*)(p.ws + O_P);
;       u16* Y = (u16*)(p.ws + O_Y);
;       const float* bs = (const float*)(p.ws + O_BS);
;       const int ch0 = hh * 64 + (lane & 31), ch1 = ch0 + 32;
;       const float gg0 = p.in[20][ch0], gg1 = p.in[20][ch1];
;       const float gb0 = p.in[21][ch0], gb1 = p.in[21][ch1];
;       const float mu0 = p.in[11][1536 + ch0], mu1 = p.in[11][1536 + ch1];
; #pragma unroll 16
;       for (int i = 0; i < 16; i++) {
;         const int rl = rbase + (i & 3) + 8 * (i >> 2);
;         const int row = m0 + rl;
;         float o0 = bf2f(Y[(size_t)row * 1024 + 256 + ch0]);
;         float o1 = bf2f(Y[(size_t)row * 1024 + 256 + ch1]);
;         float mean = hsum32(o0 + o1) * (1.0f / 64.0f);
;         float d0 = o0 - mean, d1 = o1 - mean;
;         float var = hsum32(d0 * d0 + d1 * d1) * (1.0f / 64.0f);
;         float rstd = rsqrtf(var + 64e-5f);
;         float pv0 = bf2f(P[(size_t)row * 2816 + 256 + 1536 + ch0]);
;         float pv1 = bf2f(P[(size_t)row * 2816 + 256 + 1536 + ch1]);
;         float pp0 = prevP(p, P, row, 1536 + ch0), pp1 = prevP(p, P, row, 1536 + ch1);
;         float vv0 = pv0 + (pp0 - pv0) * mu0, vv1 = pv1 + (pp1 - pv1) * mu1;
;         float b = bs[((size_t)row * 12 + hh) * 4 + 2];
;         float y0 = (d0 * rstd * gg0 + gb0 + b * vv0) * acc0[i];
;         float y1 = (d1 * rstd * gg1 + gb1 + b * vv1) * acc1[i];
;         Y[(size_t)row * 1024 + 256 + ch0] = f2bf(y0);
;         Y[(size_t)row * 1024 + 256 + ch1] = f2bf(y1);
;       }
	v_mul_f32_e32 v240, v240, v239
	v_mul_f32_e32 v244, v244, v239
	v_fma_f32 v240, v130, v240, v146
	v_fma_f32 v244, v131, v244, v147
	v_lshlrev_b32_e32 v241, 16, v210
	v_and_b32_e32 v245, 0xffff0000, v210
	v_lshlrev_b32_e32 v243, 16, v218
	v_and_b32_e32 v246, 0xffff0000, v218
	v_sub_f32_e32 v243, v243, v241
	v_sub_f32_e32 v246, v246, v245
	v_fmac_f32_e32 v241, v162, v243
	v_fmac_f32_e32 v245, v163, v246
	v_fmac_f32_e32 v240, v235, v241
	v_fmac_f32_e32 v244, v235, v245
	v_mul_f32_e32 v96, v96, v240
	v_mul_f32_e32 v97, v97, v244
	v_lshlrev_b32_e32 v240, 16, v203
	v_and_b32_e32 v244, 0xffff0000, v203
	v_sub_f32_e32 v240, v240, v238
	v_sub_f32_e32 v244, v244, v238
	v_mul_f32_e32 v240, v240, v239
	v_mul_f32_e32 v244, v244, v239
	v_fma_f32 v240, v132, v240, v148
	v_fma_f32 v244, v133, v244, v149
	v_lshlrev_b32_e32 v241, 16, v211
	v_and_b32_e32 v245, 0xffff0000, v211
	v_lshlrev_b32_e32 v243, 16, v219
	v_and_b32_e32 v246, 0xffff0000, v219
	v_sub_f32_e32 v243, v243, v241
	v_sub_f32_e32 v246, v246, v245
	v_fmac_f32_e32 v241, v164, v243
	v_fmac_f32_e32 v245, v165, v246
	v_fmac_f32_e32 v240, v235, v241
	v_fmac_f32_e32 v244, v235, v245
	v_mul_f32_e32 v98, v98, v240
	v_mul_f32_e32 v99, v99, v244
	v_lshlrev_b32_e32 v240, 16, v204
	v_and_b32_e32 v244, 0xffff0000, v204
	v_sub_f32_e32 v240, v240, v238
	v_sub_f32_e32 v244, v244, v238
	v_mul_f32_e32 v240, v240, v239
	v_mul_f32_e32 v244, v244, v239
	v_fma_f32 v240, v134, v240, v150
	v_fma_f32 v244, v135, v244, v151
	v_lshlrev_b32_e32 v241, 16, v212
	v_and_b32_e32 v245, 0xffff0000, v212
	v_lshlrev_b32_e32 v243, 16, v220
	v_and_b32_e32 v246, 0xffff0000, v220
	v_sub_f32_e32 v243, v243, v241
	v_sub_f32_e32 v246, v246, v245
	v_fmac_f32_e32 v241, v166, v243
	v_fmac_f32_e32 v245, v167, v246
	v_fmac_f32_e32 v240, v235, v241
	v_fmac_f32_e32 v244, v235, v245
	v_mul_f32_e32 v100, v100, v240
	v_mul_f32_e32 v101, v101, v244
	v_lshlrev_b32_e32 v240, 16, v205
	v_and_b32_e32 v244, 0xffff0000, v205
	v_sub_f32_e32 v240, v240, v238
	v_sub_f32_e32 v244, v244, v238
	v_mul_f32_e32 v240, v240, v239
	v_mul_f32_e32 v244, v244, v239
	v_fma_f32 v240, v136, v240, v152
	v_fma_f32 v244, v137, v244, v153
	v_lshlrev_b32_e32 v241, 16, v213
	v_and_b32_e32 v245, 0xffff0000, v213
	v_lshlrev_b32_e32 v243, 16, v221
	v_and_b32_e32 v246, 0xffff0000, v221
	v_sub_f32_e32 v243, v243, v241
	v_sub_f32_e32 v246, v246, v245
	v_fmac_f32_e32 v241, v168, v243
	v_fmac_f32_e32 v245, v169, v246
	v_fmac_f32_e32 v240, v235, v241
	v_fmac_f32_e32 v244, v235, v245
	v_mul_f32_e32 v102, v102, v240
	v_mul_f32_e32 v103, v103, v244
	v_cvt_pk_bf16_f32 v96, v96, v97
	v_cvt_pk_bf16_f32 v97, v98, v99
	v_cvt_pk_bf16_f32 v98, v100, v101
	v_cvt_pk_bf16_f32 v99, v102, v103
	global_store_dwordx4 v247, v[96:99], s[22:23] offset:0
	v_lshlrev_b32_e32 v240, 16, v206
	v_and_b32_e32 v244, 0xffff0000, v206
	v_sub_f32_e32 v240, v240, v238
	v_sub_f32_e32 v244, v244, v238
	v_mul_f32_e32 v240, v240, v239
	v_mul_f32_e32 v244, v244, v239
	v_fma_f32 v240, v138, v240, v154
	v_fma_f32 v244, v139, v244, v155
	v_lshlrev_b32_e32 v241, 16, v214
	v_and_b32_e32 v245, 0xffff0000, v214
	v_lshlrev_b32_e32 v243, 16, v222
	v_and_b32_e32 v246, 0xffff0000, v222
	v_sub_f32_e32 v243, v243, v241
	v_sub_f32_e32 v246, v246, v245
	v_fmac_f32_e32 v241, v170, v243
	v_fmac_f32_e32 v245, v171, v246
	v_fmac_f32_e32 v240, v235, v241
	v_fmac_f32_e32 v244, v235, v245
	v_mul_f32_e32 v104, v104, v240
	v_mul_f32_e32 v105, v105, v244
	v_lshlrev_b32_e32 v240, 16, v207
	v_and_b32_e32 v244, 0xffff0000, v207
	v_sub_f32_e32 v240, v240, v238
	v_sub_f32_e32 v244, v244, v238
	v_mul_f32_e32 v240, v240, v239
	v_mul_f32_e32 v244, v244, v239
	v_fma_f32 v240, v140, v240, v156
	v_fma_f32 v244, v141, v244, v157
	v_lshlrev_b32_e32 v241, 16, v215
	v_and_b32_e32 v245, 0xffff0000, v215
	v_lshlrev_b32_e32 v243, 16, v223
	v_and_b32_e32 v246, 0xffff0000, v223
	v_sub_f32_e32 v243, v243, v241
	v_sub_f32_e32 v246, v246, v245
	v_fmac_f32_e32 v241, v172, v243
	v_fmac_f32_e32 v245, v173, v246
	v_fmac_f32_e32 v240, v235, v241
	v_fmac_f32_e32 v244, v235, v245
	v_mul_f32_e32 v106, v106, v240
	v_mul_f32_e32 v107, v107, v244
	v_lshlrev_b32_e32 v240, 16, v208
	v_and_b32_e32 v244, 0xffff0000, v208
	v_sub_f32_e32 v240, v240, v238
	v_sub_f32_e32 v244, v244, v238
	v_mul_f32_e32 v240, v240, v239
	v_mul_f32_e32 v244, v244, v239
	v_fma_f32 v240, v142, v240, v158
	v_fma_f32 v244, v143, v244, v159
	v_lshlrev_b32_e32 v241, 16, v216
	v_and_b32_e32 v245, 0xffff0000, v216
	v_lshlrev_b32_e32 v243, 16, v224
	v_and_b32_e32 v246, 0xffff0000, v224
	v_sub_f32_e32 v243, v243, v241
	v_sub_f32_e32 v246, v246, v245
	v_fmac_f32_e32 v241, v174, v243
	v_fmac_f32_e32 v245, v175, v246
	v_fmac_f32_e32 v240, v235, v241
	v_fmac_f32_e32 v244, v235, v245
	v_mul_f32_e32 v108, v108, v240
	v_mul_f32_e32 v109, v109, v244
	v_lshlrev_b32_e32 v240, 16, v209
	v_and_b32_e32 v244, 0xffff0000, v209
	v_sub_f32_e32 v240, v240, v238
	v_sub_f32_e32 v244, v244, v238
	v_mul_f32_e32 v240, v240, v239
	v_mul_f32_e32 v244, v244, v239
	v_fma_f32 v240, v144, v240, v160
	v_fma_f32 v244, v145, v244, v161
	v_lshlrev_b32_e32 v241, 16, v217
	v_and_b32_e32 v245, 0xffff0000, v217
	v_lshlrev_b32_e32 v243, 16, v225
	v_and_b32_e32 v246, 0xffff0000, v225
	v_sub_f32_e32 v243, v243, v241
	v_sub_f32_e32 v246, v246, v245
	v_fmac_f32_e32 v241, v176, v243
	v_fmac_f32_e32 v245, v177, v246
	v_fmac_f32_e32 v240, v235, v241
	v_fmac_f32_e32 v244, v235, v245
	v_mul_f32_e32 v110, v110, v240
	v_mul_f32_e32 v111, v111, v244
	v_cvt_pk_bf16_f32 v104, v104, v105
	v_cvt_pk_bf16_f32 v105, v106, v107
	v_cvt_pk_bf16_f32 v106, v108, v109
	v_cvt_pk_bf16_f32 v107, v110, v111
	global_store_dwordx4 v247, v[104:107], s[22:23] offset:64
	global_load_dwordx4 v[130:133], v233, s[2:3] offset:256 sc0
	global_load_dwordx4 v[134:137], v233, s[2:3] offset:272 sc0
	global_load_dwordx4 v[138:141], v233, s[2:3] offset:384 sc0
	global_load_dwordx4 v[142:145], v233, s[2:3] offset:400 sc0
	global_load_dwordx4 v[146:149], v233, s[16:17] offset:256 sc0
	global_load_dwordx4 v[150:153], v233, s[16:17] offset:272 sc0
	global_load_dwordx4 v[154:157], v233, s[16:17] offset:384 sc0
	global_load_dwordx4 v[158:161], v233, s[16:17] offset:400 sc0
	global_load_dwordx4 v[162:165], v233, s[0:1] offset:256 sc0
	global_load_dwordx4 v[166:169], v233, s[0:1] offset:272 sc0
	global_load_dwordx4 v[170:173], v233, s[0:1] offset:384 sc0
	global_load_dwordx4 v[174:177], v233, s[0:1] offset:400 sc0
	v_add_u32_e32 v236, 0x8000, v230
	v_add_u32_e32 v237, 0x16000, v231
	v_subrev_u32_e32 v240, 0x1600, v237
	global_load_dwordx4 v[202:205], v236, s[22:23] offset:128 sc0
	global_load_dwordx4 v[206:209], v236, s[22:23] offset:192 sc0
	global_load_dwordx4 v[210:213], v237, s[96:97] offset:128 sc0
	global_load_dwordx4 v[214:217], v237, s[96:97] offset:192 sc0
	global_load_dwordx4 v[218:221], v240, s[96:97] offset:128 sc0
	global_load_dwordx4 v[222:225], v240, s[96:97] offset:192 sc0
	v_add_u32_e32 v236, 0xc00, v232
	s_nop 0
	global_load_dword v235, v236, s[96:97] offset:16
	s_waitcnt vmcnt(7)
; __device__ __forceinline__ float bf2f(u16 h) { return __uint_as_float(((unsigned)h) << 16); }
; __device__ __forceinline__ float prevP(const Params& p, const u16* P, int row, int c) {
;     ...
;   const bool start = (row < NP) ? ((row & 2047) == 0) : (((row - NP) & 3) == 0);
;   if (start) v = (row < NP) ? 0.f : p.in[3][(size_t)((row - NP) >> 2) * 2560 + c];
; template <int EPI> ...
;     ...
;       for (int i = 0; i < 16; i++) {
;         const int rl = rbase + (i & 3) + 8 * (i >> 2);
;         const int row = m0 + rl;
;         float o0 = bf2f(Y[(size_t)row * 1024 + 256 + ch0]);
;         float o1 = bf2f(Y[(size_t)row * 1024 + 256 + ch1]);
;         float mean = hsum32(o0 + o1) * (1.0f / 64.0f);
;         float d0 = o0 - mean, d1 = o1 - mean;
;         float var = hsum32(d0 * d0 + d1 * d1) * (1.0f / 64.0f);
;         float rstd = rsqrtf(var + 64e-5f);
;         float pv0 = bf2f(P[(size_t)row * 2816 + 256 + 1536 + ch0]);
;         float pv1 = bf2f(P[(size_t)row * 2816 + 256 + 1536 + ch1]);
;         float pp0 = prevP(p, P, row, 1536 + ch0), pp1 = prevP(p, P, row, 1536 + ch1);
;         float vv0 = pv0 + (pp0 - pv0) * mu0, vv1 = pv1 + (pp1 - pv1) * mu1;
;         float b = bs[((size_t)row * 12 + hh) * 4 + 2];
;         float y0 = (d0 * rstd * gg0 + gb0 + b * vv0) * acc0[i];
;         float y1 = (d1 * rstd * gg1 + gb1 + b * vv1) * acc1[i];
;         Y[(size_t)row * 1024 + 256 + ch0] = f2bf(y0);
;         Y[(size_t)row * 1024 + 256 + ch1] = f2bf(y1);
	s_and_b32 s18, s6, 7
	s_or_b32 s18, s18, s4
	s_cmp_lg_u32 s18, 0
	s_cbranch_scc1 .Lpo_nostart_p4
	v_cmp_eq_u32_e32 vcc, 0, v248
	s_nop 1
	v_cndmask_b32_e64 v194, v194, 0, vcc
	v_cndmask_b32_e64 v195, v195, 0, vcc
	v_cndmask_b32_e64 v196, v196, 0, vcc
	v_cndmask_b32_e64 v197, v197, 0, vcc
	v_cndmask_b32_e64 v198, v198, 0, vcc
	v_cndmask_b32_e64 v199, v199, 0, vcc
	v_cndmask_b32_e64 v200, v200, 0, vcc
	v_cndmask_b32_e64 v201, v201, 0, vcc
.Lpo_nostart_p4:
	v_lshlrev_b32_e32 v240, 16, v178
	v_and_b32_e32 v241, 0xffff0000, v178
	v_add_f32_e32 v244, v240, v241
	v_lshlrev_b32_e32 v240, 16, v179
	v_and_b32_e32 v241, 0xffff0000, v179
	v_add_f32_e32 v244, v244, v240
	v_add_f32_e32 v244, v244, v241
	v_lshlrev_b32_e32 v240, 16, v180
	v_and_b32_e32 v241, 0xffff0000, v180
	v_add_f32_e32 v244, v244, v240
	v_add_f32_e32 v244, v244, v241
	v_lshlrev_b32_e32 v240, 16, v181
	v_and_b32_e32 v241, 0xffff0000, v181
	v_add_f32_e32 v244, v244, v240
	v_add_f32_e32 v244, v244, v241
	v_lshlrev_b32_e32 v240, 16, v182
	v_and_b32_e32 v241, 0xffff0000, v182
	v_add_f32_e32 v244, v244, v240
	v_add_f32_e32 v244, v244, v241
	v_lshlrev_b32_e32 v240, 16, v183
	v_and_b32_e32 v241, 0xffff0000, v183
	v_add_f32_e32 v244, v244, v240
	v_add_f32_e32 v244, v244, v241
	v_lshlrev_b32_e32 v240, 16, v184
	v_and_b32_e32 v241, 0xffff0000, v184
	v_add_f32_e32 v244, v244, v240
	v_add_f32_e32 v244, v244, v241
	v_lshlrev_b32_e32 v240, 16, v185
	v_and_b32_e32 v241, 0xffff0000, v185
	v_add_f32_e32 v244, v244, v240
	v_add_f32_e32 v244, v244, v241
	v_mov_b32_e32 v240, v244
	s_nop 1
	v_permlane16_swap_b32_e32 v240, v244
	v_add_f32_e32 v244, v244, v240
	v_mov_b32_e32 v240, v244
	s_nop 1
	v_permlane32_swap_b32_e32 v240, v244
	v_add_f32_e32 v244, v244, v240
	v_mul_f32_e32 v238, 0x3c800000, v244
	v_lshlrev_b32_e32 v240, 16, v178
	v_and_b32_e32 v241, 0xffff0000, v178
	v_sub_f32_e32 v240, v240, v238
	v_sub_f32_e32 v241, v241, v238
	v_mul_f32_e32 v245, v240, v240
	v_fmac_f32_e32 v245, v241, v241
	v_lshlrev_b32_e32 v240, 16, v179
	v_and_b32_e32 v241, 0xffff0000, v179
	v_sub_f32_e32 v240, v240, v238
	v_sub_f32_e32 v241, v241, v238
	v_fmac_f32_e32 v245, v240, v240
	v_fmac_f32_e32 v245, v241, v241
	v_lshlrev_b32_e32 v240, 16, v180
	v_and_b32_e32 v241, 0xffff0000, v180
	v_sub_f32_e32 v240, v240, v238
	v_sub_f32_e32 v241, v241, v238
	v_fmac_f32_e32 v245, v240, v240
	v_fmac_f32_e32 v245, v241, v241
	v_lshlrev_b32_e32 v240, 16, v181
	v_and_b32_e32 v241, 0xffff0000, v181
	v_sub_f32_e32 v240, v240, v238
	v_sub_f32_e32 v241, v241, v238
	v_fmac_f32_e32 v245, v240, v240
	v_fmac_f32_e32 v245, v241, v241
	v_lshlrev_b32_e32 v240, 16, v182
	v_and_b32_e32 v241, 0xffff0000, v182
	v_sub_f32_e32 v240, v240, v238
	v_sub_f32_e32 v241, v241, v238
	v_fmac_f32_e32 v245, v240, v240
	v_fmac_f32_e32 v245, v241, v241
	v_lshlrev_b32_e32 v240, 16, v183
	v_and_b32_e32 v241, 0xffff0000, v183
	v_sub_f32_e32 v240, v240, v238
	v_sub_f32_e32 v241, v241, v238
	v_fmac_f32_e32 v245, v240, v240
	v_fmac_f32_e32 v245, v241, v241
	v_lshlrev_b32_e32 v240, 16, v184
	v_and_b32_e32 v241, 0xffff0000, v184
	v_sub_f32_e32 v240, v240, v238
	v_sub_f32_e32 v241, v241, v238
	v_fmac_f32_e32 v245, v240, v240
	v_fmac_f32_e32 v245, v241, v241
	v_lshlrev_b32_e32 v240, 16, v185
	v_and_b32_e32 v241, 0xffff0000, v185
	v_sub_f32_e32 v240, v240, v238
	v_sub_f32_e32 v241, v241, v238
	v_fmac_f32_e32 v245, v240, v240
	v_fmac_f32_e32 v245, v241, v241
	v_mov_b32_e32 v240, v245
	s_nop 1
	v_permlane16_swap_b32_e32 v240, v245
	v_add_f32_e32 v245, v245, v240
	v_mov_b32_e32 v240, v245
	s_nop 1
	v_permlane32_swap_b32_e32 v240, v245
	v_add_f32_e32 v245, v245, v240
	v_mov_b32_e32 v240, 0x3a27c5ac
	v_fmamk_f32 v245, v245, 0x3c800000, v240
	v_rsq_f32_e32 v239, v245
	v_add_u32_e32 v247, 0x0, v230
	v_lshlrev_b32_e32 v240, 16, v178
	v_and_b32_e32 v244, 0xffff0000, v178
	v_sub_f32_e32 v240, v240, v238
	v_sub_f32_e32 v244, v244, v238
	v_mul_f32_e32 v240, v240, v239
	v_mul_f32_e32 v244, v244, v239
	v_fma_f32 v240, v130, v240, v146
	v_fma_f32 v244, v131, v244, v147
	v_lshlrev_b32_e32 v241, 16, v186
	v_and_b32_e32 v245, 0xffff0000, v186
	v_lshlrev_b32_e32 v243, 16, v194
	v_and_b32_e32 v246, 0xffff0000, v194
	v_sub_f32_e32 v243, v243, v241
	v_sub_f32_e32 v246, v246, v245
	v_fmac_f32_e32 v241, v162, v243
	v_fmac_f32_e32 v245, v163, v246
	v_fmac_f32_e32 v240, v234, v241
	v_fmac_f32_e32 v244, v234, v245
	v_mul_f32_e32 v16, v16, v240
	v_mul_f32_e32 v17, v17, v244
	v_lshlrev_b32_e32 v240, 16, v179
	v_and_b32_e32 v244, 0xffff0000, v179
	v_sub_f32_e32 v240, v240, v238
	v_sub_f32_e32 v244, v244, v238
	v_mul_f32_e32 v240, v240, v239
	v_mul_f32_e32 v244, v244, v239
	v_fma_f32 v240, v132, v240, v148
	v_fma_f32 v244, v133, v244, v149
	v_lshlrev_b32_e32 v241, 16, v187
	v_and_b32_e32 v245, 0xffff0000, v187
	v_lshlrev_b32_e32 v243, 16, v195
	v_and_b32_e32 v246, 0xffff0000, v195
	v_sub_f32_e32 v243, v243, v241
	v_sub_f32_e32 v246, v246, v245
	v_fmac_f32_e32 v241, v164, v243
	v_fmac_f32_e32 v245, v165, v246
	v_fmac_f32_e32 v240, v234, v241
	v_fmac_f32_e32 v244, v234, v245
	v_mul_f32_e32 v18, v18, v240
	v_mul_f32_e32 v19, v19, v244
	v_lshlrev_b32_e32 v240, 16, v180
	v_and_b32_e32 v244, 0xffff0000, v180
	v_sub_f32_e32 v240, v240, v238
	v_sub_f32_e32 v244, v244, v238
	v_mul_f32_e32 v240, v240, v239
	v_mul_f32_e32 v244, v244, v239
	v_fma_f32 v240, v134, v240, v150
	v_fma_f32 v244, v135, v244, v151
	v_lshlrev_b32_e32 v241, 16, v188
	v_and_b32_e32 v245, 0xffff0000, v188
	v_lshlrev_b32_e32 v243, 16, v196
	v_and_b32_e32 v246, 0xffff0000, v196
	v_sub_f32_e32 v243, v243, v241
	v_sub_f32_e32 v246, v246, v245
	v_fmac_f32_e32 v241, v166, v243
	v_fmac_f32_e32 v245, v167, v246
	v_fmac_f32_e32 v240, v234, v241
; __device__ __forceinline__ float bf2f(u16 h) { return __uint_as_float(((unsigned)h) << 16); }
; template <int EPI> ...
;     ...
;       for (int i = 0; i < 16; i++) {
;         const int rl = rbase + (i & 3) + 8 * (i >> 2);
;         const int row = m0 + rl;
;         float o0 = bf2f(Y[(size_t)row * 1024 + 256 + ch0]);
;         float o1 = bf2f(Y[(size_t)row * 1024 + 256 + ch1]);
;         float mean = hsum32(o0 + o1) * (1.0f / 64.0f);
;         float d0 = o0 - mean, d1 = o1 - mean;
;         float var = hsum32(d0 * d0 + d1 * d1) * (1.0f / 64.0f);
;         float rstd = rsqrtf(var + 64e-5f);
;         float pv0 = bf2f(P[(size_t)row * 2816 + 256 + 1536 + ch0]);
;         float pv1 = bf2f(P[(size_t)row * 2816 + 256 + 1536 + ch1]);
;         float pp0 = prevP(p, P, row, 1536 + ch0), pp1 = prevP(p, P, row, 1536 + ch1);
;         float vv0 = pv0 + (pp0 - pv0) * mu0, vv1 = pv1 + (pp1 - pv1) * mu1;
;         float b = bs[((size_t)row * 12 + hh) * 4 + 2];
;         float y0 = (d0 * rstd * gg0 + gb0 + b * vv0) * acc0[i];
;         float y1 = (d1 * rstd * gg1 + gb1 + b * vv1) * acc1[i];
;         Y[(size_t)row * 1024 + 256 + ch0] = f2bf(y0);
;         Y[(size_t)row * 1024 + 256 + ch1] = f2bf(y1);
	v_fmac_f32_e32 v244, v234, v245
	v_mul_f32_e32 v20, v20, v240
	v_mul_f32_e32 v21, v21, v244
	v_lshlrev_b32_e32 v240, 16, v181
	v_and_b32_e32 v244, 0xffff0000, v181
	v_sub_f32_e32 v240, v240, v238
	v_sub_f32_e32 v244, v244, v238
	v_mul_f32_e32 v240, v240, v239
	v_mul_f32_e32 v244, v244, v239
	v_fma_f32 v240, v136, v240, v152
	v_fma_f32 v244, v137, v244, v153
	v_lshlrev_b32_e32 v241, 16, v189
	v_and_b32_e32 v245, 0xffff0000, v189
	v_lshlrev_b32_e32 v243, 16, v197
	v_and_b32_e32 v246, 0xffff0000, v197
	v_sub_f32_e32 v243, v243, v241
	v_sub_f32_e32 v246, v246, v245
	v_fmac_f32_e32 v241, v168, v243
	v_fmac_f32_e32 v245, v169, v246
	v_fmac_f32_e32 v240, v234, v241
	v_fmac_f32_e32 v244, v234, v245
	v_mul_f32_e32 v22, v22, v240
	v_mul_f32_e32 v23, v23, v244
	v_cvt_pk_bf16_f32 v16, v16, v17
	v_cvt_pk_bf16_f32 v17, v18, v19
	v_cvt_pk_bf16_f32 v18, v20, v21
	v_cvt_pk_bf16_f32 v19, v22, v23
	global_store_dwordx4 v247, v[16:19], s[22:23] offset:128
	v_lshlrev_b32_e32 v240, 16, v182
	v_and_b32_e32 v244, 0xffff0000, v182
	v_sub_f32_e32 v240, v240, v238
	v_sub_f32_e32 v244, v244, v238
	v_mul_f32_e32 v240, v240, v239
	v_mul_f32_e32 v244, v244, v239
	v_fma_f32 v240, v138, v240, v154
	v_fma_f32 v244, v139, v244, v155
	v_lshlrev_b32_e32 v241, 16, v190
	v_and_b32_e32 v245, 0xffff0000, v190
	v_lshlrev_b32_e32 v243, 16, v198
	v_and_b32_e32 v246, 0xffff0000, v198
	v_sub_f32_e32 v243, v243, v241
	v_sub_f32_e32 v246, v246, v245
	v_fmac_f32_e32 v241, v170, v243
	v_fmac_f32_e32 v245, v171, v246
	v_fmac_f32_e32 v240, v234, v241
	v_fmac_f32_e32 v244, v234, v245
	v_mul_f32_e32 v24, v24, v240
	v_mul_f32_e32 v25, v25, v244
	v_lshlrev_b32_e32 v240, 16, v183
	v_and_b32_e32 v244, 0xffff0000, v183
	v_sub_f32_e32 v240, v240, v238
	v_sub_f32_e32 v244, v244, v238
	v_mul_f32_e32 v240, v240, v239
	v_mul_f32_e32 v244, v244, v239
	v_fma_f32 v240, v140, v240, v156
	v_fma_f32 v244, v141, v244, v157
	v_lshlrev_b32_e32 v241, 16, v191
	v_and_b32_e32 v245, 0xffff0000, v191
	v_lshlrev_b32_e32 v243, 16, v199
	v_and_b32_e32 v246, 0xffff0000, v199
	v_sub_f32_e32 v243, v243, v241
	v_sub_f32_e32 v246, v246, v245
	v_fmac_f32_e32 v241, v172, v243
	v_fmac_f32_e32 v245, v173, v246
	v_fmac_f32_e32 v240, v234, v241
	v_fmac_f32_e32 v244, v234, v245
	v_mul_f32_e32 v26, v26, v240
	v_mul_f32_e32 v27, v27, v244
	v_lshlrev_b32_e32 v240, 16, v184
	v_and_b32_e32 v244, 0xffff0000, v184
	v_sub_f32_e32 v240, v240, v238
	v_sub_f32_e32 v244, v244, v238
	v_mul_f32_e32 v240, v240, v239
	v_mul_f32_e32 v244, v244, v239
	v_fma_f32 v240, v142, v240, v158
	v_fma_f32 v244, v143, v244, v159
	v_lshlrev_b32_e32 v241, 16, v192
	v_and_b32_e32 v245, 0xffff0000, v192
	v_lshlrev_b32_e32 v243, 16, v200
	v_and_b32_e32 v246, 0xffff0000, v200
	v_sub_f32_e32 v243, v243, v241
	v_sub_f32_e32 v246, v246, v245
	v_fmac_f32_e32 v241, v174, v243
	v_fmac_f32_e32 v245, v175, v246
	v_fmac_f32_e32 v240, v234, v241
	v_fmac_f32_e32 v244, v234, v245
	v_mul_f32_e32 v28, v28, v240
	v_mul_f32_e32 v29, v29, v244
	v_lshlrev_b32_e32 v240, 16, v185
	v_and_b32_e32 v244, 0xffff0000, v185
	v_sub_f32_e32 v240, v240, v238
	v_sub_f32_e32 v244, v244, v238
	v_mul_f32_e32 v240, v240, v239
	v_mul_f32_e32 v244, v244, v239
	v_fma_f32 v240, v144, v240, v160
	v_fma_f32 v244, v145, v244, v161
	v_lshlrev_b32_e32 v241, 16, v193
	v_and_b32_e32 v245, 0xffff0000, v193
	v_lshlrev_b32_e32 v243, 16, v201
	v_and_b32_e32 v246, 0xffff0000, v201
	v_sub_f32_e32 v243, v243, v241
	v_sub_f32_e32 v246, v246, v245
	v_fmac_f32_e32 v241, v176, v243
	v_fmac_f32_e32 v245, v177, v246
	v_fmac_f32_e32 v240, v234, v241
	v_fmac_f32_e32 v244, v234, v245
	v_mul_f32_e32 v30, v30, v240
	v_mul_f32_e32 v31, v31, v244
	v_cvt_pk_bf16_f32 v24, v24, v25
	v_cvt_pk_bf16_f32 v25, v26, v27
	v_cvt_pk_bf16_f32 v26, v28, v29
	v_cvt_pk_bf16_f32 v27, v30, v31
	global_store_dwordx4 v247, v[24:27], s[22:23] offset:192
	v_add_u32_e32 v236, 0x10000, v230
	v_add_u32_e32 v237, 0x2c000, v231
	v_subrev_u32_e32 v240, 0x1600, v237
	global_load_dwordx4 v[178:181], v236, s[22:23] offset:128 sc0
	global_load_dwordx4 v[182:185], v236, s[22:23] offset:192 sc0
	global_load_dwordx4 v[186:189], v237, s[96:97] offset:128 sc0
	global_load_dwordx4 v[190:193], v237, s[96:97] offset:192 sc0
	global_load_dwordx4 v[194:197], v240, s[96:97] offset:128 sc0
	global_load_dwordx4 v[198:201], v240, s[96:97] offset:192 sc0
	v_add_u32_e32 v236, 0x1800, v232
	s_nop 0
	global_load_dword v234, v236, s[96:97] offset:16
	s_waitcnt vmcnt(9)
; __device__ __forceinline__ float bf2f(u16 h) { return __uint_as_float(((unsigned)h) << 16); }
; template <int EPI> ...
;     ...
;       for (int i = 0; i < 16; i++) {
;         const int rl = rbase + (i & 3) + 8 * (i >> 2);
;         const int row = m0 + rl;
;         float o0 = bf2f(Y[(size_t)row * 1024 + 256 + ch0]);
;         float o1 = bf2f(Y[(size_t)row * 1024 + 256 + ch1]);
;         float mean = hsum32(o0 + o1) * (1.0f / 64.0f);
;         float d0 = o0 - mean, d1 = o1 - mean;
;         float var = hsum32(d0 * d0 + d1 * d1) * (1.0f / 64.0f);
;         float rstd = rsqrtf(var + 64e-5f);
;         float pv0 = bf2f(P[(size_t)row * 2816 + 256 + 1536 + ch0]);
;         float pv1 = bf2f(P[(size_t)row * 2816 + 256 + 1536 + ch1]);
;         float pp0 = prevP(p, P, row, 1536 + ch0), pp1 = prevP(p, P, row, 1536 + ch1);
;         float vv0 = pv0 + (pp0 - pv0) * mu0, vv1 = pv1 + (pp1 - pv1) * mu1;
;         float b = bs[((size_t)row * 12 + hh) * 4 + 2];
;         float y0 = (d0 * rstd * gg0 + gb0 + b * vv0) * acc0[i];
;         float y1 = (d1 * rstd * gg1 + gb1 + b * vv1) * acc1[i];
;         Y[(size_t)row * 1024 + 256 + ch0] = f2bf(y0);
;         Y[(size_t)row * 1024 + 256 + ch1] = f2bf(y1);
	v_lshlrev_b32_e32 v240, 16, v202
	v_and_b32_e32 v241, 0xffff0000, v202
	v_add_f32_e32 v244, v240, v241
	v_lshlrev_b32_e32 v240, 16, v203
	v_and_b32_e32 v241, 0xffff0000, v203
	v_add_f32_e32 v244, v244, v240
	v_add_f32_e32 v244, v244, v241
	v_lshlrev_b32_e32 v240, 16, v204
	v_and_b32_e32 v241, 0xffff0000, v204
	v_add_f32_e32 v244, v244, v240
	v_add_f32_e32 v244, v244, v241
	v_lshlrev_b32_e32 v240, 16, v205
	v_and_b32_e32 v241, 0xffff0000, v205
	v_add_f32_e32 v244, v244, v240
	v_add_f32_e32 v244, v244, v241
	v_lshlrev_b32_e32 v240, 16, v206
	v_and_b32_e32 v241, 0xffff0000, v206
	v_add_f32_e32 v244, v244, v240
	v_add_f32_e32 v244, v244, v241
	v_lshlrev_b32_e32 v240, 16, v207
	v_and_b32_e32 v241, 0xffff0000, v207
	v_add_f32_e32 v244, v244, v240
	v_add_f32_e32 v244, v244, v241
	v_lshlrev_b32_e32 v240, 16, v208
	v_and_b32_e32 v241, 0xffff0000, v208
	v_add_f32_e32 v244, v244, v240
	v_add_f32_e32 v244, v244, v241
	v_lshlrev_b32_e32 v240, 16, v209
	v_and_b32_e32 v241, 0xffff0000, v209
	v_add_f32_e32 v244, v244, v240
	v_add_f32_e32 v244, v244, v241
	v_mov_b32_e32 v240, v244
	s_nop 1
	v_permlane16_swap_b32_e32 v240, v244
	v_add_f32_e32 v244, v244, v240
	v_mov_b32_e32 v240, v244
	s_nop 1
	v_permlane32_swap_b32_e32 v240, v244
	v_add_f32_e32 v244, v244, v240
	v_mul_f32_e32 v238, 0x3c800000, v244
	v_lshlrev_b32_e32 v240, 16, v202
	v_and_b32_e32 v241, 0xffff0000, v202
	v_sub_f32_e32 v240, v240, v238
	v_sub_f32_e32 v241, v241, v238
	v_mul_f32_e32 v245, v240, v240
	v_fmac_f32_e32 v245, v241, v241
	v_lshlrev_b32_e32 v240, 16, v203
	v_and_b32_e32 v241, 0xffff0000, v203
	v_sub_f32_e32 v240, v240, v238
	v_sub_f32_e32 v241, v241, v238
	v_fmac_f32_e32 v245, v240, v240
	v_fmac_f32_e32 v245, v241, v241
	v_lshlrev_b32_e32 v240, 16, v204
	v_and_b32_e32 v241, 0xffff0000, v204
	v_sub_f32_e32 v240, v240, v238
	v_sub_f32_e32 v241, v241, v238
	v_fmac_f32_e32 v245, v240, v240
	v_fmac_f32_e32 v245, v241, v241
	v_lshlrev_b32_e32 v240, 16, v205
	v_and_b32_e32 v241, 0xffff0000, v205
	v_sub_f32_e32 v240, v240, v238
	v_sub_f32_e32 v241, v241, v238
	v_fmac_f32_e32 v245, v240, v240
	v_fmac_f32_e32 v245, v241, v241
	v_lshlrev_b32_e32 v240, 16, v206
	v_and_b32_e32 v241, 0xffff0000, v206
	v_sub_f32_e32 v240, v240, v238
	v_sub_f32_e32 v241, v241, v238
	v_fmac_f32_e32 v245, v240, v240
	v_fmac_f32_e32 v245, v241, v241
	v_lshlrev_b32_e32 v240, 16, v207
	v_and_b32_e32 v241, 0xffff0000, v207
	v_sub_f32_e32 v240, v240, v238
	v_sub_f32_e32 v241, v241, v238
	v_fmac_f32_e32 v245, v240, v240
	v_fmac_f32_e32 v245, v241, v241
	v_lshlrev_b32_e32 v240, 16, v208
	v_and_b32_e32 v241, 0xffff0000, v208
	v_sub_f32_e32 v240, v240, v238
	v_sub_f32_e32 v241, v241, v238
	v_fmac_f32_e32 v245, v240, v240
	v_fmac_f32_e32 v245, v241, v241
	v_lshlrev_b32_e32 v240, 16, v209
	v_and_b32_e32 v241, 0xffff0000, v209
	v_sub_f32_e32 v240, v240, v238
	v_sub_f32_e32 v241, v241, v238
	v_fmac_f32_e32 v245, v240, v240
	v_fmac_f32_e32 v245, v241, v241
	v_mov_b32_e32 v240, v245
	s_nop 1
	v_permlane16_swap_b32_e32 v240, v245
	v_add_f32_e32 v245, v245, v240
	v_mov_b32_e32 v240, v245
	s_nop 1
	v_permlane32_swap_b32_e32 v240, v245
	v_add_f32_e32 v245, v245, v240
	v_mov_b32_e32 v240, 0x3a27c5ac
	v_fmamk_f32 v245, v245, 0x3c800000, v240
	v_rsq_f32_e32 v239, v245
	v_add_u32_e32 v247, 0x8000, v230
	v_lshlrev_b32_e32 v240, 16, v202
	v_and_b32_e32 v244, 0xffff0000, v202
	v_sub_f32_e32 v240, v240, v238
	v_sub_f32_e32 v244, v244, v238
	v_mul_f32_e32 v240, v240, v239
	v_mul_f32_e32 v244, v244, v239
	v_fma_f32 v240, v130, v240, v146
	v_fma_f32 v244, v131, v244, v147
	v_lshlrev_b32_e32 v241, 16, v210
	v_and_b32_e32 v245, 0xffff0000, v210
	v_lshlrev_b32_e32 v243, 16, v218
	v_and_b32_e32 v246, 0xffff0000, v218
	v_sub_f32_e32 v243, v243, v241
	v_sub_f32_e32 v246, v246, v245
	v_fmac_f32_e32 v241, v162, v243
	v_fmac_f32_e32 v245, v163, v246
	v_fmac_f32_e32 v240, v235, v241
	v_fmac_f32_e32 v244, v235, v245
	v_mul_f32_e32 v48, v48, v240
	v_mul_f32_e32 v49, v49, v244
	v_lshlrev_b32_e32 v240, 16, v203
	v_and_b32_e32 v244, 0xffff0000, v203
	v_sub_f32_e32 v240, v240, v238
	v_sub_f32_e32 v244, v244, v238
	v_mul_f32_e32 v240, v240, v239
	v_mul_f32_e32 v244, v244, v239
	v_fma_f32 v240, v132, v240, v148
	v_fma_f32 v244, v133, v244, v149
	v_lshlrev_b32_e32 v241, 16, v211
	v_and_b32_e32 v245, 0xffff0000, v211
	v_lshlrev_b32_e32 v243, 16, v219
	v_and_b32_e32 v246, 0xffff0000, v219
	v_sub_f32_e32 v243, v243, v241
	v_sub_f32_e32 v246, v246, v245
	v_fmac_f32_e32 v241, v164, v243
	v_fmac_f32_e32 v245, v165, v246
	v_fmac_f32_e32 v240, v235, v241
	v_fmac_f32_e32 v244, v235, v245
	v_mul_f32_e32 v50, v50, v240
	v_mul_f32_e32 v51, v51, v244
	v_lshlrev_b32_e32 v240, 16, v204
	v_and_b32_e32 v244, 0xffff0000, v204
	v_sub_f32_e32 v240, v240, v238
	v_sub_f32_e32 v244, v244, v238
	v_mul_f32_e32 v240, v240, v239
	v_mul_f32_e32 v244, v244, v239
	v_fma_f32 v240, v134, v240, v150
	v_fma_f32 v244, v135, v244, v151
	v_lshlrev_b32_e32 v241, 16, v212
	v_and_b32_e32 v245, 0xffff0000, v212
	v_lshlrev_b32_e32 v243, 16, v220
	v_and_b32_e32 v246, 0xffff0000, v220
	v_sub_f32_e32 v243, v243, v241
	v_sub_f32_e32 v246, v246, v245
	v_fmac_f32_e32 v241, v166, v243
	v_fmac_f32_e32 v245, v167, v246
	v_fmac_f32_e32 v240, v235, v241
	v_fmac_f32_e32 v244, v235, v245
	v_mul_f32_e32 v52, v52, v240
	v_mul_f32_e32 v53, v53, v244
	v_lshlrev_b32_e32 v240, 16, v205
	v_and_b32_e32 v244, 0xffff0000, v205
	v_sub_f32_e32 v240, v240, v238
	v_sub_f32_e32 v244, v244, v238
	v_mul_f32_e32 v240, v240, v239
	v_mul_f32_e32 v244, v244, v239
	v_fma_f32 v240, v136, v240, v152
	v_fma_f32 v244, v137, v244, v153
	v_lshlrev_b32_e32 v241, 16, v213
	v_and_b32_e32 v245, 0xffff0000, v213
	v_lshlrev_b32_e32 v243, 16, v221
; __device__ __forceinline__ float bf2f(u16 h) { return __uint_as_float(((unsigned)h) << 16); }
; template <int EPI> ...
;     ...
;       for (int i = 0; i < 16; i++) {
;         const int rl = rbase + (i & 3) + 8 * (i >> 2);
;         const int row = m0 + rl;
;         float o0 = bf2f(Y[(size_t)row * 1024 + 256 + ch0]);
;         float o1 = bf2f(Y[(size_t)row * 1024 + 256 + ch1]);
;         float mean = hsum32(o0 + o1) * (1.0f / 64.0f);
;         float d0 = o0 - mean, d1 = o1 - mean;
;         float var = hsum32(d0 * d0 + d1 * d1) * (1.0f / 64.0f);
;         float rstd = rsqrtf(var + 64e-5f);
;         float pv0 = bf2f(P[(size_t)row * 2816 + 256 + 1536 + ch0]);
;         float pv1 = bf2f(P[(size_t)row * 2816 + 256 + 1536 + ch1]);
;         float pp0 = prevP(p, P, row, 1536 + ch0), pp1 = prevP(p, P, row, 1536 + ch1);
;         float vv0 = pv0 + (pp0 - pv0) * mu0, vv1 = pv1 + (pp1 - pv1) * mu1;
;         float b = bs[((size_t)row * 12 + hh) * 4 + 2];
;         float y0 = (d0 * rstd * gg0 + gb0 + b * vv0) * acc0[i];
;         float y1 = (d1 * rstd * gg1 + gb1 + b * vv1) * acc1[i];
;         Y[(size_t)row * 1024 + 256 + ch0] = f2bf(y0);
;         Y[(size_t)row * 1024 + 256 + ch1] = f2bf(y1);
	v_and_b32_e32 v246, 0xffff0000, v221
	v_sub_f32_e32 v243, v243, v241
	v_sub_f32_e32 v246, v246, v245
	v_fmac_f32_e32 v241, v168, v243
	v_fmac_f32_e32 v245, v169, v246
	v_fmac_f32_e32 v240, v235, v241
	v_fmac_f32_e32 v244, v235, v245
	v_mul_f32_e32 v54, v54, v240
	v_mul_f32_e32 v55, v55, v244
	v_cvt_pk_bf16_f32 v48, v48, v49
	v_cvt_pk_bf16_f32 v49, v50, v51
	v_cvt_pk_bf16_f32 v50, v52, v53
	v_cvt_pk_bf16_f32 v51, v54, v55
	global_store_dwordx4 v247, v[48:51], s[22:23] offset:128
	v_lshlrev_b32_e32 v240, 16, v206
	v_and_b32_e32 v244, 0xffff0000, v206
	v_sub_f32_e32 v240, v240, v238
	v_sub_f32_e32 v244, v244, v238
	v_mul_f32_e32 v240, v240, v239
	v_mul_f32_e32 v244, v244, v239
	v_fma_f32 v240, v138, v240, v154
	v_fma_f32 v244, v139, v244, v155
	v_lshlrev_b32_e32 v241, 16, v214
	v_and_b32_e32 v245, 0xffff0000, v214
	v_lshlrev_b32_e32 v243, 16, v222
	v_and_b32_e32 v246, 0xffff0000, v222
	v_sub_f32_e32 v243, v243, v241
	v_sub_f32_e32 v246, v246, v245
	v_fmac_f32_e32 v241, v170, v243
	v_fmac_f32_e32 v245, v171, v246
	v_fmac_f32_e32 v240, v235, v241
	v_fmac_f32_e32 v244, v235, v245
	v_mul_f32_e32 v56, v56, v240
	v_mul_f32_e32 v57, v57, v244
	v_lshlrev_b32_e32 v240, 16, v207
	v_and_b32_e32 v244, 0xffff0000, v207
	v_sub_f32_e32 v240, v240, v238
	v_sub_f32_e32 v244, v244, v238
	v_mul_f32_e32 v240, v240, v239
	v_mul_f32_e32 v244, v244, v239
	v_fma_f32 v240, v140, v240, v156
	v_fma_f32 v244, v141, v244, v157
	v_lshlrev_b32_e32 v241, 16, v215
	v_and_b32_e32 v245, 0xffff0000, v215
	v_lshlrev_b32_e32 v243, 16, v223
	v_and_b32_e32 v246, 0xffff0000, v223
	v_sub_f32_e32 v243, v243, v241
	v_sub_f32_e32 v246, v246, v245
	v_fmac_f32_e32 v241, v172, v243
	v_fmac_f32_e32 v245, v173, v246
	v_fmac_f32_e32 v240, v235, v241
	v_fmac_f32_e32 v244, v235, v245
	v_mul_f32_e32 v58, v58, v240
	v_mul_f32_e32 v59, v59, v244
	v_lshlrev_b32_e32 v240, 16, v208
	v_and_b32_e32 v244, 0xffff0000, v208
	v_sub_f32_e32 v240, v240, v238
	v_sub_f32_e32 v244, v244, v238
	v_mul_f32_e32 v240, v240, v239
	v_mul_f32_e32 v244, v244, v239
	v_fma_f32 v240, v142, v240, v158
	v_fma_f32 v244, v143, v244, v159
	v_lshlrev_b32_e32 v241, 16, v216
	v_and_b32_e32 v245, 0xffff0000, v216
	v_lshlrev_b32_e32 v243, 16, v224
	v_and_b32_e32 v246, 0xffff0000, v224
	v_sub_f32_e32 v243, v243, v241
	v_sub_f32_e32 v246, v246, v245
	v_fmac_f32_e32 v241, v174, v243
	v_fmac_f32_e32 v245, v175, v246
	v_fmac_f32_e32 v240, v235, v241
	v_fmac_f32_e32 v244, v235, v245
	v_mul_f32_e32 v60, v60, v240
	v_mul_f32_e32 v61, v61, v244
	v_lshlrev_b32_e32 v240, 16, v209
	v_and_b32_e32 v244, 0xffff0000, v209
	v_sub_f32_e32 v240, v240, v238
	v_sub_f32_e32 v244, v244, v238
	v_mul_f32_e32 v240, v240, v239
	v_mul_f32_e32 v244, v244, v239
	v_fma_f32 v240, v144, v240, v160
	v_fma_f32 v244, v145, v244, v161
	v_lshlrev_b32_e32 v241, 16, v217
	v_and_b32_e32 v245, 0xffff0000, v217
	v_lshlrev_b32_e32 v243, 16, v225
	v_and_b32_e32 v246, 0xffff0000, v225
	v_sub_f32_e32 v243, v243, v241
	v_sub_f32_e32 v246, v246, v245
	v_fmac_f32_e32 v241, v176, v243
	v_fmac_f32_e32 v245, v177, v246
	v_fmac_f32_e32 v240, v235, v241
	v_fmac_f32_e32 v244, v235, v245
	v_mul_f32_e32 v62, v62, v240
	v_mul_f32_e32 v63, v63, v244
	v_cvt_pk_bf16_f32 v56, v56, v57
	v_cvt_pk_bf16_f32 v57, v58, v59
	v_cvt_pk_bf16_f32 v58, v60, v61
	v_cvt_pk_bf16_f32 v59, v62, v63
	global_store_dwordx4 v247, v[56:59], s[22:23] offset:192
	v_add_u32_e32 v236, 0x18000, v230
	v_add_u32_e32 v237, 0x42000, v231
	v_subrev_u32_e32 v240, 0x1600, v237
	global_load_dwordx4 v[202:205], v236, s[22:23] offset:128 sc0
	global_load_dwordx4 v[206:209], v236, s[22:23] offset:192 sc0
	global_load_dwordx4 v[210:213], v237, s[96:97] offset:128 sc0
	global_load_dwordx4 v[214:217], v237, s[96:97] offset:192 sc0
	global_load_dwordx4 v[218:221], v240, s[96:97] offset:128 sc0
	global_load_dwordx4 v[222:225], v240, s[96:97] offset:192 sc0
	v_add_u32_e32 v236, 0x2400, v232
	s_nop 0
	global_load_dword v235, v236, s[96:97] offset:16
	s_waitcnt vmcnt(9)
	v_lshlrev_b32_e32 v240, 16, v178
	v_and_b32_e32 v241, 0xffff0000, v178
	v_add_f32_e32 v244, v240, v241
	v_lshlrev_b32_e32 v240, 16, v179
	v_and_b32_e32 v241, 0xffff0000, v179
	v_add_f32_e32 v244, v244, v240
	v_add_f32_e32 v244, v244, v241
	v_lshlrev_b32_e32 v240, 16, v180
	v_and_b32_e32 v241, 0xffff0000, v180
	v_add_f32_e32 v244, v244, v240
	v_add_f32_e32 v244, v244, v241
	v_lshlrev_b32_e32 v240, 16, v181
	v_and_b32_e32 v241, 0xffff0000, v181
	v_add_f32_e32 v244, v244, v240
	v_add_f32_e32 v244, v244, v241
	v_lshlrev_b32_e32 v240, 16, v182
	v_and_b32_e32 v241, 0xffff0000, v182
	v_add_f32_e32 v244, v244, v240
	v_add_f32_e32 v244, v244, v241
	v_lshlrev_b32_e32 v240, 16, v183
	v_and_b32_e32 v241, 0xffff0000, v183
	v_add_f32_e32 v244, v244, v240
	v_add_f32_e32 v244, v244, v241
	v_lshlrev_b32_e32 v240, 16, v184
	v_and_b32_e32 v241, 0xffff0000, v184
	v_add_f32_e32 v244, v244, v240
	v_add_f32_e32 v244, v244, v241
	v_lshlrev_b32_e32 v240, 16, v185
	v_and_b32_e32 v241, 0xffff0000, v185
	v_add_f32_e32 v244, v244, v240
	v_add_f32_e32 v244, v244, v241
	v_mov_b32_e32 v240, v244
	s_nop 1
	v_permlane16_swap_b32_e32 v240, v244
	v_add_f32_e32 v244, v244, v240
	v_mov_b32_e32 v240, v244
	s_nop 1
	v_permlane32_swap_b32_e32 v240, v244
	v_add_f32_e32 v244, v244, v240
	v_mul_f32_e32 v238, 0x3c800000, v244
	v_lshlrev_b32_e32 v240, 16, v178
	v_and_b32_e32 v241, 0xffff0000, v178
	v_sub_f32_e32 v240, v240, v238
	v_sub_f32_e32 v241, v241, v238
	v_mul_f32_e32 v245, v240, v240
	v_fmac_f32_e32 v245, v241, v241
	v_lshlrev_b32_e32 v240, 16, v179
	v_and_b32_e32 v241, 0xffff0000, v179
	v_sub_f32_e32 v240, v240, v238
	v_sub_f32_e32 v241, v241, v238
	v_fmac_f32_e32 v245, v240, v240
	v_fmac_f32_e32 v245, v241, v241
; __device__ __forceinline__ float bf2f(u16 h) { return __uint_as_float(((unsigned)h) << 16); }
; template <int EPI> ...
;     ...
;       for (int i = 0; i < 16; i++) {
;         const int rl = rbase + (i & 3) + 8 * (i >> 2);
;         const int row = m0 + rl;
;         float o0 = bf2f(Y[(size_t)row * 1024 + 256 + ch0]);
;         float o1 = bf2f(Y[(size_t)row * 1024 + 256 + ch1]);
;         float mean = hsum32(o0 + o1) * (1.0f / 64.0f);
;         float d0 = o0 - mean, d1 = o1 - mean;
;         float var = hsum32(d0 * d0 + d1 * d1) * (1.0f / 64.0f);
;         float rstd = rsqrtf(var + 64e-5f);
;         float pv0 = bf2f(P[(size_t)row * 2816 + 256 + 1536 + ch0]);
;         float pv1 = bf2f(P[(size_t)row * 2816 + 256 + 1536 + ch1]);
;         float pp0 = prevP(p, P, row, 1536 + ch0), pp1 = prevP(p, P, row, 1536 + ch1);
;         float vv0 = pv0 + (pp0 - pv0) * mu0, vv1 = pv1 + (pp1 - pv1) * mu1;
;         float b = bs[((size_t)row * 12 + hh) * 4 + 2];
;         float y0 = (d0 * rstd * gg0 + gb0 + b * vv0) * acc0[i];
;         float y1 = (d1 * rstd * gg1 + gb1 + b * vv1) * acc1[i];
;         Y[(size_t)row * 1024 + 256 + ch0] = f2bf(y0);
;         Y[(size_t)row * 1024 + 256 + ch1] = f2bf(y1);
	v_lshlrev_b32_e32 v240, 16, v180
	v_and_b32_e32 v241, 0xffff0000, v180
	v_sub_f32_e32 v240, v240, v238
	v_sub_f32_e32 v241, v241, v238
	v_fmac_f32_e32 v245, v240, v240
	v_fmac_f32_e32 v245, v241, v241
	v_lshlrev_b32_e32 v240, 16, v181
	v_and_b32_e32 v241, 0xffff0000, v181
	v_sub_f32_e32 v240, v240, v238
	v_sub_f32_e32 v241, v241, v238
	v_fmac_f32_e32 v245, v240, v240
	v_fmac_f32_e32 v245, v241, v241
	v_lshlrev_b32_e32 v240, 16, v182
	v_and_b32_e32 v241, 0xffff0000, v182
	v_sub_f32_e32 v240, v240, v238
	v_sub_f32_e32 v241, v241, v238
	v_fmac_f32_e32 v245, v240, v240
	v_fmac_f32_e32 v245, v241, v241
	v_lshlrev_b32_e32 v240, 16, v183
	v_and_b32_e32 v241, 0xffff0000, v183
	v_sub_f32_e32 v240, v240, v238
	v_sub_f32_e32 v241, v241, v238
	v_fmac_f32_e32 v245, v240, v240
	v_fmac_f32_e32 v245, v241, v241
	v_lshlrev_b32_e32 v240, 16, v184
	v_and_b32_e32 v241, 0xffff0000, v184
	v_sub_f32_e32 v240, v240, v238
	v_sub_f32_e32 v241, v241, v238
	v_fmac_f32_e32 v245, v240, v240
	v_fmac_f32_e32 v245, v241, v241
	v_lshlrev_b32_e32 v240, 16, v185
	v_and_b32_e32 v241, 0xffff0000, v185
	v_sub_f32_e32 v240, v240, v238
	v_sub_f32_e32 v241, v241, v238
	v_fmac_f32_e32 v245, v240, v240
	v_fmac_f32_e32 v245, v241, v241
	v_mov_b32_e32 v240, v245
	s_nop 1
	v_permlane16_swap_b32_e32 v240, v245
	v_add_f32_e32 v245, v245, v240
	v_mov_b32_e32 v240, v245
	s_nop 1
	v_permlane32_swap_b32_e32 v240, v245
	v_add_f32_e32 v245, v245, v240
	v_mov_b32_e32 v240, 0x3a27c5ac
	v_fmamk_f32 v245, v245, 0x3c800000, v240
	v_rsq_f32_e32 v239, v245
	v_add_u32_e32 v247, 0x10000, v230
	v_lshlrev_b32_e32 v240, 16, v178
	v_and_b32_e32 v244, 0xffff0000, v178
	v_sub_f32_e32 v240, v240, v238
	v_sub_f32_e32 v244, v244, v238
	v_mul_f32_e32 v240, v240, v239
	v_mul_f32_e32 v244, v244, v239
	v_fma_f32 v240, v130, v240, v146
	v_fma_f32 v244, v131, v244, v147
	v_lshlrev_b32_e32 v241, 16, v186
	v_and_b32_e32 v245, 0xffff0000, v186
	v_lshlrev_b32_e32 v243, 16, v194
	v_and_b32_e32 v246, 0xffff0000, v194
	v_sub_f32_e32 v243, v243, v241
	v_sub_f32_e32 v246, v246, v245
	v_fmac_f32_e32 v241, v162, v243
	v_fmac_f32_e32 v245, v163, v246
	v_fmac_f32_e32 v240, v234, v241
	v_fmac_f32_e32 v244, v234, v245
	v_mul_f32_e32 v80, v80, v240
	v_mul_f32_e32 v81, v81, v244
	v_lshlrev_b32_e32 v240, 16, v179
	v_and_b32_e32 v244, 0xffff0000, v179
	v_sub_f32_e32 v240, v240, v238
	v_sub_f32_e32 v244, v244, v238
	v_mul_f32_e32 v240, v240, v239
	v_mul_f32_e32 v244, v244, v239
	v_fma_f32 v240, v132, v240, v148
	v_fma_f32 v244, v133, v244, v149
	v_lshlrev_b32_e32 v241, 16, v187
	v_and_b32_e32 v245, 0xffff0000, v187
	v_lshlrev_b32_e32 v243, 16, v195
	v_and_b32_e32 v246, 0xffff0000, v195
	v_sub_f32_e32 v243, v243, v241
	v_sub_f32_e32 v246, v246, v245
	v_fmac_f32_e32 v241, v164, v243
	v_fmac_f32_e32 v245, v165, v246
	v_fmac_f32_e32 v240, v234, v241
	v_fmac_f32_e32 v244, v234, v245
	v_mul_f32_e32 v82, v82, v240
	v_mul_f32_e32 v83, v83, v244
	v_lshlrev_b32_e32 v240, 16, v180
	v_and_b32_e32 v244, 0xffff0000, v180
	v_sub_f32_e32 v240, v240, v238
	v_sub_f32_e32 v244, v244, v238
	v_mul_f32_e32 v240, v240, v239
	v_mul_f32_e32 v244, v244, v239
	v_fma_f32 v240, v134, v240, v150
	v_fma_f32 v244, v135, v244, v151
	v_lshlrev_b32_e32 v241, 16, v188
	v_and_b32_e32 v245, 0xffff0000, v188
	v_lshlrev_b32_e32 v243, 16, v196
	v_and_b32_e32 v246, 0xffff0000, v196
	v_sub_f32_e32 v243, v243, v241
	v_sub_f32_e32 v246, v246, v245
	v_fmac_f32_e32 v241, v166, v243
	v_fmac_f32_e32 v245, v167, v246
	v_fmac_f32_e32 v240, v234, v241
	v_fmac_f32_e32 v244, v234, v245
	v_mul_f32_e32 v84, v84, v240
	v_mul_f32_e32 v85, v85, v244
	v_lshlrev_b32_e32 v240, 16, v181
	v_and_b32_e32 v244, 0xffff0000, v181
	v_sub_f32_e32 v240, v240, v238
	v_sub_f32_e32 v244, v244, v238
	v_mul_f32_e32 v240, v240, v239
	v_mul_f32_e32 v244, v244, v239
	v_fma_f32 v240, v136, v240, v152
	v_fma_f32 v244, v137, v244, v153
	v_lshlrev_b32_e32 v241, 16, v189
	v_and_b32_e32 v245, 0xffff0000, v189
	v_lshlrev_b32_e32 v243, 16, v197
	v_and_b32_e32 v246, 0xffff0000, v197
	v_sub_f32_e32 v243, v243, v241
	v_sub_f32_e32 v246, v246, v245
	v_fmac_f32_e32 v241, v168, v243
	v_fmac_f32_e32 v245, v169, v246
	v_fmac_f32_e32 v240, v234, v241
	v_fmac_f32_e32 v244, v234, v245
	v_mul_f32_e32 v86, v86, v240
	v_mul_f32_e32 v87, v87, v244
	v_cvt_pk_bf16_f32 v80, v80, v81
	v_cvt_pk_bf16_f32 v81, v82, v83
	v_cvt_pk_bf16_f32 v82, v84, v85
	v_cvt_pk_bf16_f32 v83, v86, v87
	global_store_dwordx4 v247, v[80:83], s[22:23] offset:128
	v_lshlrev_b32_e32 v240, 16, v182
	v_and_b32_e32 v244, 0xffff0000, v182
	v_sub_f32_e32 v240, v240, v238
	v_sub_f32_e32 v244, v244, v238
	v_mul_f32_e32 v240, v240, v239
	v_mul_f32_e32 v244, v244, v239
	v_fma_f32 v240, v138, v240, v154
	v_fma_f32 v244, v139, v244, v155
	v_lshlrev_b32_e32 v241, 16, v190
	v_and_b32_e32 v245, 0xffff0000, v190
	v_lshlrev_b32_e32 v243, 16, v198
	v_and_b32_e32 v246, 0xffff0000, v198
	v_sub_f32_e32 v243, v243, v241
	v_sub_f32_e32 v246, v246, v245
	v_fmac_f32_e32 v241, v170, v243
	v_fmac_f32_e32 v245, v171, v246
	v_fmac_f32_e32 v240, v234, v241
	v_fmac_f32_e32 v244, v234, v245
	v_mul_f32_e32 v88, v88, v240
	v_mul_f32_e32 v89, v89, v244
	v_lshlrev_b32_e32 v240, 16, v183
	v_and_b32_e32 v244, 0xffff0000, v183
	v_sub_f32_e32 v240, v240, v238
	v_sub_f32_e32 v244, v244, v238
	v_mul_f32_e32 v240, v240, v239
	v_mul_f32_e32 v244, v244, v239
	v_fma_f32 v240, v140, v240, v156
	v_fma_f32 v244, v141, v244, v157
	v_lshlrev_b32_e32 v241, 16, v191
	v_and_b32_e32 v245, 0xffff0000, v191
	v_lshlrev_b32_e32 v243, 16, v199
	v_and_b32_e32 v246, 0xffff0000, v199
	v_sub_f32_e32 v243, v243, v241
	v_sub_f32_e32 v246, v246, v245
	v_fmac_f32_e32 v241, v172, v243
	v_fmac_f32_e32 v245, v173, v246
; __device__ __forceinline__ float bf2f(u16 h) { return __uint_as_float(((unsigned)h) << 16); }
; template <int EPI> ...
;     ...
;       for (int i = 0; i < 16; i++) {
;         const int rl = rbase + (i & 3) + 8 * (i >> 2);
;         const int row = m0 + rl;
;         float o0 = bf2f(Y[(size_t)row * 1024 + 256 + ch0]);
;         float o1 = bf2f(Y[(size_t)row * 1024 + 256 + ch1]);
;         float mean = hsum32(o0 + o1) * (1.0f / 64.0f);
;         float d0 = o0 - mean, d1 = o1 - mean;
;         float var = hsum32(d0 * d0 + d1 * d1) * (1.0f / 64.0f);
;         float rstd = rsqrtf(var + 64e-5f);
;         float pv0 = bf2f(P[(size_t)row * 2816 + 256 + 1536 + ch0]);
;         float pv1 = bf2f(P[(size_t)row * 2816 + 256 + 1536 + ch1]);
;         float pp0 = prevP(p, P, row, 1536 + ch0), pp1 = prevP(p, P, row, 1536 + ch1);
;         float vv0 = pv0 + (pp0 - pv0) * mu0, vv1 = pv1 + (pp1 - pv1) * mu1;
;         float b = bs[((size_t)row * 12 + hh) * 4 + 2];
;         float y0 = (d0 * rstd * gg0 + gb0 + b * vv0) * acc0[i];
;         float y1 = (d1 * rstd * gg1 + gb1 + b * vv1) * acc1[i];
;         Y[(size_t)row * 1024 + 256 + ch0] = f2bf(y0);
;         Y[(size_t)row * 1024 + 256 + ch1] = f2bf(y1);
	v_fmac_f32_e32 v240, v234, v241
	v_fmac_f32_e32 v244, v234, v245
	v_mul_f32_e32 v90, v90, v240
	v_mul_f32_e32 v91, v91, v244
	v_lshlrev_b32_e32 v240, 16, v184
	v_and_b32_e32 v244, 0xffff0000, v184
	v_sub_f32_e32 v240, v240, v238
	v_sub_f32_e32 v244, v244, v238
	v_mul_f32_e32 v240, v240, v239
	v_mul_f32_e32 v244, v244, v239
	v_fma_f32 v240, v142, v240, v158
	v_fma_f32 v244, v143, v244, v159
	v_lshlrev_b32_e32 v241, 16, v192
	v_and_b32_e32 v245, 0xffff0000, v192
	v_lshlrev_b32_e32 v243, 16, v200
	v_and_b32_e32 v246, 0xffff0000, v200
	v_sub_f32_e32 v243, v243, v241
	v_sub_f32_e32 v246, v246, v245
	v_fmac_f32_e32 v241, v174, v243
	v_fmac_f32_e32 v245, v175, v246
	v_fmac_f32_e32 v240, v234, v241
	v_fmac_f32_e32 v244, v234, v245
	v_mul_f32_e32 v92, v92, v240
	v_mul_f32_e32 v93, v93, v244
	v_lshlrev_b32_e32 v240, 16, v185
	v_and_b32_e32 v244, 0xffff0000, v185
	v_sub_f32_e32 v240, v240, v238
	v_sub_f32_e32 v244, v244, v238
	v_mul_f32_e32 v240, v240, v239
	v_mul_f32_e32 v244, v244, v239
	v_fma_f32 v240, v144, v240, v160
	v_fma_f32 v244, v145, v244, v161
	v_lshlrev_b32_e32 v241, 16, v193
	v_and_b32_e32 v245, 0xffff0000, v193
	v_lshlrev_b32_e32 v243, 16, v201
	v_and_b32_e32 v246, 0xffff0000, v201
	v_sub_f32_e32 v243, v243, v241
	v_sub_f32_e32 v246, v246, v245
	v_fmac_f32_e32 v241, v176, v243
	v_fmac_f32_e32 v245, v177, v246
	v_fmac_f32_e32 v240, v234, v241
	v_fmac_f32_e32 v244, v234, v245
	v_mul_f32_e32 v94, v94, v240
	v_mul_f32_e32 v95, v95, v244
	v_cvt_pk_bf16_f32 v88, v88, v89
	v_cvt_pk_bf16_f32 v89, v90, v91
	v_cvt_pk_bf16_f32 v90, v92, v93
	v_cvt_pk_bf16_f32 v91, v94, v95
	global_store_dwordx4 v247, v[88:91], s[22:23] offset:192
	s_waitcnt vmcnt(2)
	v_lshlrev_b32_e32 v240, 16, v202
	v_and_b32_e32 v241, 0xffff0000, v202
	v_add_f32_e32 v244, v240, v241
	v_lshlrev_b32_e32 v240, 16, v203
	v_and_b32_e32 v241, 0xffff0000, v203
	v_add_f32_e32 v244, v244, v240
	v_add_f32_e32 v244, v244, v241
	v_lshlrev_b32_e32 v240, 16, v204
	v_and_b32_e32 v241, 0xffff0000, v204
	v_add_f32_e32 v244, v244, v240
	v_add_f32_e32 v244, v244, v241
	v_lshlrev_b32_e32 v240, 16, v205
	v_and_b32_e32 v241, 0xffff0000, v205
	v_add_f32_e32 v244, v244, v240
	v_add_f32_e32 v244, v244, v241
	v_lshlrev_b32_e32 v240, 16, v206
	v_and_b32_e32 v241, 0xffff0000, v206
	v_add_f32_e32 v244, v244, v240
	v_add_f32_e32 v244, v244, v241
	v_lshlrev_b32_e32 v240, 16, v207
	v_and_b32_e32 v241, 0xffff0000, v207
	v_add_f32_e32 v244, v244, v240
	v_add_f32_e32 v244, v244, v241
	v_lshlrev_b32_e32 v240, 16, v208
	v_and_b32_e32 v241, 0xffff0000, v208
	v_add_f32_e32 v244, v244, v240
	v_add_f32_e32 v244, v244, v241
	v_lshlrev_b32_e32 v240, 16, v209
	v_and_b32_e32 v241, 0xffff0000, v209
	v_add_f32_e32 v244, v244, v240
	v_add_f32_e32 v244, v244, v241
	v_mov_b32_e32 v240, v244
	s_nop 1
	v_permlane16_swap_b32_e32 v240, v244
	v_add_f32_e32 v244, v244, v240
	v_mov_b32_e32 v240, v244
	s_nop 1
	v_permlane32_swap_b32_e32 v240, v244
	v_add_f32_e32 v244, v244, v240
	v_mul_f32_e32 v238, 0x3c800000, v244
	v_lshlrev_b32_e32 v240, 16, v202
	v_and_b32_e32 v241, 0xffff0000, v202
	v_sub_f32_e32 v240, v240, v238
	v_sub_f32_e32 v241, v241, v238
	v_mul_f32_e32 v245, v240, v240
	v_fmac_f32_e32 v245, v241, v241
	v_lshlrev_b32_e32 v240, 16, v203
	v_and_b32_e32 v241, 0xffff0000, v203
	v_sub_f32_e32 v240, v240, v238
	v_sub_f32_e32 v241, v241, v238
	v_fmac_f32_e32 v245, v240, v240
	v_fmac_f32_e32 v245, v241, v241
	v_lshlrev_b32_e32 v240, 16, v204
	v_and_b32_e32 v241, 0xffff0000, v204
	v_sub_f32_e32 v240, v240, v238
	v_sub_f32_e32 v241, v241, v238
	v_fmac_f32_e32 v245, v240, v240
	v_fmac_f32_e32 v245, v241, v241
	v_lshlrev_b32_e32 v240, 16, v205
	v_and_b32_e32 v241, 0xffff0000, v205
	v_sub_f32_e32 v240, v240, v238
	v_sub_f32_e32 v241, v241, v238
	v_fmac_f32_e32 v245, v240, v240
	v_fmac_f32_e32 v245, v241, v241
	v_lshlrev_b32_e32 v240, 16, v206
	v_and_b32_e32 v241, 0xffff0000, v206
	v_sub_f32_e32 v240, v240, v238
	v_sub_f32_e32 v241, v241, v238
	v_fmac_f32_e32 v245, v240, v240
	v_fmac_f32_e32 v245, v241, v241
	v_lshlrev_b32_e32 v240, 16, v207
	v_and_b32_e32 v241, 0xffff0000, v207
	v_sub_f32_e32 v240, v240, v238
	v_sub_f32_e32 v241, v241, v238
	v_fmac_f32_e32 v245, v240, v240
	v_fmac_f32_e32 v245, v241, v241
	v_lshlrev_b32_e32 v240, 16, v208
	v_and_b32_e32 v241, 0xffff0000, v208
	v_sub_f32_e32 v240, v240, v238
	v_sub_f32_e32 v241, v241, v238
	v_fmac_f32_e32 v245, v240, v240
	v_fmac_f32_e32 v245, v241, v241
	v_lshlrev_b32_e32 v240, 16, v209
	v_and_b32_e32 v241, 0xffff0000, v209
	v_sub_f32_e32 v240, v240, v238
	v_sub_f32_e32 v241, v241, v238
	v_fmac_f32_e32 v245, v240, v240
	v_fmac_f32_e32 v245, v241, v241
	v_mov_b32_e32 v240, v245
	s_nop 1
	v_permlane16_swap_b32_e32 v240, v245
	v_add_f32_e32 v245, v245, v240
	v_mov_b32_e32 v240, v245
	s_nop 1
	v_permlane32_swap_b32_e32 v240, v245
	v_add_f32_e32 v245, v245, v240
	v_mov_b32_e32 v240, 0x3a27c5ac
	v_fmamk_f32 v245, v245, 0x3c800000, v240
	v_rsq_f32_e32 v239, v245
	v_add_u32_e32 v247, 0x18000, v230
	v_lshlrev_b32_e32 v240, 16, v202
	v_and_b32_e32 v244, 0xffff0000, v202
	v_sub_f32_e32 v240, v240, v238
	v_sub_f32_e32 v244, v244, v238
	v_mul_f32_e32 v240, v240, v239
	v_mul_f32_e32 v244, v244, v239
	v_fma_f32 v240, v130, v240, v146
	v_fma_f32 v244, v131, v244, v147
	v_lshlrev_b32_e32 v241, 16, v210
	v_and_b32_e32 v245, 0xffff0000, v210
	v_lshlrev_b32_e32 v243, 16, v218
	v_and_b32_e32 v246, 0xffff0000, v218
	v_sub_f32_e32 v243, v243, v241
	v_sub_f32_e32 v246, v246, v245
	v_fmac_f32_e32 v241, v162, v243
	v_fmac_f32_e32 v245, v163, v246
	v_fmac_f32_e32 v240, v235, v241
	v_fmac_f32_e32 v244, v235, v245
	v_mul_f32_e32 v112, v112, v240
	v_mul_f32_e32 v113, v113, v244
	v_lshlrev_b32_e32 v240, 16, v203
; __device__ __forceinline__ float bf2f(u16 h) { return __uint_as_float(((unsigned)h) << 16); }
; template <int EPI> ...
;     ...
;       for (int i = 0; i < 16; i++) {
;         const int rl = rbase + (i & 3) + 8 * (i >> 2);
;         const int row = m0 + rl;
;         float o0 = bf2f(Y[(size_t)row * 1024 + 256 + ch0]);
;         float o1 = bf2f(Y[(size_t)row * 1024 + 256 + ch1]);
;         float mean = hsum32(o0 + o1) * (1.0f / 64.0f);
;         float d0 = o0 - mean, d1 = o1 - mean;
;         float var = hsum32(d0 * d0 + d1 * d1) * (1.0f / 64.0f);
;         float rstd = rsqrtf(var + 64e-5f);
;         float pv0 = bf2f(P[(size_t)row * 2816 + 256 + 1536 + ch0]);
;         float pv1 = bf2f(P[(size_t)row * 2816 + 256 + 1536 + ch1]);
;         float pp0 = prevP(p, P, row, 1536 + ch0), pp1 = prevP(p, P, row, 1536 + ch1);
;         float vv0 = pv0 + (pp0 - pv0) * mu0, vv1 = pv1 + (pp1 - pv1) * mu1;
;         float b = bs[((size_t)row * 12 + hh) * 4 + 2];
;         float y0 = (d0 * rstd * gg0 + gb0 + b * vv0) * acc0[i];
;         float y1 = (d1 * rstd * gg1 + gb1 + b * vv1) * acc1[i];
;         Y[(size_t)row * 1024 + 256 + ch0] = f2bf(y0);
;         Y[(size_t)row * 1024 + 256 + ch1] = f2bf(y1);
	v_and_b32_e32 v244, 0xffff0000, v203
	v_sub_f32_e32 v240, v240, v238
	v_sub_f32_e32 v244, v244, v238
	v_mul_f32_e32 v240, v240, v239
	v_mul_f32_e32 v244, v244, v239
	v_fma_f32 v240, v132, v240, v148
	v_fma_f32 v244, v133, v244, v149
	v_lshlrev_b32_e32 v241, 16, v211
	v_and_b32_e32 v245, 0xffff0000, v211
	v_lshlrev_b32_e32 v243, 16, v219
	v_and_b32_e32 v246, 0xffff0000, v219
	v_sub_f32_e32 v243, v243, v241
	v_sub_f32_e32 v246, v246, v245
	v_fmac_f32_e32 v241, v164, v243
	v_fmac_f32_e32 v245, v165, v246
	v_fmac_f32_e32 v240, v235, v241
	v_fmac_f32_e32 v244, v235, v245
	v_mul_f32_e32 v114, v114, v240
	v_mul_f32_e32 v115, v115, v244
	v_lshlrev_b32_e32 v240, 16, v204
	v_and_b32_e32 v244, 0xffff0000, v204
	v_sub_f32_e32 v240, v240, v238
	v_sub_f32_e32 v244, v244, v238
	v_mul_f32_e32 v240, v240, v239
	v_mul_f32_e32 v244, v244, v239
	v_fma_f32 v240, v134, v240, v150
	v_fma_f32 v244, v135, v244, v151
	v_lshlrev_b32_e32 v241, 16, v212
	v_and_b32_e32 v245, 0xffff0000, v212
	v_lshlrev_b32_e32 v243, 16, v220
	v_and_b32_e32 v246, 0xffff0000, v220
	v_sub_f32_e32 v243, v243, v241
	v_sub_f32_e32 v246, v246, v245
	v_fmac_f32_e32 v241, v166, v243
	v_fmac_f32_e32 v245, v167, v246
	v_fmac_f32_e32 v240, v235, v241
	v_fmac_f32_e32 v244, v235, v245
	v_mul_f32_e32 v116, v116, v240
	v_mul_f32_e32 v117, v117, v244
	v_lshlrev_b32_e32 v240, 16, v205
	v_and_b32_e32 v244, 0xffff0000, v205
	v_sub_f32_e32 v240, v240, v238
	v_sub_f32_e32 v244, v244, v238
	v_mul_f32_e32 v240, v240, v239
	v_mul_f32_e32 v244, v244, v239
	v_fma_f32 v240, v136, v240, v152
	v_fma_f32 v244, v137, v244, v153
	v_lshlrev_b32_e32 v241, 16, v213
	v_and_b32_e32 v245, 0xffff0000, v213
	v_lshlrev_b32_e32 v243, 16, v221
	v_and_b32_e32 v246, 0xffff0000, v221
	v_sub_f32_e32 v243, v243, v241
	v_sub_f32_e32 v246, v246, v245
	v_fmac_f32_e32 v241, v168, v243
	v_fmac_f32_e32 v245, v169, v246
	v_fmac_f32_e32 v240, v235, v241
	v_fmac_f32_e32 v244, v235, v245
	v_mul_f32_e32 v118, v118, v240
	v_mul_f32_e32 v119, v119, v244
	v_cvt_pk_bf16_f32 v112, v112, v113
	v_cvt_pk_bf16_f32 v113, v114, v115
	v_cvt_pk_bf16_f32 v114, v116, v117
	v_cvt_pk_bf16_f32 v115, v118, v119
	global_store_dwordx4 v247, v[112:115], s[22:23] offset:128
	v_lshlrev_b32_e32 v240, 16, v206
	v_and_b32_e32 v244, 0xffff0000, v206
	v_sub_f32_e32 v240, v240, v238
	v_sub_f32_e32 v244, v244, v238
	v_mul_f32_e32 v240, v240, v239
	v_mul_f32_e32 v244, v244, v239
	v_fma_f32 v240, v138, v240, v154
	v_fma_f32 v244, v139, v244, v155
	v_lshlrev_b32_e32 v241, 16, v214
	v_and_b32_e32 v245, 0xffff0000, v214
	v_lshlrev_b32_e32 v243, 16, v222
	v_and_b32_e32 v246, 0xffff0000, v222
	v_sub_f32_e32 v243, v243, v241
	v_sub_f32_e32 v246, v246, v245
	v_fmac_f32_e32 v241, v170, v243
	v_fmac_f32_e32 v245, v171, v246
	v_fmac_f32_e32 v240, v235, v241
	v_fmac_f32_e32 v244, v235, v245
	v_mul_f32_e32 v120, v120, v240
	v_mul_f32_e32 v121, v121, v244
	v_lshlrev_b32_e32 v240, 16, v207
	v_and_b32_e32 v244, 0xffff0000, v207
	v_sub_f32_e32 v240, v240, v238
	v_sub_f32_e32 v244, v244, v238
	v_mul_f32_e32 v240, v240, v239
	v_mul_f32_e32 v244, v244, v239
	v_fma_f32 v240, v140, v240, v156
	v_fma_f32 v244, v141, v244, v157
	v_lshlrev_b32_e32 v241, 16, v215
	v_and_b32_e32 v245, 0xffff0000, v215
	v_lshlrev_b32_e32 v243, 16, v223
	v_and_b32_e32 v246, 0xffff0000, v223
	v_sub_f32_e32 v243, v243, v241
	v_sub_f32_e32 v246, v246, v245
	v_fmac_f32_e32 v241, v172, v243
	v_fmac_f32_e32 v245, v173, v246
	v_fmac_f32_e32 v240, v235, v241
	v_fmac_f32_e32 v244, v235, v245
	v_mul_f32_e32 v122, v122, v240
	v_mul_f32_e32 v123, v123, v244
	v_lshlrev_b32_e32 v240, 16, v208
	v_and_b32_e32 v244, 0xffff0000, v208
	v_sub_f32_e32 v240, v240, v238
	v_sub_f32_e32 v244, v244, v238
	v_mul_f32_e32 v240, v240, v239
	v_mul_f32_e32 v244, v244, v239
	v_fma_f32 v240, v142, v240, v158
	v_fma_f32 v244, v143, v244, v159
	v_lshlrev_b32_e32 v241, 16, v216
	v_and_b32_e32 v245, 0xffff0000, v216
	v_lshlrev_b32_e32 v243, 16, v224
	v_and_b32_e32 v246, 0xffff0000, v224
	v_sub_f32_e32 v243, v243, v241
	v_sub_f32_e32 v246, v246, v245
	v_fmac_f32_e32 v241, v174, v243
	v_fmac_f32_e32 v245, v175, v246
	v_fmac_f32_e32 v240, v235, v241
	v_fmac_f32_e32 v244, v235, v245
	v_mul_f32_e32 v124, v124, v240
	v_mul_f32_e32 v125, v125, v244
	v_lshlrev_b32_e32 v240, 16, v209
	v_and_b32_e32 v244, 0xffff0000, v209
	v_sub_f32_e32 v240, v240, v238
	v_sub_f32_e32 v244, v244, v238
	v_mul_f32_e32 v240, v240, v239
	v_mul_f32_e32 v244, v244, v239
	v_fma_f32 v240, v144, v240, v160
	v_fma_f32 v244, v145, v244, v161
	v_lshlrev_b32_e32 v241, 16, v217
	v_and_b32_e32 v245, 0xffff0000, v217
	v_lshlrev_b32_e32 v243, 16, v225
	v_and_b32_e32 v246, 0xffff0000, v225
	v_sub_f32_e32 v243, v243, v241
	v_sub_f32_e32 v246, v246, v245
	v_fmac_f32_e32 v241, v176, v243
	v_fmac_f32_e32 v245, v177, v246
	v_fmac_f32_e32 v240, v235, v241
	v_fmac_f32_e32 v244, v235, v245
	v_mul_f32_e32 v126, v126, v240
	v_mul_f32_e32 v127, v127, v244
	v_cvt_pk_bf16_f32 v120, v120, v121
	v_cvt_pk_bf16_f32 v121, v122, v123
	v_cvt_pk_bf16_f32 v122, v124, v125
	v_cvt_pk_bf16_f32 v123, v126, v127
	global_store_dwordx4 v247, v[120:123], s[22:23] offset:192
	s_branch .Lpo_done
; __device__ __forceinline__ float bf2f(u16 h) { return __uint_as_float(((unsigned)h) << 16); }
; __device__ __forceinline__ float prevP(const Params& p, const u16* P, int row, int c) {
;   const int rp = row > 0 ? row - 1 : 0;
;   float v = bf2f(P[(size_t)rp * 2816 + 256 + c]);
;   const bool start = (row < NP) ? ((row & 2047) == 0) : (((row - NP) & 3) == 0);
;   if (start) v = (row < NP) ? 0.f : p.in[3][(size_t)((row - NP) >> 2) * 2560 + c];
;   return v;
; template <int EPI> ...
;     ...
;       const int ch0 = hh * 64 + (lane & 31), ch1 = ch0 + 32;
;       const float gg0 = p.in[20][ch0], gg1 = p.in[20][ch1];
;       const float gb0 = p.in[21][ch0], gb1 = p.in[21][ch1];
;       const float mu0 = p.in[11][1536 + ch0], mu1 = p.in[11][1536 + ch1];
; #pragma unroll 16
;       for (int i = 0; i < 16; i++) {
;         const int rl = rbase + (i & 3) + 8 * (i >> 2);
;         const int row = m0 + rl;
;         float o0 = bf2f(Y[(size_t)row * 1024 + 256 + ch0]);
;         float o1 = bf2f(Y[(size_t)row * 1024 + 256 + ch1]);
;         float mean = hsum32(o0 + o1) * (1.0f / 64.0f);
;         float d0 = o0 - mean, d1 = o1 - mean;
;         float var = hsum32(d0 * d0 + d1 * d1) * (1.0f / 64.0f);
;         float rstd = rsqrtf(var + 64e-5f);
;         float pv0 = bf2f(P[(size_t)row * 2816 + 256 + 1536 + ch0]);
;         float pv1 = bf2f(P[(size_t)row * 2816 + 256 + 1536 + ch1]);
;         float pp0 = prevP(p, P, row, 1536 + ch0), pp1 = prevP(p, P, row, 1536 + ch1);
;         float vv0 = pv0 + (pp0 - pv0) * mu0, vv1 = pv1 + (pp1 - pv1) * mu1;
;         float b = bs[((size_t)row * 12 + hh) * 4 + 2];
.Lpo_sample:
	s_sub_u32 s11, s6, 64
	s_lshl_b32 s11, s11, 6
	s_lshl_b32 s12, s4, 4
	s_add_u32 s11, s11, s12
	v_lshrrev_b32_e32 v247, 2, v248
	v_add_u32_e32 v247, s11, v247
	v_mul_u32_u24_e32 v247, 0x2800, v247
	v_add_u32_e32 v247, v247, v233
	v_add_u32_e32 v247, 0x1800, v247
	v_add_u32_e32 v236, 0x8000, v230
	v_add_u32_e32 v237, 0x16000, v231
	v_add_u32_e32 v240, 0xa000, v247
	global_load_dwordx4 v[218:221], v236, s[22:23] offset:0
	global_load_dwordx4 v[222:225], v237, s[96:97] offset:0
	global_load_dwordx4 v[218:221], v240, s[20:21] offset:0
	global_load_dwordx4 v[222:225], v240, s[20:21] offset:16
	global_load_dwordx4 v[218:221], v236, s[22:23] offset:64
	global_load_dwordx4 v[222:225], v237, s[96:97] offset:64
	global_load_dwordx4 v[218:221], v240, s[20:21] offset:128
	global_load_dwordx4 v[222:225], v240, s[20:21] offset:144
	v_add_u32_e32 v236, 0x10000, v230
	v_add_u32_e32 v237, 0x2c000, v231
	v_add_u32_e32 v240, 0x14000, v247
	global_load_dwordx4 v[218:221], v236, s[22:23] offset:0
	global_load_dwordx4 v[222:225], v237, s[96:97] offset:0
	global_load_dwordx4 v[218:221], v240, s[20:21] offset:0
	global_load_dwordx4 v[222:225], v240, s[20:21] offset:16
	global_load_dwordx4 v[218:221], v236, s[22:23] offset:64
	global_load_dwordx4 v[222:225], v237, s[96:97] offset:64
	global_load_dwordx4 v[218:221], v240, s[20:21] offset:128
	global_load_dwordx4 v[222:225], v240, s[20:21] offset:144
	v_add_u32_e32 v236, 0x18000, v230
	v_add_u32_e32 v237, 0x42000, v231
	v_add_u32_e32 v240, 0x1e000, v247
	global_load_dwordx4 v[218:221], v236, s[22:23] offset:0
	global_load_dwordx4 v[222:225], v237, s[96:97] offset:0
	global_load_dwordx4 v[218:221], v240, s[20:21] offset:0
	global_load_dwordx4 v[222:225], v240, s[20:21] offset:16
	global_load_dwordx4 v[218:221], v236, s[22:23] offset:64
	global_load_dwordx4 v[222:225], v237, s[96:97] offset:64
	global_load_dwordx4 v[218:221], v240, s[20:21] offset:128
	global_load_dwordx4 v[222:225], v240, s[20:21] offset:144
	v_add_u32_e32 v236, 0x0, v230
	v_add_u32_e32 v237, 0x0, v231
	v_add_u32_e32 v240, 0x0, v247
	global_load_dwordx4 v[218:221], v236, s[22:23] offset:128
	global_load_dwordx4 v[222:225], v237, s[96:97] offset:128
	global_load_dwordx4 v[218:221], v240, s[20:21] offset:256
	global_load_dwordx4 v[222:225], v240, s[20:21] offset:272
	global_load_dwordx4 v[218:221], v236, s[22:23] offset:192
	global_load_dwordx4 v[222:225], v237, s[96:97] offset:192
	global_load_dwordx4 v[218:221], v240, s[20:21] offset:384
	global_load_dwordx4 v[222:225], v240, s[20:21] offset:400
	v_add_u32_e32 v236, 0x8000, v230
	v_add_u32_e32 v237, 0x16000, v231
	v_add_u32_e32 v240, 0xa000, v247
	global_load_dwordx4 v[218:221], v236, s[22:23] offset:128
	global_load_dwordx4 v[222:225], v237, s[96:97] offset:128
	global_load_dwordx4 v[218:221], v240, s[20:21] offset:256
	global_load_dwordx4 v[222:225], v240, s[20:21] offset:272
	global_load_dwordx4 v[218:221], v236, s[22:23] offset:192
	global_load_dwordx4 v[222:225], v237, s[96:97] offset:192
	global_load_dwordx4 v[218:221], v240, s[20:21] offset:384
	global_load_dwordx4 v[222:225], v240, s[20:21] offset:400
	v_add_u32_e32 v236, 0x10000, v230
	v_add_u32_e32 v237, 0x2c000, v231
	v_add_u32_e32 v240, 0x14000, v247
	global_load_dwordx4 v[218:221], v236, s[22:23] offset:128
	global_load_dwordx4 v[222:225], v237, s[96:97] offset:128
	global_load_dwordx4 v[218:221], v240, s[20:21] offset:256
	global_load_dwordx4 v[222:225], v240, s[20:21] offset:272
	global_load_dwordx4 v[218:221], v236, s[22:23] offset:192
	global_load_dwordx4 v[222:225], v237, s[96:97] offset:192
	global_load_dwordx4 v[218:221], v240, s[20:21] offset:384
	global_load_dwordx4 v[222:225], v240, s[20:21] offset:400
	v_add_u32_e32 v236, 0x18000, v230
	v_add_u32_e32 v237, 0x42000, v231
	v_add_u32_e32 v240, 0x1e000, v247
	global_load_dwordx4 v[218:221], v236, s[22:23] offset:128
	global_load_dwordx4 v[222:225], v237, s[96:97] offset:128
	global_load_dwordx4 v[218:221], v240, s[20:21] offset:256
	global_load_dwordx4 v[222:225], v240, s[20:21] offset:272
	global_load_dwordx4 v[218:221], v236, s[22:23] offset:192
	global_load_dwordx4 v[222:225], v237, s[96:97] offset:192
	global_load_dwordx4 v[218:221], v240, s[20:21] offset:384
	global_load_dwordx4 v[222:225], v240, s[20:21] offset:400
	global_load_dwordx4 v[130:133], v233, s[2:3] offset:0 sc0
	global_load_dwordx4 v[134:137], v233, s[2:3] offset:16 sc0
	global_load_dwordx4 v[138:141], v233, s[2:3] offset:128 sc0
	global_load_dwordx4 v[142:145], v233, s[2:3] offset:144 sc0
	global_load_dwordx4 v[146:149], v233, s[16:17] offset:0 sc0
	global_load_dwordx4 v[150:153], v233, s[16:17] offset:16 sc0
	global_load_dwordx4 v[154:157], v233, s[16:17] offset:128 sc0
	global_load_dwordx4 v[158:161], v233, s[16:17] offset:144 sc0
	global_load_dwordx4 v[162:165], v233, s[0:1] offset:0 sc0
	global_load_dwordx4 v[166:169], v233, s[0:1] offset:16 sc0
	global_load_dwordx4 v[170:173], v233, s[0:1] offset:128 sc0
	global_load_dwordx4 v[174:177], v233, s[0:1] offset:144 sc0
	v_add_u32_e32 v236, 0x0, v230
	v_add_u32_e32 v237, 0x0, v231
	v_subrev_u32_e32 v240, 0x1600, v237
	global_load_dwordx4 v[178:181], v236, s[22:23] offset:0 sc0
	global_load_dwordx4 v[182:185], v236, s[22:23] offset:64 sc0
	global_load_dwordx4 v[186:189], v237, s[96:97] offset:0 sc0
	global_load_dwordx4 v[190:193], v237, s[96:97] offset:64 sc0
	global_load_dwordx4 v[194:197], v240, s[96:97] offset:0 sc0
	global_load_dwordx4 v[198:201], v240, s[96:97] offset:64 sc0
	v_add_u32_e32 v236, 0x0, v232
	s_nop 0
	global_load_dword v234, v236, s[96:97] offset:0
	v_add_u32_e32 v237, 0x0, v247
	global_load_dwordx4 v[202:205], v237, s[20:21] offset:0 sc0
	global_load_dwordx4 v[206:209], v237, s[20:21] offset:16 sc0
	global_load_dwordx4 v[210:213], v237, s[20:21] offset:128 sc0
	global_load_dwordx4 v[214:217], v237, s[20:21] offset:144 sc0
	s_waitcnt vmcnt(0)
; __device__ __forceinline__ float bf2f(u16 h) { return __uint_as_float(((unsigned)h) << 16); }
; __device__ __forceinline__ float prevP(const Params& p, const u16* P, int row, int c) {
;     ...
;   const bool start = (row < NP) ? ((row & 2047) == 0) : (((row - NP) & 3) == 0);
;   if (start) v = (row < NP) ? 0.f : p.in[3][(size_t)((row - NP) >> 2) * 2560 + c];
; template <int EPI> ...
;     ...
;       for (int i = 0; i < 16; i++) {
;         const int rl = rbase + (i & 3) + 8 * (i >> 2);
;         const int row = m0 + rl;
;         float o0 = bf2f(Y[(size_t)row * 1024 + 256 + ch0]);
;         float o1 = bf2f(Y[(size_t)row * 1024 + 256 + ch1]);
;         float mean = hsum32(o0 + o1) * (1.0f / 64.0f);
;         float d0 = o0 - mean, d1 = o1 - mean;
;         float var = hsum32(d0 * d0 + d1 * d1) * (1.0f / 64.0f);
;         float rstd = rsqrtf(var + 64e-5f);
;         float pv0 = bf2f(P[(size_t)row * 2816 + 256 + 1536 + ch0]);
;         float pv1 = bf2f(P[(size_t)row * 2816 + 256 + 1536 + ch1]);
;         float pp0 = prevP(p, P, row, 1536 + ch0), pp1 = prevP(p, P, row, 1536 + ch1);
;         float vv0 = pv0 + (pp0 - pv0) * mu0, vv1 = pv1 + (pp1 - pv1) * mu1;
;         float b = bs[((size_t)row * 12 + hh) * 4 + 2];
;         float y0 = (d0 * rstd * gg0 + gb0 + b * vv0) * acc0[i];
;         float y1 = (d1 * rstd * gg1 + gb1 + b * vv1) * acc1[i];
;         Y[(size_t)row * 1024 + 256 + ch0] = f2bf(y0);
;         Y[(size_t)row * 1024 + 256 + ch1] = f2bf(y1);
	v_lshlrev_b32_e32 v240, 16, v178
	v_and_b32_e32 v241, 0xffff0000, v178
	v_add_f32_e32 v244, v240, v241
	v_lshlrev_b32_e32 v240, 16, v179
	v_and_b32_e32 v241, 0xffff0000, v179
	v_add_f32_e32 v244, v244, v240
	v_add_f32_e32 v244, v244, v241
	v_lshlrev_b32_e32 v240, 16, v180
	v_and_b32_e32 v241, 0xffff0000, v180
	v_add_f32_e32 v244, v244, v240
	v_add_f32_e32 v244, v244, v241
	v_lshlrev_b32_e32 v240, 16, v181
	v_and_b32_e32 v241, 0xffff0000, v181
	v_add_f32_e32 v244, v244, v240
	v_add_f32_e32 v244, v244, v241
	v_lshlrev_b32_e32 v240, 16, v182
	v_and_b32_e32 v241, 0xffff0000, v182
	v_add_f32_e32 v244, v244, v240
	v_add_f32_e32 v244, v244, v241
	v_lshlrev_b32_e32 v240, 16, v183
	v_and_b32_e32 v241, 0xffff0000, v183
	v_add_f32_e32 v244, v244, v240
	v_add_f32_e32 v244, v244, v241
	v_lshlrev_b32_e32 v240, 16, v184
	v_and_b32_e32 v241, 0xffff0000, v184
	v_add_f32_e32 v244, v244, v240
	v_add_f32_e32 v244, v244, v241
	v_lshlrev_b32_e32 v240, 16, v185
	v_and_b32_e32 v241, 0xffff0000, v185
	v_add_f32_e32 v244, v244, v240
	v_add_f32_e32 v244, v244, v241
	v_mov_b32_e32 v240, v244
	s_nop 1
	v_permlane16_swap_b32_e32 v240, v244
	v_add_f32_e32 v244, v244, v240
	v_mov_b32_e32 v240, v244
	s_nop 1
	v_permlane32_swap_b32_e32 v240, v244
	v_add_f32_e32 v244, v244, v240
	v_mul_f32_e32 v238, 0x3c800000, v244
	v_lshlrev_b32_e32 v240, 16, v178
	v_and_b32_e32 v241, 0xffff0000, v178
	v_sub_f32_e32 v240, v240, v238
	v_sub_f32_e32 v241, v241, v238
	v_mul_f32_e32 v245, v240, v240
	v_fmac_f32_e32 v245, v241, v241
	v_lshlrev_b32_e32 v240, 16, v179
	v_and_b32_e32 v241, 0xffff0000, v179
	v_sub_f32_e32 v240, v240, v238
	v_sub_f32_e32 v241, v241, v238
	v_fmac_f32_e32 v245, v240, v240
	v_fmac_f32_e32 v245, v241, v241
	v_lshlrev_b32_e32 v240, 16, v180
	v_and_b32_e32 v241, 0xffff0000, v180
	v_sub_f32_e32 v240, v240, v238
	v_sub_f32_e32 v241, v241, v238
	v_fmac_f32_e32 v245, v240, v240
	v_fmac_f32_e32 v245, v241, v241
	v_lshlrev_b32_e32 v240, 16, v181
	v_and_b32_e32 v241, 0xffff0000, v181
	v_sub_f32_e32 v240, v240, v238
	v_sub_f32_e32 v241, v241, v238
	v_fmac_f32_e32 v245, v240, v240
	v_fmac_f32_e32 v245, v241, v241
	v_lshlrev_b32_e32 v240, 16, v182
	v_and_b32_e32 v241, 0xffff0000, v182
	v_sub_f32_e32 v240, v240, v238
	v_sub_f32_e32 v241, v241, v238
	v_fmac_f32_e32 v245, v240, v240
	v_fmac_f32_e32 v245, v241, v241
	v_lshlrev_b32_e32 v240, 16, v183
	v_and_b32_e32 v241, 0xffff0000, v183
	v_sub_f32_e32 v240, v240, v238
	v_sub_f32_e32 v241, v241, v238
	v_fmac_f32_e32 v245, v240, v240
	v_fmac_f32_e32 v245, v241, v241
	v_lshlrev_b32_e32 v240, 16, v184
	v_and_b32_e32 v241, 0xffff0000, v184
	v_sub_f32_e32 v240, v240, v238
	v_sub_f32_e32 v241, v241, v238
	v_fmac_f32_e32 v245, v240, v240
	v_fmac_f32_e32 v245, v241, v241
	v_lshlrev_b32_e32 v240, 16, v185
	v_and_b32_e32 v241, 0xffff0000, v185
	v_sub_f32_e32 v240, v240, v238
	v_sub_f32_e32 v241, v241, v238
	v_fmac_f32_e32 v245, v240, v240
	v_fmac_f32_e32 v245, v241, v241
	v_mov_b32_e32 v240, v245
	s_nop 1
	v_permlane16_swap_b32_e32 v240, v245
	v_add_f32_e32 v245, v245, v240
	v_mov_b32_e32 v240, v245
	s_nop 1
	v_permlane32_swap_b32_e32 v240, v245
	v_add_f32_e32 v245, v245, v240
	v_mov_b32_e32 v240, 0x3a27c5ac
	v_fmamk_f32 v245, v245, 0x3c800000, v240
	v_rsq_f32_e32 v239, v245
	v_and_b32_e32 v240, 3, v248
	v_cmp_eq_u32_e32 vcc, 0, v240
	s_nop 1
	v_lshlrev_b32_e32 v240, 16, v178
	v_and_b32_e32 v244, 0xffff0000, v178
	v_sub_f32_e32 v240, v240, v238
	v_sub_f32_e32 v244, v244, v238
	v_mul_f32_e32 v240, v240, v239
	v_mul_f32_e32 v244, v244, v239
	v_fma_f32 v240, v130, v240, v146
	v_fma_f32 v244, v131, v244, v147
	v_lshlrev_b32_e32 v241, 16, v186
	v_and_b32_e32 v245, 0xffff0000, v186
	v_lshlrev_b32_e32 v243, 16, v194
	v_and_b32_e32 v246, 0xffff0000, v194
	v_cndmask_b32_e32 v243, v243, v202, vcc
	v_cndmask_b32_e32 v246, v246, v203, vcc
	v_sub_f32_e32 v243, v243, v241
	v_sub_f32_e32 v246, v246, v245
	v_fmac_f32_e32 v241, v162, v243
	v_fmac_f32_e32 v245, v163, v246
	v_fmac_f32_e32 v240, v234, v241
	v_fmac_f32_e32 v244, v234, v245
	v_mul_f32_e32 v0, v0, v240
	v_mul_f32_e32 v1, v1, v244
	v_lshlrev_b32_e32 v240, 16, v179
	v_and_b32_e32 v244, 0xffff0000, v179
	v_sub_f32_e32 v240, v240, v238
	v_sub_f32_e32 v244, v244, v238
	v_mul_f32_e32 v240, v240, v239
	v_mul_f32_e32 v244, v244, v239
	v_fma_f32 v240, v132, v240, v148
	v_fma_f32 v244, v133, v244, v149
	v_lshlrev_b32_e32 v241, 16, v187
	v_and_b32_e32 v245, 0xffff0000, v187
	v_lshlrev_b32_e32 v243, 16, v195
	v_and_b32_e32 v246, 0xffff0000, v195
	v_cndmask_b32_e32 v243, v243, v204, vcc
	v_cndmask_b32_e32 v246, v246, v205, vcc
	v_sub_f32_e32 v243, v243, v241
	v_sub_f32_e32 v246, v246, v245
	v_fmac_f32_e32 v241, v164, v243
	v_fmac_f32_e32 v245, v165, v246
	v_fmac_f32_e32 v240, v234, v241
	v_fmac_f32_e32 v244, v234, v245
	v_mul_f32_e32 v2, v2, v240
	v_mul_f32_e32 v3, v3, v244
	v_lshlrev_b32_e32 v240, 16, v180
	v_and_b32_e32 v244, 0xffff0000, v180
	v_sub_f32_e32 v240, v240, v238
	v_sub_f32_e32 v244, v244, v238
	v_mul_f32_e32 v240, v240, v239
	v_mul_f32_e32 v244, v244, v239
	v_fma_f32 v240, v134, v240, v150
	v_fma_f32 v244, v135, v244, v151
	v_lshlrev_b32_e32 v241, 16, v188
	v_and_b32_e32 v245, 0xffff0000, v188
	v_lshlrev_b32_e32 v243, 16, v196
	v_and_b32_e32 v246, 0xffff0000, v196
	v_cndmask_b32_e32 v243, v243, v206, vcc
	v_cndmask_b32_e32 v246, v246, v207, vcc
	v_sub_f32_e32 v243, v243, v241
	v_sub_f32_e32 v246, v246, v245
	v_fmac_f32_e32 v241, v166, v243
	v_fmac_f32_e32 v245, v167, v246
	v_fmac_f32_e32 v240, v234, v241
	v_fmac_f32_e32 v244, v234, v245
	v_mul_f32_e32 v4, v4, v240
	v_mul_f32_e32 v5, v5, v244
	v_lshlrev_b32_e32 v240, 16, v181
	v_and_b32_e32 v244, 0xffff0000, v181
	v_sub_f32_e32 v240, v240, v238
; __device__ __forceinline__ float bf2f(u16 h) { return __uint_as_float(((unsigned)h) << 16); }
; __device__ __forceinline__ float prevP(const Params& p, const u16* P, int row, int c) {
;     ...
;   const bool start = (row < NP) ? ((row & 2047) == 0) : (((row - NP) & 3) == 0);
;   if (start) v = (row < NP) ? 0.f : p.in[3][(size_t)((row - NP) >> 2) * 2560 + c];
; template <int EPI> ...
;     ...
;       for (int i = 0; i < 16; i++) {
;         const int rl = rbase + (i & 3) + 8 * (i >> 2);
;         const int row = m0 + rl;
;         float o0 = bf2f(Y[(size_t)row * 1024 + 256 + ch0]);
;         float o1 = bf2f(Y[(size_t)row * 1024 + 256 + ch1]);
;         float mean = hsum32(o0 + o1) * (1.0f / 64.0f);
;         float d0 = o0 - mean, d1 = o1 - mean;
;         float var = hsum32(d0 * d0 + d1 * d1) * (1.0f / 64.0f);
;         float rstd = rsqrtf(var + 64e-5f);
;         float pv0 = bf2f(P[(size_t)row * 2816 + 256 + 1536 + ch0]);
;         float pv1 = bf2f(P[(size_t)row * 2816 + 256 + 1536 + ch1]);
;         float pp0 = prevP(p, P, row, 1536 + ch0), pp1 = prevP(p, P, row, 1536 + ch1);
;         float vv0 = pv0 + (pp0 - pv0) * mu0, vv1 = pv1 + (pp1 - pv1) * mu1;
;         float b = bs[((size_t)row * 12 + hh) * 4 + 2];
;         float y0 = (d0 * rstd * gg0 + gb0 + b * vv0) * acc0[i];
;         float y1 = (d1 * rstd * gg1 + gb1 + b * vv1) * acc1[i];
;         Y[(size_t)row * 1024 + 256 + ch0] = f2bf(y0);
;         Y[(size_t)row * 1024 + 256 + ch1] = f2bf(y1);
	v_sub_f32_e32 v244, v244, v238
	v_mul_f32_e32 v240, v240, v239
	v_mul_f32_e32 v244, v244, v239
	v_fma_f32 v240, v136, v240, v152
	v_fma_f32 v244, v137, v244, v153
	v_lshlrev_b32_e32 v241, 16, v189
	v_and_b32_e32 v245, 0xffff0000, v189
	v_lshlrev_b32_e32 v243, 16, v197
	v_and_b32_e32 v246, 0xffff0000, v197
	v_cndmask_b32_e32 v243, v243, v208, vcc
	v_cndmask_b32_e32 v246, v246, v209, vcc
	v_sub_f32_e32 v243, v243, v241
	v_sub_f32_e32 v246, v246, v245
	v_fmac_f32_e32 v241, v168, v243
	v_fmac_f32_e32 v245, v169, v246
	v_fmac_f32_e32 v240, v234, v241
	v_fmac_f32_e32 v244, v234, v245
	v_mul_f32_e32 v6, v6, v240
	v_mul_f32_e32 v7, v7, v244
	v_cvt_pk_bf16_f32 v0, v0, v1
	v_cvt_pk_bf16_f32 v1, v2, v3
	v_cvt_pk_bf16_f32 v2, v4, v5
	v_cvt_pk_bf16_f32 v3, v6, v7
	v_add_u32_e32 v236, 0x0, v230
	s_nop 0
	global_store_dwordx4 v236, v[0:3], s[22:23] offset:0
	v_lshlrev_b32_e32 v240, 16, v182
	v_and_b32_e32 v244, 0xffff0000, v182
	v_sub_f32_e32 v240, v240, v238
	v_sub_f32_e32 v244, v244, v238
	v_mul_f32_e32 v240, v240, v239
	v_mul_f32_e32 v244, v244, v239
	v_fma_f32 v240, v138, v240, v154
	v_fma_f32 v244, v139, v244, v155
	v_lshlrev_b32_e32 v241, 16, v190
	v_and_b32_e32 v245, 0xffff0000, v190
	v_lshlrev_b32_e32 v243, 16, v198
	v_and_b32_e32 v246, 0xffff0000, v198
	v_cndmask_b32_e32 v243, v243, v210, vcc
	v_cndmask_b32_e32 v246, v246, v211, vcc
	v_sub_f32_e32 v243, v243, v241
	v_sub_f32_e32 v246, v246, v245
	v_fmac_f32_e32 v241, v170, v243
	v_fmac_f32_e32 v245, v171, v246
	v_fmac_f32_e32 v240, v234, v241
	v_fmac_f32_e32 v244, v234, v245
	v_mul_f32_e32 v8, v8, v240
	v_mul_f32_e32 v9, v9, v244
	v_lshlrev_b32_e32 v240, 16, v183
	v_and_b32_e32 v244, 0xffff0000, v183
	v_sub_f32_e32 v240, v240, v238
	v_sub_f32_e32 v244, v244, v238
	v_mul_f32_e32 v240, v240, v239
	v_mul_f32_e32 v244, v244, v239
	v_fma_f32 v240, v140, v240, v156
	v_fma_f32 v244, v141, v244, v157
	v_lshlrev_b32_e32 v241, 16, v191
	v_and_b32_e32 v245, 0xffff0000, v191
	v_lshlrev_b32_e32 v243, 16, v199
	v_and_b32_e32 v246, 0xffff0000, v199
	v_cndmask_b32_e32 v243, v243, v212, vcc
	v_cndmask_b32_e32 v246, v246, v213, vcc
	v_sub_f32_e32 v243, v243, v241
	v_sub_f32_e32 v246, v246, v245
	v_fmac_f32_e32 v241, v172, v243
	v_fmac_f32_e32 v245, v173, v246
	v_fmac_f32_e32 v240, v234, v241
	v_fmac_f32_e32 v244, v234, v245
	v_mul_f32_e32 v10, v10, v240
	v_mul_f32_e32 v11, v11, v244
	v_lshlrev_b32_e32 v240, 16, v184
	v_and_b32_e32 v244, 0xffff0000, v184
	v_sub_f32_e32 v240, v240, v238
	v_sub_f32_e32 v244, v244, v238
	v_mul_f32_e32 v240, v240, v239
	v_mul_f32_e32 v244, v244, v239
	v_fma_f32 v240, v142, v240, v158
	v_fma_f32 v244, v143, v244, v159
	v_lshlrev_b32_e32 v241, 16, v192
	v_and_b32_e32 v245, 0xffff0000, v192
	v_lshlrev_b32_e32 v243, 16, v200
	v_and_b32_e32 v246, 0xffff0000, v200
	v_cndmask_b32_e32 v243, v243, v214, vcc
	v_cndmask_b32_e32 v246, v246, v215, vcc
	v_sub_f32_e32 v243, v243, v241
	v_sub_f32_e32 v246, v246, v245
	v_fmac_f32_e32 v241, v174, v243
	v_fmac_f32_e32 v245, v175, v246
	v_fmac_f32_e32 v240, v234, v241
	v_fmac_f32_e32 v244, v234, v245
	v_mul_f32_e32 v12, v12, v240
	v_mul_f32_e32 v13, v13, v244
	v_lshlrev_b32_e32 v240, 16, v185
	v_and_b32_e32 v244, 0xffff0000, v185
	v_sub_f32_e32 v240, v240, v238
	v_sub_f32_e32 v244, v244, v238
	v_mul_f32_e32 v240, v240, v239
	v_mul_f32_e32 v244, v244, v239
	v_fma_f32 v240, v144, v240, v160
	v_fma_f32 v244, v145, v244, v161
	v_lshlrev_b32_e32 v241, 16, v193
	v_and_b32_e32 v245, 0xffff0000, v193
	v_lshlrev_b32_e32 v243, 16, v201
	v_and_b32_e32 v246, 0xffff0000, v201
	v_cndmask_b32_e32 v243, v243, v216, vcc
	v_cndmask_b32_e32 v246, v246, v217, vcc
	v_sub_f32_e32 v243, v243, v241
	v_sub_f32_e32 v246, v246, v245
	v_fmac_f32_e32 v241, v176, v243
	v_fmac_f32_e32 v245, v177, v246
	v_fmac_f32_e32 v240, v234, v241
	v_fmac_f32_e32 v244, v234, v245
	v_mul_f32_e32 v14, v14, v240
	v_mul_f32_e32 v15, v15, v244
	v_cvt_pk_bf16_f32 v8, v8, v9
	v_cvt_pk_bf16_f32 v9, v10, v11
	v_cvt_pk_bf16_f32 v10, v12, v13
	v_cvt_pk_bf16_f32 v11, v14, v15
	v_add_u32_e32 v236, 0x0, v230
	s_nop 0
	global_store_dwordx4 v236, v[8:11], s[22:23] offset:64
	v_add_u32_e32 v236, 0x8000, v230
	v_add_u32_e32 v237, 0x16000, v231
	v_subrev_u32_e32 v240, 0x1600, v237
	global_load_dwordx4 v[178:181], v236, s[22:23] offset:0 sc0
	global_load_dwordx4 v[182:185], v236, s[22:23] offset:64 sc0
	global_load_dwordx4 v[186:189], v237, s[96:97] offset:0 sc0
	global_load_dwordx4 v[190:193], v237, s[96:97] offset:64 sc0
	global_load_dwordx4 v[194:197], v240, s[96:97] offset:0 sc0
	global_load_dwordx4 v[198:201], v240, s[96:97] offset:64 sc0
	v_add_u32_e32 v236, 0xc00, v232
	s_nop 0
	global_load_dword v234, v236, s[96:97] offset:0
	v_add_u32_e32 v237, 0xa000, v247
	global_load_dwordx4 v[202:205], v237, s[20:21] offset:0 sc0
	global_load_dwordx4 v[206:209], v237, s[20:21] offset:16 sc0
	global_load_dwordx4 v[210:213], v237, s[20:21] offset:128 sc0
	global_load_dwordx4 v[214:217], v237, s[20:21] offset:144 sc0
	s_waitcnt vmcnt(0)
; __device__ __forceinline__ float bf2f(u16 h) { return __uint_as_float(((unsigned)h) << 16); }
; __device__ __forceinline__ float prevP(const Params& p, const u16* P, int row, int c) {
;     ...
;   const bool start = (row < NP) ? ((row & 2047) == 0) : (((row - NP) & 3) == 0);
;   if (start) v = (row < NP) ? 0.f : p.in[3][(size_t)((row - NP) >> 2) * 2560 + c];
; template <int EPI> ...
;     ...
;       for (int i = 0; i < 16; i++) {
;         const int rl = rbase + (i & 3) + 8 * (i >> 2);
;         const int row = m0 + rl;
;         float o0 = bf2f(Y[(size_t)row * 1024 + 256 + ch0]);
;         float o1 = bf2f(Y[(size_t)row * 1024 + 256 + ch1]);
;         float mean = hsum32(o0 + o1) * (1.0f / 64.0f);
;         float d0 = o0 - mean, d1 = o1 - mean;
;         float var = hsum32(d0 * d0 + d1 * d1) * (1.0f / 64.0f);
;         float rstd = rsqrtf(var + 64e-5f);
;         float pv0 = bf2f(P[(size_t)row * 2816 + 256 + 1536 + ch0]);
;         float pv1 = bf2f(P[(size_t)row * 2816 + 256 + 1536 + ch1]);
;         float pp0 = prevP(p, P, row, 1536 + ch0), pp1 = prevP(p, P, row, 1536 + ch1);
;         float vv0 = pv0 + (pp0 - pv0) * mu0, vv1 = pv1 + (pp1 - pv1) * mu1;
;         float b = bs[((size_t)row * 12 + hh) * 4 + 2];
;         float y0 = (d0 * rstd * gg0 + gb0 + b * vv0) * acc0[i];
;         float y1 = (d1 * rstd * gg1 + gb1 + b * vv1) * acc1[i];
;         Y[(size_t)row * 1024 + 256 + ch0] = f2bf(y0);
;         Y[(size_t)row * 1024 + 256 + ch1] = f2bf(y1);
	v_lshlrev_b32_e32 v240, 16, v178
	v_and_b32_e32 v241, 0xffff0000, v178
	v_add_f32_e32 v244, v240, v241
	v_lshlrev_b32_e32 v240, 16, v179
	v_and_b32_e32 v241, 0xffff0000, v179
	v_add_f32_e32 v244, v244, v240
	v_add_f32_e32 v244, v244, v241
	v_lshlrev_b32_e32 v240, 16, v180
	v_and_b32_e32 v241, 0xffff0000, v180
	v_add_f32_e32 v244, v244, v240
	v_add_f32_e32 v244, v244, v241
	v_lshlrev_b32_e32 v240, 16, v181
	v_and_b32_e32 v241, 0xffff0000, v181
	v_add_f32_e32 v244, v244, v240
	v_add_f32_e32 v244, v244, v241
	v_lshlrev_b32_e32 v240, 16, v182
	v_and_b32_e32 v241, 0xffff0000, v182
	v_add_f32_e32 v244, v244, v240
	v_add_f32_e32 v244, v244, v241
	v_lshlrev_b32_e32 v240, 16, v183
	v_and_b32_e32 v241, 0xffff0000, v183
	v_add_f32_e32 v244, v244, v240
	v_add_f32_e32 v244, v244, v241
	v_lshlrev_b32_e32 v240, 16, v184
	v_and_b32_e32 v241, 0xffff0000, v184
	v_add_f32_e32 v244, v244, v240
	v_add_f32_e32 v244, v244, v241
	v_lshlrev_b32_e32 v240, 16, v185
	v_and_b32_e32 v241, 0xffff0000, v185
	v_add_f32_e32 v244, v244, v240
	v_add_f32_e32 v244, v244, v241
	v_mov_b32_e32 v240, v244
	s_nop 1
	v_permlane16_swap_b32_e32 v240, v244
	v_add_f32_e32 v244, v244, v240
	v_mov_b32_e32 v240, v244
	s_nop 1
	v_permlane32_swap_b32_e32 v240, v244
	v_add_f32_e32 v244, v244, v240
	v_mul_f32_e32 v238, 0x3c800000, v244
	v_lshlrev_b32_e32 v240, 16, v178
	v_and_b32_e32 v241, 0xffff0000, v178
	v_sub_f32_e32 v240, v240, v238
	v_sub_f32_e32 v241, v241, v238
	v_mul_f32_e32 v245, v240, v240
	v_fmac_f32_e32 v245, v241, v241
	v_lshlrev_b32_e32 v240, 16, v179
	v_and_b32_e32 v241, 0xffff0000, v179
	v_sub_f32_e32 v240, v240, v238
	v_sub_f32_e32 v241, v241, v238
	v_fmac_f32_e32 v245, v240, v240
	v_fmac_f32_e32 v245, v241, v241
	v_lshlrev_b32_e32 v240, 16, v180
	v_and_b32_e32 v241, 0xffff0000, v180
	v_sub_f32_e32 v240, v240, v238
	v_sub_f32_e32 v241, v241, v238
	v_fmac_f32_e32 v245, v240, v240
	v_fmac_f32_e32 v245, v241, v241
	v_lshlrev_b32_e32 v240, 16, v181
	v_and_b32_e32 v241, 0xffff0000, v181
	v_sub_f32_e32 v240, v240, v238
	v_sub_f32_e32 v241, v241, v238
	v_fmac_f32_e32 v245, v240, v240
	v_fmac_f32_e32 v245, v241, v241
	v_lshlrev_b32_e32 v240, 16, v182
	v_and_b32_e32 v241, 0xffff0000, v182
	v_sub_f32_e32 v240, v240, v238
	v_sub_f32_e32 v241, v241, v238
	v_fmac_f32_e32 v245, v240, v240
	v_fmac_f32_e32 v245, v241, v241
	v_lshlrev_b32_e32 v240, 16, v183
	v_and_b32_e32 v241, 0xffff0000, v183
	v_sub_f32_e32 v240, v240, v238
	v_sub_f32_e32 v241, v241, v238
	v_fmac_f32_e32 v245, v240, v240
	v_fmac_f32_e32 v245, v241, v241
	v_lshlrev_b32_e32 v240, 16, v184
	v_and_b32_e32 v241, 0xffff0000, v184
	v_sub_f32_e32 v240, v240, v238
	v_sub_f32_e32 v241, v241, v238
	v_fmac_f32_e32 v245, v240, v240
	v_fmac_f32_e32 v245, v241, v241
	v_lshlrev_b32_e32 v240, 16, v185
	v_and_b32_e32 v241, 0xffff0000, v185
	v_sub_f32_e32 v240, v240, v238
	v_sub_f32_e32 v241, v241, v238
	v_fmac_f32_e32 v245, v240, v240
	v_fmac_f32_e32 v245, v241, v241
	v_mov_b32_e32 v240, v245
	s_nop 1
	v_permlane16_swap_b32_e32 v240, v245
	v_add_f32_e32 v245, v245, v240
	v_mov_b32_e32 v240, v245
	s_nop 1
	v_permlane32_swap_b32_e32 v240, v245
	v_add_f32_e32 v245, v245, v240
	v_mov_b32_e32 v240, 0x3a27c5ac
	v_fmamk_f32 v245, v245, 0x3c800000, v240
	v_rsq_f32_e32 v239, v245
	v_and_b32_e32 v240, 3, v248
	v_cmp_eq_u32_e32 vcc, 0, v240
	s_nop 1
	v_lshlrev_b32_e32 v240, 16, v178
	v_and_b32_e32 v244, 0xffff0000, v178
	v_sub_f32_e32 v240, v240, v238
	v_sub_f32_e32 v244, v244, v238
	v_mul_f32_e32 v240, v240, v239
	v_mul_f32_e32 v244, v244, v239
	v_fma_f32 v240, v130, v240, v146
	v_fma_f32 v244, v131, v244, v147
	v_lshlrev_b32_e32 v241, 16, v186
	v_and_b32_e32 v245, 0xffff0000, v186
	v_lshlrev_b32_e32 v243, 16, v194
	v_and_b32_e32 v246, 0xffff0000, v194
	v_cndmask_b32_e32 v243, v243, v202, vcc
	v_cndmask_b32_e32 v246, v246, v203, vcc
	v_sub_f32_e32 v243, v243, v241
	v_sub_f32_e32 v246, v246, v245
	v_fmac_f32_e32 v241, v162, v243
	v_fmac_f32_e32 v245, v163, v246
	v_fmac_f32_e32 v240, v234, v241
	v_fmac_f32_e32 v244, v234, v245
	v_mul_f32_e32 v32, v32, v240
	v_mul_f32_e32 v33, v33, v244
	v_lshlrev_b32_e32 v240, 16, v179
	v_and_b32_e32 v244, 0xffff0000, v179
	v_sub_f32_e32 v240, v240, v238
	v_sub_f32_e32 v244, v244, v238
	v_mul_f32_e32 v240, v240, v239
	v_mul_f32_e32 v244, v244, v239
	v_fma_f32 v240, v132, v240, v148
	v_fma_f32 v244, v133, v244, v149
	v_lshlrev_b32_e32 v241, 16, v187
	v_and_b32_e32 v245, 0xffff0000, v187
	v_lshlrev_b32_e32 v243, 16, v195
	v_and_b32_e32 v246, 0xffff0000, v195
	v_cndmask_b32_e32 v243, v243, v204, vcc
	v_cndmask_b32_e32 v246, v246, v205, vcc
	v_sub_f32_e32 v243, v243, v241
	v_sub_f32_e32 v246, v246, v245
	v_fmac_f32_e32 v241, v164, v243
	v_fmac_f32_e32 v245, v165, v246
	v_fmac_f32_e32 v240, v234, v241
	v_fmac_f32_e32 v244, v234, v245
	v_mul_f32_e32 v34, v34, v240
	v_mul_f32_e32 v35, v35, v244
	v_lshlrev_b32_e32 v240, 16, v180
	v_and_b32_e32 v244, 0xffff0000, v180
	v_sub_f32_e32 v240, v240, v238
	v_sub_f32_e32 v244, v244, v238
	v_mul_f32_e32 v240, v240, v239
	v_mul_f32_e32 v244, v244, v239
	v_fma_f32 v240, v134, v240, v150
	v_fma_f32 v244, v135, v244, v151
	v_lshlrev_b32_e32 v241, 16, v188
	v_and_b32_e32 v245, 0xffff0000, v188
	v_lshlrev_b32_e32 v243, 16, v196
	v_and_b32_e32 v246, 0xffff0000, v196
	v_cndmask_b32_e32 v243, v243, v206, vcc
	v_cndmask_b32_e32 v246, v246, v207, vcc
	v_sub_f32_e32 v243, v243, v241
	v_sub_f32_e32 v246, v246, v245
	v_fmac_f32_e32 v241, v166, v243
	v_fmac_f32_e32 v245, v167, v246
	v_fmac_f32_e32 v240, v234, v241
	v_fmac_f32_e32 v244, v234, v245
	v_mul_f32_e32 v36, v36, v240
	v_mul_f32_e32 v37, v37, v244
	v_lshlrev_b32_e32 v240, 16, v181
	v_and_b32_e32 v244, 0xffff0000, v181
	v_sub_f32_e32 v240, v240, v238
; __device__ __forceinline__ float bf2f(u16 h) { return __uint_as_float(((unsigned)h) << 16); }
; __device__ __forceinline__ float prevP(const Params& p, const u16* P, int row, int c) {
;     ...
;   const bool start = (row < NP) ? ((row & 2047) == 0) : (((row - NP) & 3) == 0);
;   if (start) v = (row < NP) ? 0.f : p.in[3][(size_t)((row - NP) >> 2) * 2560 + c];
; template <int EPI> ...
;     ...
;       for (int i = 0; i < 16; i++) {
;         const int rl = rbase + (i & 3) + 8 * (i >> 2);
;         const int row = m0 + rl;
;         float o0 = bf2f(Y[(size_t)row * 1024 + 256 + ch0]);
;         float o1 = bf2f(Y[(size_t)row * 1024 + 256 + ch1]);
;         float mean = hsum32(o0 + o1) * (1.0f / 64.0f);
;         float d0 = o0 - mean, d1 = o1 - mean;
;         float var = hsum32(d0 * d0 + d1 * d1) * (1.0f / 64.0f);
;         float rstd = rsqrtf(var + 64e-5f);
;         float pv0 = bf2f(P[(size_t)row * 2816 + 256 + 1536 + ch0]);
;         float pv1 = bf2f(P[(size_t)row * 2816 + 256 + 1536 + ch1]);
;         float pp0 = prevP(p, P, row, 1536 + ch0), pp1 = prevP(p, P, row, 1536 + ch1);
;         float vv0 = pv0 + (pp0 - pv0) * mu0, vv1 = pv1 + (pp1 - pv1) * mu1;
;         float b = bs[((size_t)row * 12 + hh) * 4 + 2];
;         float y0 = (d0 * rstd * gg0 + gb0 + b * vv0) * acc0[i];
;         float y1 = (d1 * rstd * gg1 + gb1 + b * vv1) * acc1[i];
;         Y[(size_t)row * 1024 + 256 + ch0] = f2bf(y0);
;         Y[(size_t)row * 1024 + 256 + ch1] = f2bf(y1);
	v_sub_f32_e32 v244, v244, v238
	v_mul_f32_e32 v240, v240, v239
	v_mul_f32_e32 v244, v244, v239
	v_fma_f32 v240, v136, v240, v152
	v_fma_f32 v244, v137, v244, v153
	v_lshlrev_b32_e32 v241, 16, v189
	v_and_b32_e32 v245, 0xffff0000, v189
	v_lshlrev_b32_e32 v243, 16, v197
	v_and_b32_e32 v246, 0xffff0000, v197
	v_cndmask_b32_e32 v243, v243, v208, vcc
	v_cndmask_b32_e32 v246, v246, v209, vcc
	v_sub_f32_e32 v243, v243, v241
	v_sub_f32_e32 v246, v246, v245
	v_fmac_f32_e32 v241, v168, v243
	v_fmac_f32_e32 v245, v169, v246
	v_fmac_f32_e32 v240, v234, v241
	v_fmac_f32_e32 v244, v234, v245
	v_mul_f32_e32 v38, v38, v240
	v_mul_f32_e32 v39, v39, v244
	v_cvt_pk_bf16_f32 v32, v32, v33
	v_cvt_pk_bf16_f32 v33, v34, v35
	v_cvt_pk_bf16_f32 v34, v36, v37
	v_cvt_pk_bf16_f32 v35, v38, v39
	v_add_u32_e32 v236, 0x8000, v230
	s_nop 0
	global_store_dwordx4 v236, v[32:35], s[22:23] offset:0
	v_lshlrev_b32_e32 v240, 16, v182
	v_and_b32_e32 v244, 0xffff0000, v182
	v_sub_f32_e32 v240, v240, v238
	v_sub_f32_e32 v244, v244, v238
	v_mul_f32_e32 v240, v240, v239
	v_mul_f32_e32 v244, v244, v239
	v_fma_f32 v240, v138, v240, v154
	v_fma_f32 v244, v139, v244, v155
	v_lshlrev_b32_e32 v241, 16, v190
	v_and_b32_e32 v245, 0xffff0000, v190
	v_lshlrev_b32_e32 v243, 16, v198
	v_and_b32_e32 v246, 0xffff0000, v198
	v_cndmask_b32_e32 v243, v243, v210, vcc
	v_cndmask_b32_e32 v246, v246, v211, vcc
	v_sub_f32_e32 v243, v243, v241
	v_sub_f32_e32 v246, v246, v245
	v_fmac_f32_e32 v241, v170, v243
	v_fmac_f32_e32 v245, v171, v246
	v_fmac_f32_e32 v240, v234, v241
	v_fmac_f32_e32 v244, v234, v245
	v_mul_f32_e32 v40, v40, v240
	v_mul_f32_e32 v41, v41, v244
	v_lshlrev_b32_e32 v240, 16, v183
	v_and_b32_e32 v244, 0xffff0000, v183
	v_sub_f32_e32 v240, v240, v238
	v_sub_f32_e32 v244, v244, v238
	v_mul_f32_e32 v240, v240, v239
	v_mul_f32_e32 v244, v244, v239
	v_fma_f32 v240, v140, v240, v156
	v_fma_f32 v244, v141, v244, v157
	v_lshlrev_b32_e32 v241, 16, v191
	v_and_b32_e32 v245, 0xffff0000, v191
	v_lshlrev_b32_e32 v243, 16, v199
	v_and_b32_e32 v246, 0xffff0000, v199
	v_cndmask_b32_e32 v243, v243, v212, vcc
	v_cndmask_b32_e32 v246, v246, v213, vcc
	v_sub_f32_e32 v243, v243, v241
	v_sub_f32_e32 v246, v246, v245
	v_fmac_f32_e32 v241, v172, v243
	v_fmac_f32_e32 v245, v173, v246
	v_fmac_f32_e32 v240, v234, v241
	v_fmac_f32_e32 v244, v234, v245
	v_mul_f32_e32 v42, v42, v240
	v_mul_f32_e32 v43, v43, v244
	v_lshlrev_b32_e32 v240, 16, v184
	v_and_b32_e32 v244, 0xffff0000, v184
	v_sub_f32_e32 v240, v240, v238
	v_sub_f32_e32 v244, v244, v238
	v_mul_f32_e32 v240, v240, v239
	v_mul_f32_e32 v244, v244, v239
	v_fma_f32 v240, v142, v240, v158
	v_fma_f32 v244, v143, v244, v159
	v_lshlrev_b32_e32 v241, 16, v192
	v_and_b32_e32 v245, 0xffff0000, v192
	v_lshlrev_b32_e32 v243, 16, v200
	v_and_b32_e32 v246, 0xffff0000, v200
	v_cndmask_b32_e32 v243, v243, v214, vcc
	v_cndmask_b32_e32 v246, v246, v215, vcc
	v_sub_f32_e32 v243, v243, v241
	v_sub_f32_e32 v246, v246, v245
	v_fmac_f32_e32 v241, v174, v243
	v_fmac_f32_e32 v245, v175, v246
	v_fmac_f32_e32 v240, v234, v241
	v_fmac_f32_e32 v244, v234, v245
	v_mul_f32_e32 v44, v44, v240
	v_mul_f32_e32 v45, v45, v244
	v_lshlrev_b32_e32 v240, 16, v185
	v_and_b32_e32 v244, 0xffff0000, v185
	v_sub_f32_e32 v240, v240, v238
	v_sub_f32_e32 v244, v244, v238
	v_mul_f32_e32 v240, v240, v239
	v_mul_f32_e32 v244, v244, v239
	v_fma_f32 v240, v144, v240, v160
	v_fma_f32 v244, v145, v244, v161
	v_lshlrev_b32_e32 v241, 16, v193
	v_and_b32_e32 v245, 0xffff0000, v193
	v_lshlrev_b32_e32 v243, 16, v201
	v_and_b32_e32 v246, 0xffff0000, v201
	v_cndmask_b32_e32 v243, v243, v216, vcc
	v_cndmask_b32_e32 v246, v246, v217, vcc
	v_sub_f32_e32 v243, v243, v241
	v_sub_f32_e32 v246, v246, v245
	v_fmac_f32_e32 v241, v176, v243
	v_fmac_f32_e32 v245, v177, v246
	v_fmac_f32_e32 v240, v234, v241
	v_fmac_f32_e32 v244, v234, v245
	v_mul_f32_e32 v46, v46, v240
	v_mul_f32_e32 v47, v47, v244
	v_cvt_pk_bf16_f32 v40, v40, v41
	v_cvt_pk_bf16_f32 v41, v42, v43
	v_cvt_pk_bf16_f32 v42, v44, v45
	v_cvt_pk_bf16_f32 v43, v46, v47
	v_add_u32_e32 v236, 0x8000, v230
	s_nop 0
	global_store_dwordx4 v236, v[40:43], s[22:23] offset:64
	v_add_u32_e32 v236, 0x10000, v230
	v_add_u32_e32 v237, 0x2c000, v231
	v_subrev_u32_e32 v240, 0x1600, v237
	global_load_dwordx4 v[178:181], v236, s[22:23] offset:0 sc0
	global_load_dwordx4 v[182:185], v236, s[22:23] offset:64 sc0
	global_load_dwordx4 v[186:189], v237, s[96:97] offset:0 sc0
	global_load_dwordx4 v[190:193], v237, s[96:97] offset:64 sc0
	global_load_dwordx4 v[194:197], v240, s[96:97] offset:0 sc0
	global_load_dwordx4 v[198:201], v240, s[96:97] offset:64 sc0
	v_add_u32_e32 v236, 0x1800, v232
	s_nop 0
	global_load_dword v234, v236, s[96:97] offset:0
	v_add_u32_e32 v237, 0x14000, v247
	global_load_dwordx4 v[202:205], v237, s[20:21] offset:0 sc0
	global_load_dwordx4 v[206:209], v237, s[20:21] offset:16 sc0
	global_load_dwordx4 v[210:213], v237, s[20:21] offset:128 sc0
	global_load_dwordx4 v[214:217], v237, s[20:21] offset:144 sc0
	s_waitcnt vmcnt(0)
; __device__ __forceinline__ float bf2f(u16 h) { return __uint_as_float(((unsigned)h) << 16); }
; __device__ __forceinline__ float prevP(const Params& p, const u16* P, int row, int c) {
;     ...
;   const bool start = (row < NP) ? ((row & 2047) == 0) : (((row - NP) & 3) == 0);
;   if (start) v = (row < NP) ? 0.f : p.in[3][(size_t)((row - NP) >> 2) * 2560 + c];
; template <int EPI> ...
;     ...
;       for (int i = 0; i < 16; i++) {
;         const int rl = rbase + (i & 3) + 8 * (i >> 2);
;         const int row = m0 + rl;
;         float o0 = bf2f(Y[(size_t)row * 1024 + 256 + ch0]);
;         float o1 = bf2f(Y[(size_t)row * 1024 + 256 + ch1]);
;         float mean = hsum32(o0 + o1) * (1.0f / 64.0f);
;         float d0 = o0 - mean, d1 = o1 - mean;
;         float var = hsum32(d0 * d0 + d1 * d1) * (1.0f / 64.0f);
;         float rstd = rsqrtf(var + 64e-5f);
;         float pv0 = bf2f(P[(size_t)row * 2816 + 256 + 1536 + ch0]);
;         float pv1 = bf2f(P[(size_t)row * 2816 + 256 + 1536 + ch1]);
;         float pp0 = prevP(p, P, row, 1536 + ch0), pp1 = prevP(p, P, row, 1536 + ch1);
;         float vv0 = pv0 + (pp0 - pv0) * mu0, vv1 = pv1 + (pp1 - pv1) * mu1;
;         float b = bs[((size_t)row * 12 + hh) * 4 + 2];
;         float y0 = (d0 * rstd * gg0 + gb0 + b * vv0) * acc0[i];
;         float y1 = (d1 * rstd * gg1 + gb1 + b * vv1) * acc1[i];
;         Y[(size_t)row * 1024 + 256 + ch0] = f2bf(y0);
;         Y[(size_t)row * 1024 + 256 + ch1] = f2bf(y1);
	v_lshlrev_b32_e32 v240, 16, v178
	v_and_b32_e32 v241, 0xffff0000, v178
	v_add_f32_e32 v244, v240, v241
	v_lshlrev_b32_e32 v240, 16, v179
	v_and_b32_e32 v241, 0xffff0000, v179
	v_add_f32_e32 v244, v244, v240
	v_add_f32_e32 v244, v244, v241
	v_lshlrev_b32_e32 v240, 16, v180
	v_and_b32_e32 v241, 0xffff0000, v180
	v_add_f32_e32 v244, v244, v240
	v_add_f32_e32 v244, v244, v241
	v_lshlrev_b32_e32 v240, 16, v181
	v_and_b32_e32 v241, 0xffff0000, v181
	v_add_f32_e32 v244, v244, v240
	v_add_f32_e32 v244, v244, v241
	v_lshlrev_b32_e32 v240, 16, v182
	v_and_b32_e32 v241, 0xffff0000, v182
	v_add_f32_e32 v244, v244, v240
	v_add_f32_e32 v244, v244, v241
	v_lshlrev_b32_e32 v240, 16, v183
	v_and_b32_e32 v241, 0xffff0000, v183
	v_add_f32_e32 v244, v244, v240
	v_add_f32_e32 v244, v244, v241
	v_lshlrev_b32_e32 v240, 16, v184
	v_and_b32_e32 v241, 0xffff0000, v184
	v_add_f32_e32 v244, v244, v240
	v_add_f32_e32 v244, v244, v241
	v_lshlrev_b32_e32 v240, 16, v185
	v_and_b32_e32 v241, 0xffff0000, v185
	v_add_f32_e32 v244, v244, v240
	v_add_f32_e32 v244, v244, v241
	v_mov_b32_e32 v240, v244
	s_nop 1
	v_permlane16_swap_b32_e32 v240, v244
	v_add_f32_e32 v244, v244, v240
	v_mov_b32_e32 v240, v244
	s_nop 1
	v_permlane32_swap_b32_e32 v240, v244
	v_add_f32_e32 v244, v244, v240
	v_mul_f32_e32 v238, 0x3c800000, v244
	v_lshlrev_b32_e32 v240, 16, v178
	v_and_b32_e32 v241, 0xffff0000, v178
	v_sub_f32_e32 v240, v240, v238
	v_sub_f32_e32 v241, v241, v238
	v_mul_f32_e32 v245, v240, v240
	v_fmac_f32_e32 v245, v241, v241
	v_lshlrev_b32_e32 v240, 16, v179
	v_and_b32_e32 v241, 0xffff0000, v179
	v_sub_f32_e32 v240, v240, v238
	v_sub_f32_e32 v241, v241, v238
	v_fmac_f32_e32 v245, v240, v240
	v_fmac_f32_e32 v245, v241, v241
	v_lshlrev_b32_e32 v240, 16, v180
	v_and_b32_e32 v241, 0xffff0000, v180
	v_sub_f32_e32 v240, v240, v238
	v_sub_f32_e32 v241, v241, v238
	v_fmac_f32_e32 v245, v240, v240
	v_fmac_f32_e32 v245, v241, v241
	v_lshlrev_b32_e32 v240, 16, v181
	v_and_b32_e32 v241, 0xffff0000, v181
	v_sub_f32_e32 v240, v240, v238
	v_sub_f32_e32 v241, v241, v238
	v_fmac_f32_e32 v245, v240, v240
	v_fmac_f32_e32 v245, v241, v241
	v_lshlrev_b32_e32 v240, 16, v182
	v_and_b32_e32 v241, 0xffff0000, v182
	v_sub_f32_e32 v240, v240, v238
	v_sub_f32_e32 v241, v241, v238
	v_fmac_f32_e32 v245, v240, v240
	v_fmac_f32_e32 v245, v241, v241
	v_lshlrev_b32_e32 v240, 16, v183
	v_and_b32_e32 v241, 0xffff0000, v183
	v_sub_f32_e32 v240, v240, v238
	v_sub_f32_e32 v241, v241, v238
	v_fmac_f32_e32 v245, v240, v240
	v_fmac_f32_e32 v245, v241, v241
	v_lshlrev_b32_e32 v240, 16, v184
	v_and_b32_e32 v241, 0xffff0000, v184
	v_sub_f32_e32 v240, v240, v238
	v_sub_f32_e32 v241, v241, v238
	v_fmac_f32_e32 v245, v240, v240
	v_fmac_f32_e32 v245, v241, v241
	v_lshlrev_b32_e32 v240, 16, v185
	v_and_b32_e32 v241, 0xffff0000, v185
	v_sub_f32_e32 v240, v240, v238
	v_sub_f32_e32 v241, v241, v238
	v_fmac_f32_e32 v245, v240, v240
	v_fmac_f32_e32 v245, v241, v241
	v_mov_b32_e32 v240, v245
	s_nop 1
	v_permlane16_swap_b32_e32 v240, v245
	v_add_f32_e32 v245, v245, v240
	v_mov_b32_e32 v240, v245
	s_nop 1
	v_permlane32_swap_b32_e32 v240, v245
	v_add_f32_e32 v245, v245, v240
	v_mov_b32_e32 v240, 0x3a27c5ac
	v_fmamk_f32 v245, v245, 0x3c800000, v240
	v_rsq_f32_e32 v239, v245
	v_and_b32_e32 v240, 3, v248
	v_cmp_eq_u32_e32 vcc, 0, v240
	s_nop 1
	v_lshlrev_b32_e32 v240, 16, v178
	v_and_b32_e32 v244, 0xffff0000, v178
	v_sub_f32_e32 v240, v240, v238
	v_sub_f32_e32 v244, v244, v238
	v_mul_f32_e32 v240, v240, v239
	v_mul_f32_e32 v244, v244, v239
	v_fma_f32 v240, v130, v240, v146
	v_fma_f32 v244, v131, v244, v147
	v_lshlrev_b32_e32 v241, 16, v186
	v_and_b32_e32 v245, 0xffff0000, v186
	v_lshlrev_b32_e32 v243, 16, v194
	v_and_b32_e32 v246, 0xffff0000, v194
	v_cndmask_b32_e32 v243, v243, v202, vcc
	v_cndmask_b32_e32 v246, v246, v203, vcc
	v_sub_f32_e32 v243, v243, v241
	v_sub_f32_e32 v246, v246, v245
	v_fmac_f32_e32 v241, v162, v243
	v_fmac_f32_e32 v245, v163, v246
	v_fmac_f32_e32 v240, v234, v241
	v_fmac_f32_e32 v244, v234, v245
	v_mul_f32_e32 v64, v64, v240
	v_mul_f32_e32 v65, v65, v244
	v_lshlrev_b32_e32 v240, 16, v179
	v_and_b32_e32 v244, 0xffff0000, v179
	v_sub_f32_e32 v240, v240, v238
	v_sub_f32_e32 v244, v244, v238
	v_mul_f32_e32 v240, v240, v239
	v_mul_f32_e32 v244, v244, v239
	v_fma_f32 v240, v132, v240, v148
	v_fma_f32 v244, v133, v244, v149
	v_lshlrev_b32_e32 v241, 16, v187
	v_and_b32_e32 v245, 0xffff0000, v187
	v_lshlrev_b32_e32 v243, 16, v195
	v_and_b32_e32 v246, 0xffff0000, v195
	v_cndmask_b32_e32 v243, v243, v204, vcc
	v_cndmask_b32_e32 v246, v246, v205, vcc
	v_sub_f32_e32 v243, v243, v241
	v_sub_f32_e32 v246, v246, v245
	v_fmac_f32_e32 v241, v164, v243
	v_fmac_f32_e32 v245, v165, v246
	v_fmac_f32_e32 v240, v234, v241
	v_fmac_f32_e32 v244, v234, v245
	v_mul_f32_e32 v66, v66, v240
	v_mul_f32_e32 v67, v67, v244
	v_lshlrev_b32_e32 v240, 16, v180
	v_and_b32_e32 v244, 0xffff0000, v180
	v_sub_f32_e32 v240, v240, v238
	v_sub_f32_e32 v244, v244, v238
	v_mul_f32_e32 v240, v240, v239
	v_mul_f32_e32 v244, v244, v239
	v_fma_f32 v240, v134, v240, v150
	v_fma_f32 v244, v135, v244, v151
	v_lshlrev_b32_e32 v241, 16, v188
	v_and_b32_e32 v245, 0xffff0000, v188
	v_lshlrev_b32_e32 v243, 16, v196
	v_and_b32_e32 v246, 0xffff0000, v196
	v_cndmask_b32_e32 v243, v243, v206, vcc
	v_cndmask_b32_e32 v246, v246, v207, vcc
	v_sub_f32_e32 v243, v243, v241
	v_sub_f32_e32 v246, v246, v245
	v_fmac_f32_e32 v241, v166, v243
	v_fmac_f32_e32 v245, v167, v246
	v_fmac_f32_e32 v240, v234, v241
	v_fmac_f32_e32 v244, v234, v245
	v_mul_f32_e32 v68, v68, v240
	v_mul_f32_e32 v69, v69, v244
	v_lshlrev_b32_e32 v240, 16, v181
	v_and_b32_e32 v244, 0xffff0000, v181
	v_sub_f32_e32 v240, v240, v238
; __device__ __forceinline__ float bf2f(u16 h) { return __uint_as_float(((unsigned)h) << 16); }
; __device__ __forceinline__ float prevP(const Params& p, const u16* P, int row, int c) {
;     ...
;   const bool start = (row < NP) ? ((row & 2047) == 0) : (((row - NP) & 3) == 0);
;   if (start) v = (row < NP) ? 0.f : p.in[3][(size_t)((row - NP) >> 2) * 2560 + c];
; template <int EPI> ...
;     ...
;       for (int i = 0; i < 16; i++) {
;         const int rl = rbase + (i & 3) + 8 * (i >> 2);
;         const int row = m0 + rl;
;         float o0 = bf2f(Y[(size_t)row * 1024 + 256 + ch0]);
;         float o1 = bf2f(Y[(size_t)row * 1024 + 256 + ch1]);
;         float mean = hsum32(o0 + o1) * (1.0f / 64.0f);
;         float d0 = o0 - mean, d1 = o1 - mean;
;         float var = hsum32(d0 * d0 + d1 * d1) * (1.0f / 64.0f);
;         float rstd = rsqrtf(var + 64e-5f);
;         float pv0 = bf2f(P[(size_t)row * 2816 + 256 + 1536 + ch0]);
;         float pv1 = bf2f(P[(size_t)row * 2816 + 256 + 1536 + ch1]);
;         float pp0 = prevP(p, P, row, 1536 + ch0), pp1 = prevP(p, P, row, 1536 + ch1);
;         float vv0 = pv0 + (pp0 - pv0) * mu0, vv1 = pv1 + (pp1 - pv1) * mu1;
;         float b = bs[((size_t)row * 12 + hh) * 4 + 2];
;         float y0 = (d0 * rstd * gg0 + gb0 + b * vv0) * acc0[i];
;         float y1 = (d1 * rstd * gg1 + gb1 + b * vv1) * acc1[i];
;         Y[(size_t)row * 1024 + 256 + ch0] = f2bf(y0);
;         Y[(size_t)row * 1024 + 256 + ch1] = f2bf(y1);
	v_sub_f32_e32 v244, v244, v238
	v_mul_f32_e32 v240, v240, v239
	v_mul_f32_e32 v244, v244, v239
	v_fma_f32 v240, v136, v240, v152
	v_fma_f32 v244, v137, v244, v153
	v_lshlrev_b32_e32 v241, 16, v189
	v_and_b32_e32 v245, 0xffff0000, v189
	v_lshlrev_b32_e32 v243, 16, v197
	v_and_b32_e32 v246, 0xffff0000, v197
	v_cndmask_b32_e32 v243, v243, v208, vcc
	v_cndmask_b32_e32 v246, v246, v209, vcc
	v_sub_f32_e32 v243, v243, v241
	v_sub_f32_e32 v246, v246, v245
	v_fmac_f32_e32 v241, v168, v243
	v_fmac_f32_e32 v245, v169, v246
	v_fmac_f32_e32 v240, v234, v241
	v_fmac_f32_e32 v244, v234, v245
	v_mul_f32_e32 v70, v70, v240
	v_mul_f32_e32 v71, v71, v244
	v_cvt_pk_bf16_f32 v64, v64, v65
	v_cvt_pk_bf16_f32 v65, v66, v67
	v_cvt_pk_bf16_f32 v66, v68, v69
	v_cvt_pk_bf16_f32 v67, v70, v71
	v_add_u32_e32 v236, 0x10000, v230
	s_nop 0
	global_store_dwordx4 v236, v[64:67], s[22:23] offset:0
	v_lshlrev_b32_e32 v240, 16, v182
	v_and_b32_e32 v244, 0xffff0000, v182
	v_sub_f32_e32 v240, v240, v238
	v_sub_f32_e32 v244, v244, v238
	v_mul_f32_e32 v240, v240, v239
	v_mul_f32_e32 v244, v244, v239
	v_fma_f32 v240, v138, v240, v154
	v_fma_f32 v244, v139, v244, v155
	v_lshlrev_b32_e32 v241, 16, v190
	v_and_b32_e32 v245, 0xffff0000, v190
	v_lshlrev_b32_e32 v243, 16, v198
	v_and_b32_e32 v246, 0xffff0000, v198
	v_cndmask_b32_e32 v243, v243, v210, vcc
	v_cndmask_b32_e32 v246, v246, v211, vcc
	v_sub_f32_e32 v243, v243, v241
	v_sub_f32_e32 v246, v246, v245
	v_fmac_f32_e32 v241, v170, v243
	v_fmac_f32_e32 v245, v171, v246
	v_fmac_f32_e32 v240, v234, v241
	v_fmac_f32_e32 v244, v234, v245
	v_mul_f32_e32 v72, v72, v240
	v_mul_f32_e32 v73, v73, v244
	v_lshlrev_b32_e32 v240, 16, v183
	v_and_b32_e32 v244, 0xffff0000, v183
	v_sub_f32_e32 v240, v240, v238
	v_sub_f32_e32 v244, v244, v238
	v_mul_f32_e32 v240, v240, v239
	v_mul_f32_e32 v244, v244, v239
	v_fma_f32 v240, v140, v240, v156
	v_fma_f32 v244, v141, v244, v157
	v_lshlrev_b32_e32 v241, 16, v191
	v_and_b32_e32 v245, 0xffff0000, v191
	v_lshlrev_b32_e32 v243, 16, v199
	v_and_b32_e32 v246, 0xffff0000, v199
	v_cndmask_b32_e32 v243, v243, v212, vcc
	v_cndmask_b32_e32 v246, v246, v213, vcc
	v_sub_f32_e32 v243, v243, v241
	v_sub_f32_e32 v246, v246, v245
	v_fmac_f32_e32 v241, v172, v243
	v_fmac_f32_e32 v245, v173, v246
	v_fmac_f32_e32 v240, v234, v241
	v_fmac_f32_e32 v244, v234, v245
	v_mul_f32_e32 v74, v74, v240
	v_mul_f32_e32 v75, v75, v244
	v_lshlrev_b32_e32 v240, 16, v184
	v_and_b32_e32 v244, 0xffff0000, v184
	v_sub_f32_e32 v240, v240, v238
	v_sub_f32_e32 v244, v244, v238
	v_mul_f32_e32 v240, v240, v239
	v_mul_f32_e32 v244, v244, v239
	v_fma_f32 v240, v142, v240, v158
	v_fma_f32 v244, v143, v244, v159
	v_lshlrev_b32_e32 v241, 16, v192
	v_and_b32_e32 v245, 0xffff0000, v192
	v_lshlrev_b32_e32 v243, 16, v200
	v_and_b32_e32 v246, 0xffff0000, v200
	v_cndmask_b32_e32 v243, v243, v214, vcc
	v_cndmask_b32_e32 v246, v246, v215, vcc
	v_sub_f32_e32 v243, v243, v241
	v_sub_f32_e32 v246, v246, v245
	v_fmac_f32_e32 v241, v174, v243
	v_fmac_f32_e32 v245, v175, v246
	v_fmac_f32_e32 v240, v234, v241
	v_fmac_f32_e32 v244, v234, v245
	v_mul_f32_e32 v76, v76, v240
	v_mul_f32_e32 v77, v77, v244
	v_lshlrev_b32_e32 v240, 16, v185
	v_and_b32_e32 v244, 0xffff0000, v185
	v_sub_f32_e32 v240, v240, v238
	v_sub_f32_e32 v244, v244, v238
	v_mul_f32_e32 v240, v240, v239
	v_mul_f32_e32 v244, v244, v239
	v_fma_f32 v240, v144, v240, v160
	v_fma_f32 v244, v145, v244, v161
	v_lshlrev_b32_e32 v241, 16, v193
	v_and_b32_e32 v245, 0xffff0000, v193
	v_lshlrev_b32_e32 v243, 16, v201
	v_and_b32_e32 v246, 0xffff0000, v201
	v_cndmask_b32_e32 v243, v243, v216, vcc
	v_cndmask_b32_e32 v246, v246, v217, vcc
	v_sub_f32_e32 v243, v243, v241
	v_sub_f32_e32 v246, v246, v245
	v_fmac_f32_e32 v241, v176, v243
	v_fmac_f32_e32 v245, v177, v246
	v_fmac_f32_e32 v240, v234, v241
	v_fmac_f32_e32 v244, v234, v245
	v_mul_f32_e32 v78, v78, v240
	v_mul_f32_e32 v79, v79, v244
	v_cvt_pk_bf16_f32 v72, v72, v73
	v_cvt_pk_bf16_f32 v73, v74, v75
	v_cvt_pk_bf16_f32 v74, v76, v77
	v_cvt_pk_bf16_f32 v75, v78, v79
	v_add_u32_e32 v236, 0x10000, v230
	s_nop 0
	global_store_dwordx4 v236, v[72:75], s[22:23] offset:64
	v_add_u32_e32 v236, 0x18000, v230
	v_add_u32_e32 v237, 0x42000, v231
	v_subrev_u32_e32 v240, 0x1600, v237
	global_load_dwordx4 v[178:181], v236, s[22:23] offset:0 sc0
	global_load_dwordx4 v[182:185], v236, s[22:23] offset:64 sc0
	global_load_dwordx4 v[186:189], v237, s[96:97] offset:0 sc0
	global_load_dwordx4 v[190:193], v237, s[96:97] offset:64 sc0
	global_load_dwordx4 v[194:197], v240, s[96:97] offset:0 sc0
	global_load_dwordx4 v[198:201], v240, s[96:97] offset:64 sc0
	v_add_u32_e32 v236, 0x2400, v232
	s_nop 0
	global_load_dword v234, v236, s[96:97] offset:0
	v_add_u32_e32 v237, 0x1e000, v247
	global_load_dwordx4 v[202:205], v237, s[20:21] offset:0 sc0
	global_load_dwordx4 v[206:209], v237, s[20:21] offset:16 sc0
	global_load_dwordx4 v[210:213], v237, s[20:21] offset:128 sc0
	global_load_dwordx4 v[214:217], v237, s[20:21] offset:144 sc0
	s_waitcnt vmcnt(0)
; __device__ __forceinline__ float bf2f(u16 h) { return __uint_as_float(((unsigned)h) << 16); }
; __device__ __forceinline__ float prevP(const Params& p, const u16* P, int row, int c) {
;     ...
;   const bool start = (row < NP) ? ((row & 2047) == 0) : (((row - NP) & 3) == 0);
;   if (start) v = (row < NP) ? 0.f : p.in[3][(size_t)((row - NP) >> 2) * 2560 + c];
; template <int EPI> ...
;     ...
;       for (int i = 0; i < 16; i++) {
;         const int rl = rbase + (i & 3) + 8 * (i >> 2);
;         const int row = m0 + rl;
;         float o0 = bf2f(Y[(size_t)row * 1024 + 256 + ch0]);
;         float o1 = bf2f(Y[(size_t)row * 1024 + 256 + ch1]);
;         float mean = hsum32(o0 + o1) * (1.0f / 64.0f);
;         float d0 = o0 - mean, d1 = o1 - mean;
;         float var = hsum32(d0 * d0 + d1 * d1) * (1.0f / 64.0f);
;         float rstd = rsqrtf(var + 64e-5f);
;         float pv0 = bf2f(P[(size_t)row * 2816 + 256 + 1536 + ch0]);
;         float pv1 = bf2f(P[(size_t)row * 2816 + 256 + 1536 + ch1]);
;         float pp0 = prevP(p, P, row, 1536 + ch0), pp1 = prevP(p, P, row, 1536 + ch1);
;         float vv0 = pv0 + (pp0 - pv0) * mu0, vv1 = pv1 + (pp1 - pv1) * mu1;
;         float b = bs[((size_t)row * 12 + hh) * 4 + 2];
;         float y0 = (d0 * rstd * gg0 + gb0 + b * vv0) * acc0[i];
;         float y1 = (d1 * rstd * gg1 + gb1 + b * vv1) * acc1[i];
;         Y[(size_t)row * 1024 + 256 + ch0] = f2bf(y0);
;         Y[(size_t)row * 1024 + 256 + ch1] = f2bf(y1);
	v_lshlrev_b32_e32 v240, 16, v178
	v_and_b32_e32 v241, 0xffff0000, v178
	v_add_f32_e32 v244, v240, v241
	v_lshlrev_b32_e32 v240, 16, v179
	v_and_b32_e32 v241, 0xffff0000, v179
	v_add_f32_e32 v244, v244, v240
	v_add_f32_e32 v244, v244, v241
	v_lshlrev_b32_e32 v240, 16, v180
	v_and_b32_e32 v241, 0xffff0000, v180
	v_add_f32_e32 v244, v244, v240
	v_add_f32_e32 v244, v244, v241
	v_lshlrev_b32_e32 v240, 16, v181
	v_and_b32_e32 v241, 0xffff0000, v181
	v_add_f32_e32 v244, v244, v240
	v_add_f32_e32 v244, v244, v241
	v_lshlrev_b32_e32 v240, 16, v182
	v_and_b32_e32 v241, 0xffff0000, v182
	v_add_f32_e32 v244, v244, v240
	v_add_f32_e32 v244, v244, v241
	v_lshlrev_b32_e32 v240, 16, v183
	v_and_b32_e32 v241, 0xffff0000, v183
	v_add_f32_e32 v244, v244, v240
	v_add_f32_e32 v244, v244, v241
	v_lshlrev_b32_e32 v240, 16, v184
	v_and_b32_e32 v241, 0xffff0000, v184
	v_add_f32_e32 v244, v244, v240
	v_add_f32_e32 v244, v244, v241
	v_lshlrev_b32_e32 v240, 16, v185
	v_and_b32_e32 v241, 0xffff0000, v185
	v_add_f32_e32 v244, v244, v240
	v_add_f32_e32 v244, v244, v241
	v_mov_b32_e32 v240, v244
	s_nop 1
	v_permlane16_swap_b32_e32 v240, v244
	v_add_f32_e32 v244, v244, v240
	v_mov_b32_e32 v240, v244
	s_nop 1
	v_permlane32_swap_b32_e32 v240, v244
	v_add_f32_e32 v244, v244, v240
	v_mul_f32_e32 v238, 0x3c800000, v244
	v_lshlrev_b32_e32 v240, 16, v178
	v_and_b32_e32 v241, 0xffff0000, v178
	v_sub_f32_e32 v240, v240, v238
	v_sub_f32_e32 v241, v241, v238
	v_mul_f32_e32 v245, v240, v240
	v_fmac_f32_e32 v245, v241, v241
	v_lshlrev_b32_e32 v240, 16, v179
	v_and_b32_e32 v241, 0xffff0000, v179
	v_sub_f32_e32 v240, v240, v238
	v_sub_f32_e32 v241, v241, v238
	v_fmac_f32_e32 v245, v240, v240
	v_fmac_f32_e32 v245, v241, v241
	v_lshlrev_b32_e32 v240, 16, v180
	v_and_b32_e32 v241, 0xffff0000, v180
	v_sub_f32_e32 v240, v240, v238
	v_sub_f32_e32 v241, v241, v238
	v_fmac_f32_e32 v245, v240, v240
	v_fmac_f32_e32 v245, v241, v241
	v_lshlrev_b32_e32 v240, 16, v181
	v_and_b32_e32 v241, 0xffff0000, v181
	v_sub_f32_e32 v240, v240, v238
	v_sub_f32_e32 v241, v241, v238
	v_fmac_f32_e32 v245, v240, v240
	v_fmac_f32_e32 v245, v241, v241
	v_lshlrev_b32_e32 v240, 16, v182
	v_and_b32_e32 v241, 0xffff0000, v182
	v_sub_f32_e32 v240, v240, v238
	v_sub_f32_e32 v241, v241, v238
	v_fmac_f32_e32 v245, v240, v240
	v_fmac_f32_e32 v245, v241, v241
	v_lshlrev_b32_e32 v240, 16, v183
	v_and_b32_e32 v241, 0xffff0000, v183
	v_sub_f32_e32 v240, v240, v238
	v_sub_f32_e32 v241, v241, v238
	v_fmac_f32_e32 v245, v240, v240
	v_fmac_f32_e32 v245, v241, v241
	v_lshlrev_b32_e32 v240, 16, v184
	v_and_b32_e32 v241, 0xffff0000, v184
	v_sub_f32_e32 v240, v240, v238
	v_sub_f32_e32 v241, v241, v238
	v_fmac_f32_e32 v245, v240, v240
	v_fmac_f32_e32 v245, v241, v241
	v_lshlrev_b32_e32 v240, 16, v185
	v_and_b32_e32 v241, 0xffff0000, v185
	v_sub_f32_e32 v240, v240, v238
	v_sub_f32_e32 v241, v241, v238
	v_fmac_f32_e32 v245, v240, v240
	v_fmac_f32_e32 v245, v241, v241
	v_mov_b32_e32 v240, v245
	s_nop 1
	v_permlane16_swap_b32_e32 v240, v245
	v_add_f32_e32 v245, v245, v240
	v_mov_b32_e32 v240, v245
	s_nop 1
	v_permlane32_swap_b32_e32 v240, v245
	v_add_f32_e32 v245, v245, v240
	v_mov_b32_e32 v240, 0x3a27c5ac
	v_fmamk_f32 v245, v245, 0x3c800000, v240
	v_rsq_f32_e32 v239, v245
	v_and_b32_e32 v240, 3, v248
	v_cmp_eq_u32_e32 vcc, 0, v240
	s_nop 1
	v_lshlrev_b32_e32 v240, 16, v178
	v_and_b32_e32 v244, 0xffff0000, v178
	v_sub_f32_e32 v240, v240, v238
	v_sub_f32_e32 v244, v244, v238
	v_mul_f32_e32 v240, v240, v239
	v_mul_f32_e32 v244, v244, v239
	v_fma_f32 v240, v130, v240, v146
	v_fma_f32 v244, v131, v244, v147
	v_lshlrev_b32_e32 v241, 16, v186
	v_and_b32_e32 v245, 0xffff0000, v186
	v_lshlrev_b32_e32 v243, 16, v194
	v_and_b32_e32 v246, 0xffff0000, v194
	v_cndmask_b32_e32 v243, v243, v202, vcc
	v_cndmask_b32_e32 v246, v246, v203, vcc
	v_sub_f32_e32 v243, v243, v241
	v_sub_f32_e32 v246, v246, v245
	v_fmac_f32_e32 v241, v162, v243
	v_fmac_f32_e32 v245, v163, v246
	v_fmac_f32_e32 v240, v234, v241
	v_fmac_f32_e32 v244, v234, v245
	v_mul_f32_e32 v96, v96, v240
	v_mul_f32_e32 v97, v97, v244
	v_lshlrev_b32_e32 v240, 16, v179
	v_and_b32_e32 v244, 0xffff0000, v179
	v_sub_f32_e32 v240, v240, v238
	v_sub_f32_e32 v244, v244, v238
	v_mul_f32_e32 v240, v240, v239
	v_mul_f32_e32 v244, v244, v239
	v_fma_f32 v240, v132, v240, v148
	v_fma_f32 v244, v133, v244, v149
	v_lshlrev_b32_e32 v241, 16, v187
	v_and_b32_e32 v245, 0xffff0000, v187
	v_lshlrev_b32_e32 v243, 16, v195
	v_and_b32_e32 v246, 0xffff0000, v195
	v_cndmask_b32_e32 v243, v243, v204, vcc
	v_cndmask_b32_e32 v246, v246, v205, vcc
	v_sub_f32_e32 v243, v243, v241
	v_sub_f32_e32 v246, v246, v245
	v_fmac_f32_e32 v241, v164, v243
	v_fmac_f32_e32 v245, v165, v246
	v_fmac_f32_e32 v240, v234, v241
	v_fmac_f32_e32 v244, v234, v245
	v_mul_f32_e32 v98, v98, v240
	v_mul_f32_e32 v99, v99, v244
	v_lshlrev_b32_e32 v240, 16, v180
	v_and_b32_e32 v244, 0xffff0000, v180
	v_sub_f32_e32 v240, v240, v238
	v_sub_f32_e32 v244, v244, v238
	v_mul_f32_e32 v240, v240, v239
	v_mul_f32_e32 v244, v244, v239
	v_fma_f32 v240, v134, v240, v150
	v_fma_f32 v244, v135, v244, v151
	v_lshlrev_b32_e32 v241, 16, v188
	v_and_b32_e32 v245, 0xffff0000, v188
	v_lshlrev_b32_e32 v243, 16, v196
	v_and_b32_e32 v246, 0xffff0000, v196
	v_cndmask_b32_e32 v243, v243, v206, vcc
	v_cndmask_b32_e32 v246, v246, v207, vcc
	v_sub_f32_e32 v243, v243, v241
	v_sub_f32_e32 v246, v246, v245
	v_fmac_f32_e32 v241, v166, v243
	v_fmac_f32_e32 v245, v167, v246
	v_fmac_f32_e32 v240, v234, v241
	v_fmac_f32_e32 v244, v234, v245
	v_mul_f32_e32 v100, v100, v240
	v_mul_f32_e32 v101, v101, v244
	v_lshlrev_b32_e32 v240, 16, v181
	v_and_b32_e32 v244, 0xffff0000, v181
; __device__ __forceinline__ float bf2f(u16 h) { return __uint_as_float(((unsigned)h) << 16); }
; __device__ __forceinline__ float prevP(const Params& p, const u16* P, int row, int c) {
;     ...
;   const bool start = (row < NP) ? ((row & 2047) == 0) : (((row - NP) & 3) == 0);
;   if (start) v = (row < NP) ? 0.f : p.in[3][(size_t)((row - NP) >> 2) * 2560 + c];
; template <int EPI> ...
;     ...
;       for (int i = 0; i < 16; i++) {
;         const int rl = rbase + (i & 3) + 8 * (i >> 2);
;         const int row = m0 + rl;
;         float o0 = bf2f(Y[(size_t)row * 1024 + 256 + ch0]);
;         float o1 = bf2f(Y[(size_t)row * 1024 + 256 + ch1]);
;         float mean = hsum32(o0 + o1) * (1.0f / 64.0f);
;         float d0 = o0 - mean, d1 = o1 - mean;
;         float var = hsum32(d0 * d0 + d1 * d1) * (1.0f / 64.0f);
;         float rstd = rsqrtf(var + 64e-5f);
;         float pv0 = bf2f(P[(size_t)row * 2816 + 256 + 1536 + ch0]);
;         float pv1 = bf2f(P[(size_t)row * 2816 + 256 + 1536 + ch1]);
;         float pp0 = prevP(p, P, row, 1536 + ch0), pp1 = prevP(p, P, row, 1536 + ch1);
;         float vv0 = pv0 + (pp0 - pv0) * mu0, vv1 = pv1 + (pp1 - pv1) * mu1;
;         float b = bs[((size_t)row * 12 + hh) * 4 + 2];
;         float y0 = (d0 * rstd * gg0 + gb0 + b * vv0) * acc0[i];
;         float y1 = (d1 * rstd * gg1 + gb1 + b * vv1) * acc1[i];
;         Y[(size_t)row * 1024 + 256 + ch0] = f2bf(y0);
;         Y[(size_t)row * 1024 + 256 + ch1] = f2bf(y1);
	v_sub_f32_e32 v240, v240, v238
	v_sub_f32_e32 v244, v244, v238
	v_mul_f32_e32 v240, v240, v239
	v_mul_f32_e32 v244, v244, v239
	v_fma_f32 v240, v136, v240, v152
	v_fma_f32 v244, v137, v244, v153
	v_lshlrev_b32_e32 v241, 16, v189
	v_and_b32_e32 v245, 0xffff0000, v189
	v_lshlrev_b32_e32 v243, 16, v197
	v_and_b32_e32 v246, 0xffff0000, v197
	v_cndmask_b32_e32 v243, v243, v208, vcc
	v_cndmask_b32_e32 v246, v246, v209, vcc
	v_sub_f32_e32 v243, v243, v241
	v_sub_f32_e32 v246, v246, v245
	v_fmac_f32_e32 v241, v168, v243
	v_fmac_f32_e32 v245, v169, v246
	v_fmac_f32_e32 v240, v234, v241
	v_fmac_f32_e32 v244, v234, v245
	v_mul_f32_e32 v102, v102, v240
	v_mul_f32_e32 v103, v103, v244
	v_cvt_pk_bf16_f32 v96, v96, v97
	v_cvt_pk_bf16_f32 v97, v98, v99
	v_cvt_pk_bf16_f32 v98, v100, v101
	v_cvt_pk_bf16_f32 v99, v102, v103
	v_add_u32_e32 v236, 0x18000, v230
	s_nop 0
	global_store_dwordx4 v236, v[96:99], s[22:23] offset:0
	v_lshlrev_b32_e32 v240, 16, v182
	v_and_b32_e32 v244, 0xffff0000, v182
	v_sub_f32_e32 v240, v240, v238
	v_sub_f32_e32 v244, v244, v238
	v_mul_f32_e32 v240, v240, v239
	v_mul_f32_e32 v244, v244, v239
	v_fma_f32 v240, v138, v240, v154
	v_fma_f32 v244, v139, v244, v155
	v_lshlrev_b32_e32 v241, 16, v190
	v_and_b32_e32 v245, 0xffff0000, v190
	v_lshlrev_b32_e32 v243, 16, v198
	v_and_b32_e32 v246, 0xffff0000, v198
	v_cndmask_b32_e32 v243, v243, v210, vcc
	v_cndmask_b32_e32 v246, v246, v211, vcc
	v_sub_f32_e32 v243, v243, v241
	v_sub_f32_e32 v246, v246, v245
	v_fmac_f32_e32 v241, v170, v243
	v_fmac_f32_e32 v245, v171, v246
	v_fmac_f32_e32 v240, v234, v241
	v_fmac_f32_e32 v244, v234, v245
	v_mul_f32_e32 v104, v104, v240
	v_mul_f32_e32 v105, v105, v244
	v_lshlrev_b32_e32 v240, 16, v183
	v_and_b32_e32 v244, 0xffff0000, v183
	v_sub_f32_e32 v240, v240, v238
	v_sub_f32_e32 v244, v244, v238
	v_mul_f32_e32 v240, v240, v239
	v_mul_f32_e32 v244, v244, v239
	v_fma_f32 v240, v140, v240, v156
	v_fma_f32 v244, v141, v244, v157
	v_lshlrev_b32_e32 v241, 16, v191
	v_and_b32_e32 v245, 0xffff0000, v191
	v_lshlrev_b32_e32 v243, 16, v199
	v_and_b32_e32 v246, 0xffff0000, v199
	v_cndmask_b32_e32 v243, v243, v212, vcc
	v_cndmask_b32_e32 v246, v246, v213, vcc
	v_sub_f32_e32 v243, v243, v241
	v_sub_f32_e32 v246, v246, v245
	v_fmac_f32_e32 v241, v172, v243
	v_fmac_f32_e32 v245, v173, v246
	v_fmac_f32_e32 v240, v234, v241
	v_fmac_f32_e32 v244, v234, v245
	v_mul_f32_e32 v106, v106, v240
	v_mul_f32_e32 v107, v107, v244
	v_lshlrev_b32_e32 v240, 16, v184
	v_and_b32_e32 v244, 0xffff0000, v184
	v_sub_f32_e32 v240, v240, v238
	v_sub_f32_e32 v244, v244, v238
	v_mul_f32_e32 v240, v240, v239
	v_mul_f32_e32 v244, v244, v239
	v_fma_f32 v240, v142, v240, v158
	v_fma_f32 v244, v143, v244, v159
	v_lshlrev_b32_e32 v241, 16, v192
	v_and_b32_e32 v245, 0xffff0000, v192
	v_lshlrev_b32_e32 v243, 16, v200
	v_and_b32_e32 v246, 0xffff0000, v200
	v_cndmask_b32_e32 v243, v243, v214, vcc
	v_cndmask_b32_e32 v246, v246, v215, vcc
	v_sub_f32_e32 v243, v243, v241
	v_sub_f32_e32 v246, v246, v245
	v_fmac_f32_e32 v241, v174, v243
	v_fmac_f32_e32 v245, v175, v246
	v_fmac_f32_e32 v240, v234, v241
	v_fmac_f32_e32 v244, v234, v245
	v_mul_f32_e32 v108, v108, v240
	v_mul_f32_e32 v109, v109, v244
	v_lshlrev_b32_e32 v240, 16, v185
	v_and_b32_e32 v244, 0xffff0000, v185
	v_sub_f32_e32 v240, v240, v238
	v_sub_f32_e32 v244, v244, v238
	v_mul_f32_e32 v240, v240, v239
	v_mul_f32_e32 v244, v244, v239
	v_fma_f32 v240, v144, v240, v160
	v_fma_f32 v244, v145, v244, v161
	v_lshlrev_b32_e32 v241, 16, v193
	v_and_b32_e32 v245, 0xffff0000, v193
	v_lshlrev_b32_e32 v243, 16, v201
	v_and_b32_e32 v246, 0xffff0000, v201
	v_cndmask_b32_e32 v243, v243, v216, vcc
	v_cndmask_b32_e32 v246, v246, v217, vcc
	v_sub_f32_e32 v243, v243, v241
	v_sub_f32_e32 v246, v246, v245
	v_fmac_f32_e32 v241, v176, v243
	v_fmac_f32_e32 v245, v177, v246
	v_fmac_f32_e32 v240, v234, v241
	v_fmac_f32_e32 v244, v234, v245
	v_mul_f32_e32 v110, v110, v240
	v_mul_f32_e32 v111, v111, v244
	v_cvt_pk_bf16_f32 v104, v104, v105
	v_cvt_pk_bf16_f32 v105, v106, v107
	v_cvt_pk_bf16_f32 v106, v108, v109
	v_cvt_pk_bf16_f32 v107, v110, v111
	v_add_u32_e32 v236, 0x18000, v230
	s_nop 0
	global_store_dwordx4 v236, v[104:107], s[22:23] offset:64
	global_load_dwordx4 v[130:133], v233, s[2:3] offset:256 sc0
	global_load_dwordx4 v[134:137], v233, s[2:3] offset:272 sc0
	global_load_dwordx4 v[138:141], v233, s[2:3] offset:384 sc0
	global_load_dwordx4 v[142:145], v233, s[2:3] offset:400 sc0
	global_load_dwordx4 v[146:149], v233, s[16:17] offset:256 sc0
	global_load_dwordx4 v[150:153], v233, s[16:17] offset:272 sc0
	global_load_dwordx4 v[154:157], v233, s[16:17] offset:384 sc0
	global_load_dwordx4 v[158:161], v233, s[16:17] offset:400 sc0
	global_load_dwordx4 v[162:165], v233, s[0:1] offset:256 sc0
	global_load_dwordx4 v[166:169], v233, s[0:1] offset:272 sc0
	global_load_dwordx4 v[170:173], v233, s[0:1] offset:384 sc0
	global_load_dwordx4 v[174:177], v233, s[0:1] offset:400 sc0
	v_add_u32_e32 v236, 0x0, v230
	v_add_u32_e32 v237, 0x0, v231
	v_subrev_u32_e32 v240, 0x1600, v237
	global_load_dwordx4 v[178:181], v236, s[22:23] offset:128 sc0
	global_load_dwordx4 v[182:185], v236, s[22:23] offset:192 sc0
	global_load_dwordx4 v[186:189], v237, s[96:97] offset:128 sc0
	global_load_dwordx4 v[190:193], v237, s[96:97] offset:192 sc0
	global_load_dwordx4 v[194:197], v240, s[96:97] offset:128 sc0
	global_load_dwordx4 v[198:201], v240, s[96:97] offset:192 sc0
	v_add_u32_e32 v236, 0x0, v232
	s_nop 0
	global_load_dword v234, v236, s[96:97] offset:16
	v_add_u32_e32 v237, 0x0, v247
	global_load_dwordx4 v[202:205], v237, s[20:21] offset:256 sc0
	global_load_dwordx4 v[206:209], v237, s[20:21] offset:272 sc0
	global_load_dwordx4 v[210:213], v237, s[20:21] offset:384 sc0
	global_load_dwordx4 v[214:217], v237, s[20:21] offset:400 sc0
	s_waitcnt vmcnt(0)
; __device__ __forceinline__ float bf2f(u16 h) { return __uint_as_float(((unsigned)h) << 16); }
; __device__ __forceinline__ float prevP(const Params& p, const u16* P, int row, int c) {
;     ...
;   const bool start = (row < NP) ? ((row & 2047) == 0) : (((row - NP) & 3) == 0);
;   if (start) v = (row < NP) ? 0.f : p.in[3][(size_t)((row - NP) >> 2) * 2560 + c];
; template <int EPI> ...
;     ...
;       for (int i = 0; i < 16; i++) {
;         const int rl = rbase + (i & 3) + 8 * (i >> 2);
;         const int row = m0 + rl;
;         float o0 = bf2f(Y[(size_t)row * 1024 + 256 + ch0]);
;         float o1 = bf2f(Y[(size_t)row * 1024 + 256 + ch1]);
;         float mean = hsum32(o0 + o1) * (1.0f / 64.0f);
;         float d0 = o0 - mean, d1 = o1 - mean;
;         float var = hsum32(d0 * d0 + d1 * d1) * (1.0f / 64.0f);
;         float rstd = rsqrtf(var + 64e-5f);
;         float pv0 = bf2f(P[(size_t)row * 2816 + 256 + 1536 + ch0]);
;         float pv1 = bf2f(P[(size_t)row * 2816 + 256 + 1536 + ch1]);
;         float pp0 = prevP(p, P, row, 1536 + ch0), pp1 = prevP(p, P, row, 1536 + ch1);
;         float vv0 = pv0 + (pp0 - pv0) * mu0, vv1 = pv1 + (pp1 - pv1) * mu1;
;         float b = bs[((size_t)row * 12 + hh) * 4 + 2];
;         float y0 = (d0 * rstd * gg0 + gb0 + b * vv0) * acc0[i];
;         float y1 = (d1 * rstd * gg1 + gb1 + b * vv1) * acc1[i];
;         Y[(size_t)row * 1024 + 256 + ch0] = f2bf(y0);
;         Y[(size_t)row * 1024 + 256 + ch1] = f2bf(y1);
	v_lshlrev_b32_e32 v240, 16, v178
	v_and_b32_e32 v241, 0xffff0000, v178
	v_add_f32_e32 v244, v240, v241
	v_lshlrev_b32_e32 v240, 16, v179
	v_and_b32_e32 v241, 0xffff0000, v179
	v_add_f32_e32 v244, v244, v240
	v_add_f32_e32 v244, v244, v241
	v_lshlrev_b32_e32 v240, 16, v180
	v_and_b32_e32 v241, 0xffff0000, v180
	v_add_f32_e32 v244, v244, v240
	v_add_f32_e32 v244, v244, v241
	v_lshlrev_b32_e32 v240, 16, v181
	v_and_b32_e32 v241, 0xffff0000, v181
	v_add_f32_e32 v244, v244, v240
	v_add_f32_e32 v244, v244, v241
	v_lshlrev_b32_e32 v240, 16, v182
	v_and_b32_e32 v241, 0xffff0000, v182
	v_add_f32_e32 v244, v244, v240
	v_add_f32_e32 v244, v244, v241
	v_lshlrev_b32_e32 v240, 16, v183
	v_and_b32_e32 v241, 0xffff0000, v183
	v_add_f32_e32 v244, v244, v240
	v_add_f32_e32 v244, v244, v241
	v_lshlrev_b32_e32 v240, 16, v184
	v_and_b32_e32 v241, 0xffff0000, v184
	v_add_f32_e32 v244, v244, v240
	v_add_f32_e32 v244, v244, v241
	v_lshlrev_b32_e32 v240, 16, v185
	v_and_b32_e32 v241, 0xffff0000, v185
	v_add_f32_e32 v244, v244, v240
	v_add_f32_e32 v244, v244, v241
	v_mov_b32_e32 v240, v244
	s_nop 1
	v_permlane16_swap_b32_e32 v240, v244
	v_add_f32_e32 v244, v244, v240
	v_mov_b32_e32 v240, v244
	s_nop 1
	v_permlane32_swap_b32_e32 v240, v244
	v_add_f32_e32 v244, v244, v240
	v_mul_f32_e32 v238, 0x3c800000, v244
	v_lshlrev_b32_e32 v240, 16, v178
	v_and_b32_e32 v241, 0xffff0000, v178
	v_sub_f32_e32 v240, v240, v238
	v_sub_f32_e32 v241, v241, v238
	v_mul_f32_e32 v245, v240, v240
	v_fmac_f32_e32 v245, v241, v241
	v_lshlrev_b32_e32 v240, 16, v179
	v_and_b32_e32 v241, 0xffff0000, v179
	v_sub_f32_e32 v240, v240, v238
	v_sub_f32_e32 v241, v241, v238
	v_fmac_f32_e32 v245, v240, v240
	v_fmac_f32_e32 v245, v241, v241
	v_lshlrev_b32_e32 v240, 16, v180
	v_and_b32_e32 v241, 0xffff0000, v180
	v_sub_f32_e32 v240, v240, v238
	v_sub_f32_e32 v241, v241, v238
	v_fmac_f32_e32 v245, v240, v240
	v_fmac_f32_e32 v245, v241, v241
	v_lshlrev_b32_e32 v240, 16, v181
	v_and_b32_e32 v241, 0xffff0000, v181
	v_sub_f32_e32 v240, v240, v238
	v_sub_f32_e32 v241, v241, v238
	v_fmac_f32_e32 v245, v240, v240
	v_fmac_f32_e32 v245, v241, v241
	v_lshlrev_b32_e32 v240, 16, v182
	v_and_b32_e32 v241, 0xffff0000, v182
	v_sub_f32_e32 v240, v240, v238
	v_sub_f32_e32 v241, v241, v238
	v_fmac_f32_e32 v245, v240, v240
	v_fmac_f32_e32 v245, v241, v241
	v_lshlrev_b32_e32 v240, 16, v183
	v_and_b32_e32 v241, 0xffff0000, v183
	v_sub_f32_e32 v240, v240, v238
	v_sub_f32_e32 v241, v241, v238
	v_fmac_f32_e32 v245, v240, v240
	v_fmac_f32_e32 v245, v241, v241
	v_lshlrev_b32_e32 v240, 16, v184
	v_and_b32_e32 v241, 0xffff0000, v184
	v_sub_f32_e32 v240, v240, v238
	v_sub_f32_e32 v241, v241, v238
	v_fmac_f32_e32 v245, v240, v240
	v_fmac_f32_e32 v245, v241, v241
	v_lshlrev_b32_e32 v240, 16, v185
	v_and_b32_e32 v241, 0xffff0000, v185
	v_sub_f32_e32 v240, v240, v238
	v_sub_f32_e32 v241, v241, v238
	v_fmac_f32_e32 v245, v240, v240
	v_fmac_f32_e32 v245, v241, v241
	v_mov_b32_e32 v240, v245
	s_nop 1
	v_permlane16_swap_b32_e32 v240, v245
	v_add_f32_e32 v245, v245, v240
	v_mov_b32_e32 v240, v245
	s_nop 1
	v_permlane32_swap_b32_e32 v240, v245
	v_add_f32_e32 v245, v245, v240
	v_mov_b32_e32 v240, 0x3a27c5ac
	v_fmamk_f32 v245, v245, 0x3c800000, v240
	v_rsq_f32_e32 v239, v245
	v_and_b32_e32 v240, 3, v248
	v_cmp_eq_u32_e32 vcc, 0, v240
	s_nop 1
	v_lshlrev_b32_e32 v240, 16, v178
	v_and_b32_e32 v244, 0xffff0000, v178
	v_sub_f32_e32 v240, v240, v238
	v_sub_f32_e32 v244, v244, v238
	v_mul_f32_e32 v240, v240, v239
	v_mul_f32_e32 v244, v244, v239
	v_fma_f32 v240, v130, v240, v146
	v_fma_f32 v244, v131, v244, v147
	v_lshlrev_b32_e32 v241, 16, v186
	v_and_b32_e32 v245, 0xffff0000, v186
	v_lshlrev_b32_e32 v243, 16, v194
	v_and_b32_e32 v246, 0xffff0000, v194
	v_cndmask_b32_e32 v243, v243, v202, vcc
	v_cndmask_b32_e32 v246, v246, v203, vcc
	v_sub_f32_e32 v243, v243, v241
	v_sub_f32_e32 v246, v246, v245
	v_fmac_f32_e32 v241, v162, v243
	v_fmac_f32_e32 v245, v163, v246
	v_fmac_f32_e32 v240, v234, v241
	v_fmac_f32_e32 v244, v234, v245
	v_mul_f32_e32 v16, v16, v240
	v_mul_f32_e32 v17, v17, v244
	v_lshlrev_b32_e32 v240, 16, v179
	v_and_b32_e32 v244, 0xffff0000, v179
	v_sub_f32_e32 v240, v240, v238
	v_sub_f32_e32 v244, v244, v238
	v_mul_f32_e32 v240, v240, v239
	v_mul_f32_e32 v244, v244, v239
	v_fma_f32 v240, v132, v240, v148
	v_fma_f32 v244, v133, v244, v149
	v_lshlrev_b32_e32 v241, 16, v187
	v_and_b32_e32 v245, 0xffff0000, v187
	v_lshlrev_b32_e32 v243, 16, v195
	v_and_b32_e32 v246, 0xffff0000, v195
	v_cndmask_b32_e32 v243, v243, v204, vcc
	v_cndmask_b32_e32 v246, v246, v205, vcc
	v_sub_f32_e32 v243, v243, v241
	v_sub_f32_e32 v246, v246, v245
	v_fmac_f32_e32 v241, v164, v243
	v_fmac_f32_e32 v245, v165, v246
	v_fmac_f32_e32 v240, v234, v241
	v_fmac_f32_e32 v244, v234, v245
	v_mul_f32_e32 v18, v18, v240
	v_mul_f32_e32 v19, v19, v244
	v_lshlrev_b32_e32 v240, 16, v180
	v_and_b32_e32 v244, 0xffff0000, v180
	v_sub_f32_e32 v240, v240, v238
	v_sub_f32_e32 v244, v244, v238
	v_mul_f32_e32 v240, v240, v239
	v_mul_f32_e32 v244, v244, v239
	v_fma_f32 v240, v134, v240, v150
	v_fma_f32 v244, v135, v244, v151
	v_lshlrev_b32_e32 v241, 16, v188
	v_and_b32_e32 v245, 0xffff0000, v188
	v_lshlrev_b32_e32 v243, 16, v196
	v_and_b32_e32 v246, 0xffff0000, v196
	v_cndmask_b32_e32 v243, v243, v206, vcc
	v_cndmask_b32_e32 v246, v246, v207, vcc
	v_sub_f32_e32 v243, v243, v241
	v_sub_f32_e32 v246, v246, v245
	v_fmac_f32_e32 v241, v166, v243
	v_fmac_f32_e32 v245, v167, v246
	v_fmac_f32_e32 v240, v234, v241
	v_fmac_f32_e32 v244, v234, v245
	v_mul_f32_e32 v20, v20, v240
	v_mul_f32_e32 v21, v21, v244
	v_lshlrev_b32_e32 v240, 16, v181
	v_and_b32_e32 v244, 0xffff0000, v181
	v_sub_f32_e32 v240, v240, v238
; __device__ __forceinline__ float bf2f(u16 h) { return __uint_as_float(((unsigned)h) << 16); }
; __device__ __forceinline__ float prevP(const Params& p, const u16* P, int row, int c) {
;     ...
;   const bool start = (row < NP) ? ((row & 2047) == 0) : (((row - NP) & 3) == 0);
;   if (start) v = (row < NP) ? 0.f : p.in[3][(size_t)((row - NP) >> 2) * 2560 + c];
; template <int EPI> ...
;     ...
;       for (int i = 0; i < 16; i++) {
;         const int rl = rbase + (i & 3) + 8 * (i >> 2);
;         const int row = m0 + rl;
;         float o0 = bf2f(Y[(size_t)row * 1024 + 256 + ch0]);
;         float o1 = bf2f(Y[(size_t)row * 1024 + 256 + ch1]);
;         float mean = hsum32(o0 + o1) * (1.0f / 64.0f);
;         float d0 = o0 - mean, d1 = o1 - mean;
;         float var = hsum32(d0 * d0 + d1 * d1) * (1.0f / 64.0f);
;         float rstd = rsqrtf(var + 64e-5f);
;         float pv0 = bf2f(P[(size_t)row * 2816 + 256 + 1536 + ch0]);
;         float pv1 = bf2f(P[(size_t)row * 2816 + 256 + 1536 + ch1]);
;         float pp0 = prevP(p, P, row, 1536 + ch0), pp1 = prevP(p, P, row, 1536 + ch1);
;         float vv0 = pv0 + (pp0 - pv0) * mu0, vv1 = pv1 + (pp1 - pv1) * mu1;
;         float b = bs[((size_t)row * 12 + hh) * 4 + 2];
;         float y0 = (d0 * rstd * gg0 + gb0 + b * vv0) * acc0[i];
;         float y1 = (d1 * rstd * gg1 + gb1 + b * vv1) * acc1[i];
;         Y[(size_t)row * 1024 + 256 + ch0] = f2bf(y0);
;         Y[(size_t)row * 1024 + 256 + ch1] = f2bf(y1);
	v_sub_f32_e32 v244, v244, v238
	v_mul_f32_e32 v240, v240, v239
	v_mul_f32_e32 v244, v244, v239
	v_fma_f32 v240, v136, v240, v152
	v_fma_f32 v244, v137, v244, v153
	v_lshlrev_b32_e32 v241, 16, v189
	v_and_b32_e32 v245, 0xffff0000, v189
	v_lshlrev_b32_e32 v243, 16, v197
	v_and_b32_e32 v246, 0xffff0000, v197
	v_cndmask_b32_e32 v243, v243, v208, vcc
	v_cndmask_b32_e32 v246, v246, v209, vcc
	v_sub_f32_e32 v243, v243, v241
	v_sub_f32_e32 v246, v246, v245
	v_fmac_f32_e32 v241, v168, v243
	v_fmac_f32_e32 v245, v169, v246
	v_fmac_f32_e32 v240, v234, v241
	v_fmac_f32_e32 v244, v234, v245
	v_mul_f32_e32 v22, v22, v240
	v_mul_f32_e32 v23, v23, v244
	v_cvt_pk_bf16_f32 v16, v16, v17
	v_cvt_pk_bf16_f32 v17, v18, v19
	v_cvt_pk_bf16_f32 v18, v20, v21
	v_cvt_pk_bf16_f32 v19, v22, v23
	v_add_u32_e32 v236, 0x0, v230
	s_nop 0
	global_store_dwordx4 v236, v[16:19], s[22:23] offset:128
	v_lshlrev_b32_e32 v240, 16, v182
	v_and_b32_e32 v244, 0xffff0000, v182
	v_sub_f32_e32 v240, v240, v238
	v_sub_f32_e32 v244, v244, v238
	v_mul_f32_e32 v240, v240, v239
	v_mul_f32_e32 v244, v244, v239
	v_fma_f32 v240, v138, v240, v154
	v_fma_f32 v244, v139, v244, v155
	v_lshlrev_b32_e32 v241, 16, v190
	v_and_b32_e32 v245, 0xffff0000, v190
	v_lshlrev_b32_e32 v243, 16, v198
	v_and_b32_e32 v246, 0xffff0000, v198
	v_cndmask_b32_e32 v243, v243, v210, vcc
	v_cndmask_b32_e32 v246, v246, v211, vcc
	v_sub_f32_e32 v243, v243, v241
	v_sub_f32_e32 v246, v246, v245
	v_fmac_f32_e32 v241, v170, v243
	v_fmac_f32_e32 v245, v171, v246
	v_fmac_f32_e32 v240, v234, v241
	v_fmac_f32_e32 v244, v234, v245
	v_mul_f32_e32 v24, v24, v240
	v_mul_f32_e32 v25, v25, v244
	v_lshlrev_b32_e32 v240, 16, v183
	v_and_b32_e32 v244, 0xffff0000, v183
	v_sub_f32_e32 v240, v240, v238
	v_sub_f32_e32 v244, v244, v238
	v_mul_f32_e32 v240, v240, v239
	v_mul_f32_e32 v244, v244, v239
	v_fma_f32 v240, v140, v240, v156
	v_fma_f32 v244, v141, v244, v157
	v_lshlrev_b32_e32 v241, 16, v191
	v_and_b32_e32 v245, 0xffff0000, v191
	v_lshlrev_b32_e32 v243, 16, v199
	v_and_b32_e32 v246, 0xffff0000, v199
	v_cndmask_b32_e32 v243, v243, v212, vcc
	v_cndmask_b32_e32 v246, v246, v213, vcc
	v_sub_f32_e32 v243, v243, v241
	v_sub_f32_e32 v246, v246, v245
	v_fmac_f32_e32 v241, v172, v243
	v_fmac_f32_e32 v245, v173, v246
	v_fmac_f32_e32 v240, v234, v241
	v_fmac_f32_e32 v244, v234, v245
	v_mul_f32_e32 v26, v26, v240
	v_mul_f32_e32 v27, v27, v244
	v_lshlrev_b32_e32 v240, 16, v184
	v_and_b32_e32 v244, 0xffff0000, v184
	v_sub_f32_e32 v240, v240, v238
	v_sub_f32_e32 v244, v244, v238
	v_mul_f32_e32 v240, v240, v239
	v_mul_f32_e32 v244, v244, v239
	v_fma_f32 v240, v142, v240, v158
	v_fma_f32 v244, v143, v244, v159
	v_lshlrev_b32_e32 v241, 16, v192
	v_and_b32_e32 v245, 0xffff0000, v192
	v_lshlrev_b32_e32 v243, 16, v200
	v_and_b32_e32 v246, 0xffff0000, v200
	v_cndmask_b32_e32 v243, v243, v214, vcc
	v_cndmask_b32_e32 v246, v246, v215, vcc
	v_sub_f32_e32 v243, v243, v241
	v_sub_f32_e32 v246, v246, v245
	v_fmac_f32_e32 v241, v174, v243
	v_fmac_f32_e32 v245, v175, v246
	v_fmac_f32_e32 v240, v234, v241
	v_fmac_f32_e32 v244, v234, v245
	v_mul_f32_e32 v28, v28, v240
	v_mul_f32_e32 v29, v29, v244
	v_lshlrev_b32_e32 v240, 16, v185
	v_and_b32_e32 v244, 0xffff0000, v185
	v_sub_f32_e32 v240, v240, v238
	v_sub_f32_e32 v244, v244, v238
	v_mul_f32_e32 v240, v240, v239
	v_mul_f32_e32 v244, v244, v239
	v_fma_f32 v240, v144, v240, v160
	v_fma_f32 v244, v145, v244, v161
	v_lshlrev_b32_e32 v241, 16, v193
	v_and_b32_e32 v245, 0xffff0000, v193
	v_lshlrev_b32_e32 v243, 16, v201
	v_and_b32_e32 v246, 0xffff0000, v201
	v_cndmask_b32_e32 v243, v243, v216, vcc
	v_cndmask_b32_e32 v246, v246, v217, vcc
	v_sub_f32_e32 v243, v243, v241
	v_sub_f32_e32 v246, v246, v245
	v_fmac_f32_e32 v241, v176, v243
	v_fmac_f32_e32 v245, v177, v246
	v_fmac_f32_e32 v240, v234, v241
	v_fmac_f32_e32 v244, v234, v245
	v_mul_f32_e32 v30, v30, v240
	v_mul_f32_e32 v31, v31, v244
	v_cvt_pk_bf16_f32 v24, v24, v25
	v_cvt_pk_bf16_f32 v25, v26, v27
	v_cvt_pk_bf16_f32 v26, v28, v29
	v_cvt_pk_bf16_f32 v27, v30, v31
	v_add_u32_e32 v236, 0x0, v230
	s_nop 0
	global_store_dwordx4 v236, v[24:27], s[22:23] offset:192
	v_add_u32_e32 v236, 0x8000, v230
	v_add_u32_e32 v237, 0x16000, v231
	v_subrev_u32_e32 v240, 0x1600, v237
	global_load_dwordx4 v[178:181], v236, s[22:23] offset:128 sc0
	global_load_dwordx4 v[182:185], v236, s[22:23] offset:192 sc0
	global_load_dwordx4 v[186:189], v237, s[96:97] offset:128 sc0
	global_load_dwordx4 v[190:193], v237, s[96:97] offset:192 sc0
	global_load_dwordx4 v[194:197], v240, s[96:97] offset:128 sc0
	global_load_dwordx4 v[198:201], v240, s[96:97] offset:192 sc0
	v_add_u32_e32 v236, 0xc00, v232
	s_nop 0
	global_load_dword v234, v236, s[96:97] offset:16
	v_add_u32_e32 v237, 0xa000, v247
	global_load_dwordx4 v[202:205], v237, s[20:21] offset:256 sc0
	global_load_dwordx4 v[206:209], v237, s[20:21] offset:272 sc0
	global_load_dwordx4 v[210:213], v237, s[20:21] offset:384 sc0
	global_load_dwordx4 v[214:217], v237, s[20:21] offset:400 sc0
	s_waitcnt vmcnt(0)
; __device__ __forceinline__ float bf2f(u16 h) { return __uint_as_float(((unsigned)h) << 16); }
; __device__ __forceinline__ float prevP(const Params& p, const u16* P, int row, int c) {
;     ...
;   const bool start = (row < NP) ? ((row & 2047) == 0) : (((row - NP) & 3) == 0);
;   if (start) v = (row < NP) ? 0.f : p.in[3][(size_t)((row - NP) >> 2) * 2560 + c];
; template <int EPI> ...
;     ...
;       for (int i = 0; i < 16; i++) {
;         const int rl = rbase + (i & 3) + 8 * (i >> 2);
;         const int row = m0 + rl;
;         float o0 = bf2f(Y[(size_t)row * 1024 + 256 + ch0]);
;         float o1 = bf2f(Y[(size_t)row * 1024 + 256 + ch1]);
;         float mean = hsum32(o0 + o1) * (1.0f / 64.0f);
;         float d0 = o0 - mean, d1 = o1 - mean;
;         float var = hsum32(d0 * d0 + d1 * d1) * (1.0f / 64.0f);
;         float rstd = rsqrtf(var + 64e-5f);
;         float pv0 = bf2f(P[(size_t)row * 2816 + 256 + 1536 + ch0]);
;         float pv1 = bf2f(P[(size_t)row * 2816 + 256 + 1536 + ch1]);
;         float pp0 = prevP(p, P, row, 1536 + ch0), pp1 = prevP(p, P, row, 1536 + ch1);
;         float vv0 = pv0 + (pp0 - pv0) * mu0, vv1 = pv1 + (pp1 - pv1) * mu1;
;         float b = bs[((size_t)row * 12 + hh) * 4 + 2];
;         float y0 = (d0 * rstd * gg0 + gb0 + b * vv0) * acc0[i];
;         float y1 = (d1 * rstd * gg1 + gb1 + b * vv1) * acc1[i];
;         Y[(size_t)row * 1024 + 256 + ch0] = f2bf(y0);
;         Y[(size_t)row * 1024 + 256 + ch1] = f2bf(y1);
	v_lshlrev_b32_e32 v240, 16, v178
	v_and_b32_e32 v241, 0xffff0000, v178
	v_add_f32_e32 v244, v240, v241
	v_lshlrev_b32_e32 v240, 16, v179
	v_and_b32_e32 v241, 0xffff0000, v179
	v_add_f32_e32 v244, v244, v240
	v_add_f32_e32 v244, v244, v241
	v_lshlrev_b32_e32 v240, 16, v180
	v_and_b32_e32 v241, 0xffff0000, v180
	v_add_f32_e32 v244, v244, v240
	v_add_f32_e32 v244, v244, v241
	v_lshlrev_b32_e32 v240, 16, v181
	v_and_b32_e32 v241, 0xffff0000, v181
	v_add_f32_e32 v244, v244, v240
	v_add_f32_e32 v244, v244, v241
	v_lshlrev_b32_e32 v240, 16, v182
	v_and_b32_e32 v241, 0xffff0000, v182
	v_add_f32_e32 v244, v244, v240
	v_add_f32_e32 v244, v244, v241
	v_lshlrev_b32_e32 v240, 16, v183
	v_and_b32_e32 v241, 0xffff0000, v183
	v_add_f32_e32 v244, v244, v240
	v_add_f32_e32 v244, v244, v241
	v_lshlrev_b32_e32 v240, 16, v184
	v_and_b32_e32 v241, 0xffff0000, v184
	v_add_f32_e32 v244, v244, v240
	v_add_f32_e32 v244, v244, v241
	v_lshlrev_b32_e32 v240, 16, v185
	v_and_b32_e32 v241, 0xffff0000, v185
	v_add_f32_e32 v244, v244, v240
	v_add_f32_e32 v244, v244, v241
	v_mov_b32_e32 v240, v244
	s_nop 1
	v_permlane16_swap_b32_e32 v240, v244
	v_add_f32_e32 v244, v244, v240
	v_mov_b32_e32 v240, v244
	s_nop 1
	v_permlane32_swap_b32_e32 v240, v244
	v_add_f32_e32 v244, v244, v240
	v_mul_f32_e32 v238, 0x3c800000, v244
	v_lshlrev_b32_e32 v240, 16, v178
	v_and_b32_e32 v241, 0xffff0000, v178
	v_sub_f32_e32 v240, v240, v238
	v_sub_f32_e32 v241, v241, v238
	v_mul_f32_e32 v245, v240, v240
	v_fmac_f32_e32 v245, v241, v241
	v_lshlrev_b32_e32 v240, 16, v179
	v_and_b32_e32 v241, 0xffff0000, v179
	v_sub_f32_e32 v240, v240, v238
	v_sub_f32_e32 v241, v241, v238
	v_fmac_f32_e32 v245, v240, v240
	v_fmac_f32_e32 v245, v241, v241
	v_lshlrev_b32_e32 v240, 16, v180
	v_and_b32_e32 v241, 0xffff0000, v180
	v_sub_f32_e32 v240, v240, v238
	v_sub_f32_e32 v241, v241, v238
	v_fmac_f32_e32 v245, v240, v240
	v_fmac_f32_e32 v245, v241, v241
	v_lshlrev_b32_e32 v240, 16, v181
	v_and_b32_e32 v241, 0xffff0000, v181
	v_sub_f32_e32 v240, v240, v238
	v_sub_f32_e32 v241, v241, v238
	v_fmac_f32_e32 v245, v240, v240
	v_fmac_f32_e32 v245, v241, v241
	v_lshlrev_b32_e32 v240, 16, v182
	v_and_b32_e32 v241, 0xffff0000, v182
	v_sub_f32_e32 v240, v240, v238
	v_sub_f32_e32 v241, v241, v238
	v_fmac_f32_e32 v245, v240, v240
	v_fmac_f32_e32 v245, v241, v241
	v_lshlrev_b32_e32 v240, 16, v183
	v_and_b32_e32 v241, 0xffff0000, v183
	v_sub_f32_e32 v240, v240, v238
	v_sub_f32_e32 v241, v241, v238
	v_fmac_f32_e32 v245, v240, v240
	v_fmac_f32_e32 v245, v241, v241
	v_lshlrev_b32_e32 v240, 16, v184
	v_and_b32_e32 v241, 0xffff0000, v184
	v_sub_f32_e32 v240, v240, v238
	v_sub_f32_e32 v241, v241, v238
	v_fmac_f32_e32 v245, v240, v240
	v_fmac_f32_e32 v245, v241, v241
	v_lshlrev_b32_e32 v240, 16, v185
	v_and_b32_e32 v241, 0xffff0000, v185
	v_sub_f32_e32 v240, v240, v238
	v_sub_f32_e32 v241, v241, v238
	v_fmac_f32_e32 v245, v240, v240
	v_fmac_f32_e32 v245, v241, v241
	v_mov_b32_e32 v240, v245
	s_nop 1
	v_permlane16_swap_b32_e32 v240, v245
	v_add_f32_e32 v245, v245, v240
	v_mov_b32_e32 v240, v245
	s_nop 1
	v_permlane32_swap_b32_e32 v240, v245
	v_add_f32_e32 v245, v245, v240
	v_mov_b32_e32 v240, 0x3a27c5ac
	v_fmamk_f32 v245, v245, 0x3c800000, v240
	v_rsq_f32_e32 v239, v245
	v_and_b32_e32 v240, 3, v248
	v_cmp_eq_u32_e32 vcc, 0, v240
	s_nop 1
	v_lshlrev_b32_e32 v240, 16, v178
	v_and_b32_e32 v244, 0xffff0000, v178
	v_sub_f32_e32 v240, v240, v238
	v_sub_f32_e32 v244, v244, v238
	v_mul_f32_e32 v240, v240, v239
	v_mul_f32_e32 v244, v244, v239
	v_fma_f32 v240, v130, v240, v146
	v_fma_f32 v244, v131, v244, v147
	v_lshlrev_b32_e32 v241, 16, v186
	v_and_b32_e32 v245, 0xffff0000, v186
	v_lshlrev_b32_e32 v243, 16, v194
	v_and_b32_e32 v246, 0xffff0000, v194
	v_cndmask_b32_e32 v243, v243, v202, vcc
	v_cndmask_b32_e32 v246, v246, v203, vcc
	v_sub_f32_e32 v243, v243, v241
	v_sub_f32_e32 v246, v246, v245
	v_fmac_f32_e32 v241, v162, v243
	v_fmac_f32_e32 v245, v163, v246
	v_fmac_f32_e32 v240, v234, v241
	v_fmac_f32_e32 v244, v234, v245
	v_mul_f32_e32 v48, v48, v240
	v_mul_f32_e32 v49, v49, v244
	v_lshlrev_b32_e32 v240, 16, v179
	v_and_b32_e32 v244, 0xffff0000, v179
	v_sub_f32_e32 v240, v240, v238
	v_sub_f32_e32 v244, v244, v238
	v_mul_f32_e32 v240, v240, v239
	v_mul_f32_e32 v244, v244, v239
	v_fma_f32 v240, v132, v240, v148
	v_fma_f32 v244, v133, v244, v149
	v_lshlrev_b32_e32 v241, 16, v187
	v_and_b32_e32 v245, 0xffff0000, v187
	v_lshlrev_b32_e32 v243, 16, v195
	v_and_b32_e32 v246, 0xffff0000, v195
	v_cndmask_b32_e32 v243, v243, v204, vcc
	v_cndmask_b32_e32 v246, v246, v205, vcc
	v_sub_f32_e32 v243, v243, v241
	v_sub_f32_e32 v246, v246, v245
	v_fmac_f32_e32 v241, v164, v243
	v_fmac_f32_e32 v245, v165, v246
	v_fmac_f32_e32 v240, v234, v241
	v_fmac_f32_e32 v244, v234, v245
	v_mul_f32_e32 v50, v50, v240
	v_mul_f32_e32 v51, v51, v244
	v_lshlrev_b32_e32 v240, 16, v180
	v_and_b32_e32 v244, 0xffff0000, v180
	v_sub_f32_e32 v240, v240, v238
	v_sub_f32_e32 v244, v244, v238
	v_mul_f32_e32 v240, v240, v239
	v_mul_f32_e32 v244, v244, v239
	v_fma_f32 v240, v134, v240, v150
	v_fma_f32 v244, v135, v244, v151
	v_lshlrev_b32_e32 v241, 16, v188
	v_and_b32_e32 v245, 0xffff0000, v188
	v_lshlrev_b32_e32 v243, 16, v196
	v_and_b32_e32 v246, 0xffff0000, v196
	v_cndmask_b32_e32 v243, v243, v206, vcc
	v_cndmask_b32_e32 v246, v246, v207, vcc
	v_sub_f32_e32 v243, v243, v241
	v_sub_f32_e32 v246, v246, v245
	v_fmac_f32_e32 v241, v166, v243
	v_fmac_f32_e32 v245, v167, v246
	v_fmac_f32_e32 v240, v234, v241
	v_fmac_f32_e32 v244, v234, v245
	v_mul_f32_e32 v52, v52, v240
	v_mul_f32_e32 v53, v53, v244
	v_lshlrev_b32_e32 v240, 16, v181
	v_and_b32_e32 v244, 0xffff0000, v181
	v_sub_f32_e32 v240, v240, v238
; __device__ __forceinline__ float bf2f(u16 h) { return __uint_as_float(((unsigned)h) << 16); }
; __device__ __forceinline__ float prevP(const Params& p, const u16* P, int row, int c) {
;     ...
;   const bool start = (row < NP) ? ((row & 2047) == 0) : (((row - NP) & 3) == 0);
;   if (start) v = (row < NP) ? 0.f : p.in[3][(size_t)((row - NP) >> 2) * 2560 + c];
; template <int EPI> ...
;     ...
;       for (int i = 0; i < 16; i++) {
;         const int rl = rbase + (i & 3) + 8 * (i >> 2);
;         const int row = m0 + rl;
;         float o0 = bf2f(Y[(size_t)row * 1024 + 256 + ch0]);
;         float o1 = bf2f(Y[(size_t)row * 1024 + 256 + ch1]);
;         float mean = hsum32(o0 + o1) * (1.0f / 64.0f);
;         float d0 = o0 - mean, d1 = o1 - mean;
;         float var = hsum32(d0 * d0 + d1 * d1) * (1.0f / 64.0f);
;         float rstd = rsqrtf(var + 64e-5f);
;         float pv0 = bf2f(P[(size_t)row * 2816 + 256 + 1536 + ch0]);
;         float pv1 = bf2f(P[(size_t)row * 2816 + 256 + 1536 + ch1]);
;         float pp0 = prevP(p, P, row, 1536 + ch0), pp1 = prevP(p, P, row, 1536 + ch1);
;         float vv0 = pv0 + (pp0 - pv0) * mu0, vv1 = pv1 + (pp1 - pv1) * mu1;
;         float b = bs[((size_t)row * 12 + hh) * 4 + 2];
;         float y0 = (d0 * rstd * gg0 + gb0 + b * vv0) * acc0[i];
;         float y1 = (d1 * rstd * gg1 + gb1 + b * vv1) * acc1[i];
;         Y[(size_t)row * 1024 + 256 + ch0] = f2bf(y0);
;         Y[(size_t)row * 1024 + 256 + ch1] = f2bf(y1);
	v_sub_f32_e32 v244, v244, v238
	v_mul_f32_e32 v240, v240, v239
	v_mul_f32_e32 v244, v244, v239
	v_fma_f32 v240, v136, v240, v152
	v_fma_f32 v244, v137, v244, v153
	v_lshlrev_b32_e32 v241, 16, v189
	v_and_b32_e32 v245, 0xffff0000, v189
	v_lshlrev_b32_e32 v243, 16, v197
	v_and_b32_e32 v246, 0xffff0000, v197
	v_cndmask_b32_e32 v243, v243, v208, vcc
	v_cndmask_b32_e32 v246, v246, v209, vcc
	v_sub_f32_e32 v243, v243, v241
	v_sub_f32_e32 v246, v246, v245
	v_fmac_f32_e32 v241, v168, v243
	v_fmac_f32_e32 v245, v169, v246
	v_fmac_f32_e32 v240, v234, v241
	v_fmac_f32_e32 v244, v234, v245
	v_mul_f32_e32 v54, v54, v240
	v_mul_f32_e32 v55, v55, v244
	v_cvt_pk_bf16_f32 v48, v48, v49
	v_cvt_pk_bf16_f32 v49, v50, v51
	v_cvt_pk_bf16_f32 v50, v52, v53
	v_cvt_pk_bf16_f32 v51, v54, v55
	v_add_u32_e32 v236, 0x8000, v230
	s_nop 0
	global_store_dwordx4 v236, v[48:51], s[22:23] offset:128
	v_lshlrev_b32_e32 v240, 16, v182
	v_and_b32_e32 v244, 0xffff0000, v182
	v_sub_f32_e32 v240, v240, v238
	v_sub_f32_e32 v244, v244, v238
	v_mul_f32_e32 v240, v240, v239
	v_mul_f32_e32 v244, v244, v239
	v_fma_f32 v240, v138, v240, v154
	v_fma_f32 v244, v139, v244, v155
	v_lshlrev_b32_e32 v241, 16, v190
	v_and_b32_e32 v245, 0xffff0000, v190
	v_lshlrev_b32_e32 v243, 16, v198
	v_and_b32_e32 v246, 0xffff0000, v198
	v_cndmask_b32_e32 v243, v243, v210, vcc
	v_cndmask_b32_e32 v246, v246, v211, vcc
	v_sub_f32_e32 v243, v243, v241
	v_sub_f32_e32 v246, v246, v245
	v_fmac_f32_e32 v241, v170, v243
	v_fmac_f32_e32 v245, v171, v246
	v_fmac_f32_e32 v240, v234, v241
	v_fmac_f32_e32 v244, v234, v245
	v_mul_f32_e32 v56, v56, v240
	v_mul_f32_e32 v57, v57, v244
	v_lshlrev_b32_e32 v240, 16, v183
	v_and_b32_e32 v244, 0xffff0000, v183
	v_sub_f32_e32 v240, v240, v238
	v_sub_f32_e32 v244, v244, v238
	v_mul_f32_e32 v240, v240, v239
	v_mul_f32_e32 v244, v244, v239
	v_fma_f32 v240, v140, v240, v156
	v_fma_f32 v244, v141, v244, v157
	v_lshlrev_b32_e32 v241, 16, v191
	v_and_b32_e32 v245, 0xffff0000, v191
	v_lshlrev_b32_e32 v243, 16, v199
	v_and_b32_e32 v246, 0xffff0000, v199
	v_cndmask_b32_e32 v243, v243, v212, vcc
	v_cndmask_b32_e32 v246, v246, v213, vcc
	v_sub_f32_e32 v243, v243, v241
	v_sub_f32_e32 v246, v246, v245
	v_fmac_f32_e32 v241, v172, v243
	v_fmac_f32_e32 v245, v173, v246
	v_fmac_f32_e32 v240, v234, v241
	v_fmac_f32_e32 v244, v234, v245
	v_mul_f32_e32 v58, v58, v240
	v_mul_f32_e32 v59, v59, v244
	v_lshlrev_b32_e32 v240, 16, v184
	v_and_b32_e32 v244, 0xffff0000, v184
	v_sub_f32_e32 v240, v240, v238
	v_sub_f32_e32 v244, v244, v238
	v_mul_f32_e32 v240, v240, v239
	v_mul_f32_e32 v244, v244, v239
	v_fma_f32 v240, v142, v240, v158
	v_fma_f32 v244, v143, v244, v159
	v_lshlrev_b32_e32 v241, 16, v192
	v_and_b32_e32 v245, 0xffff0000, v192
	v_lshlrev_b32_e32 v243, 16, v200
	v_and_b32_e32 v246, 0xffff0000, v200
	v_cndmask_b32_e32 v243, v243, v214, vcc
	v_cndmask_b32_e32 v246, v246, v215, vcc
	v_sub_f32_e32 v243, v243, v241
	v_sub_f32_e32 v246, v246, v245
	v_fmac_f32_e32 v241, v174, v243
	v_fmac_f32_e32 v245, v175, v246
	v_fmac_f32_e32 v240, v234, v241
	v_fmac_f32_e32 v244, v234, v245
	v_mul_f32_e32 v60, v60, v240
	v_mul_f32_e32 v61, v61, v244
	v_lshlrev_b32_e32 v240, 16, v185
	v_and_b32_e32 v244, 0xffff0000, v185
	v_sub_f32_e32 v240, v240, v238
	v_sub_f32_e32 v244, v244, v238
	v_mul_f32_e32 v240, v240, v239
	v_mul_f32_e32 v244, v244, v239
	v_fma_f32 v240, v144, v240, v160
	v_fma_f32 v244, v145, v244, v161
	v_lshlrev_b32_e32 v241, 16, v193
	v_and_b32_e32 v245, 0xffff0000, v193
	v_lshlrev_b32_e32 v243, 16, v201
	v_and_b32_e32 v246, 0xffff0000, v201
	v_cndmask_b32_e32 v243, v243, v216, vcc
	v_cndmask_b32_e32 v246, v246, v217, vcc
	v_sub_f32_e32 v243, v243, v241
	v_sub_f32_e32 v246, v246, v245
	v_fmac_f32_e32 v241, v176, v243
	v_fmac_f32_e32 v245, v177, v246
	v_fmac_f32_e32 v240, v234, v241
	v_fmac_f32_e32 v244, v234, v245
	v_mul_f32_e32 v62, v62, v240
	v_mul_f32_e32 v63, v63, v244
	v_cvt_pk_bf16_f32 v56, v56, v57
	v_cvt_pk_bf16_f32 v57, v58, v59
	v_cvt_pk_bf16_f32 v58, v60, v61
	v_cvt_pk_bf16_f32 v59, v62, v63
	v_add_u32_e32 v236, 0x8000, v230
	s_nop 0
	global_store_dwordx4 v236, v[56:59], s[22:23] offset:192
	v_add_u32_e32 v236, 0x10000, v230
	v_add_u32_e32 v237, 0x2c000, v231
	v_subrev_u32_e32 v240, 0x1600, v237
	global_load_dwordx4 v[178:181], v236, s[22:23] offset:128 sc0
	global_load_dwordx4 v[182:185], v236, s[22:23] offset:192 sc0
	global_load_dwordx4 v[186:189], v237, s[96:97] offset:128 sc0
	global_load_dwordx4 v[190:193], v237, s[96:97] offset:192 sc0
	global_load_dwordx4 v[194:197], v240, s[96:97] offset:128 sc0
	global_load_dwordx4 v[198:201], v240, s[96:97] offset:192 sc0
	v_add_u32_e32 v236, 0x1800, v232
	s_nop 0
	global_load_dword v234, v236, s[96:97] offset:16
	v_add_u32_e32 v237, 0x14000, v247
	global_load_dwordx4 v[202:205], v237, s[20:21] offset:256 sc0
	global_load_dwordx4 v[206:209], v237, s[20:21] offset:272 sc0
	global_load_dwordx4 v[210:213], v237, s[20:21] offset:384 sc0
	global_load_dwordx4 v[214:217], v237, s[20:21] offset:400 sc0
	s_waitcnt vmcnt(0)
; __device__ __forceinline__ float bf2f(u16 h) { return __uint_as_float(((unsigned)h) << 16); }
; __device__ __forceinline__ float prevP(const Params& p, const u16* P, int row, int c) {
;     ...
;   const bool start = (row < NP) ? ((row & 2047) == 0) : (((row - NP) & 3) == 0);
;   if (start) v = (row < NP) ? 0.f : p.in[3][(size_t)((row - NP) >> 2) * 2560 + c];
; template <int EPI> ...
;     ...
;       for (int i = 0; i < 16; i++) {
;         const int rl = rbase + (i & 3) + 8 * (i >> 2);
;         const int row = m0 + rl;
;         float o0 = bf2f(Y[(size_t)row * 1024 + 256 + ch0]);
;         float o1 = bf2f(Y[(size_t)row * 1024 + 256 + ch1]);
;         float mean = hsum32(o0 + o1) * (1.0f / 64.0f);
;         float d0 = o0 - mean, d1 = o1 - mean;
;         float var = hsum32(d0 * d0 + d1 * d1) * (1.0f / 64.0f);
;         float rstd = rsqrtf(var + 64e-5f);
;         float pv0 = bf2f(P[(size_t)row * 2816 + 256 + 1536 + ch0]);
;         float pv1 = bf2f(P[(size_t)row * 2816 + 256 + 1536 + ch1]);
;         float pp0 = prevP(p, P, row, 1536 + ch0), pp1 = prevP(p, P, row, 1536 + ch1);
;         float vv0 = pv0 + (pp0 - pv0) * mu0, vv1 = pv1 + (pp1 - pv1) * mu1;
;         float b = bs[((size_t)row * 12 + hh) * 4 + 2];
;         float y0 = (d0 * rstd * gg0 + gb0 + b * vv0) * acc0[i];
;         float y1 = (d1 * rstd * gg1 + gb1 + b * vv1) * acc1[i];
;         Y[(size_t)row * 1024 + 256 + ch0] = f2bf(y0);
;         Y[(size_t)row * 1024 + 256 + ch1] = f2bf(y1);
	v_lshlrev_b32_e32 v240, 16, v178
	v_and_b32_e32 v241, 0xffff0000, v178
	v_add_f32_e32 v244, v240, v241
	v_lshlrev_b32_e32 v240, 16, v179
	v_and_b32_e32 v241, 0xffff0000, v179
	v_add_f32_e32 v244, v244, v240
	v_add_f32_e32 v244, v244, v241
	v_lshlrev_b32_e32 v240, 16, v180
	v_and_b32_e32 v241, 0xffff0000, v180
	v_add_f32_e32 v244, v244, v240
	v_add_f32_e32 v244, v244, v241
	v_lshlrev_b32_e32 v240, 16, v181
	v_and_b32_e32 v241, 0xffff0000, v181
	v_add_f32_e32 v244, v244, v240
	v_add_f32_e32 v244, v244, v241
	v_lshlrev_b32_e32 v240, 16, v182
	v_and_b32_e32 v241, 0xffff0000, v182
	v_add_f32_e32 v244, v244, v240
	v_add_f32_e32 v244, v244, v241
	v_lshlrev_b32_e32 v240, 16, v183
	v_and_b32_e32 v241, 0xffff0000, v183
	v_add_f32_e32 v244, v244, v240
	v_add_f32_e32 v244, v244, v241
	v_lshlrev_b32_e32 v240, 16, v184
	v_and_b32_e32 v241, 0xffff0000, v184
	v_add_f32_e32 v244, v244, v240
	v_add_f32_e32 v244, v244, v241
	v_lshlrev_b32_e32 v240, 16, v185
	v_and_b32_e32 v241, 0xffff0000, v185
	v_add_f32_e32 v244, v244, v240
	v_add_f32_e32 v244, v244, v241
	v_mov_b32_e32 v240, v244
	s_nop 1
	v_permlane16_swap_b32_e32 v240, v244
	v_add_f32_e32 v244, v244, v240
	v_mov_b32_e32 v240, v244
	s_nop 1
	v_permlane32_swap_b32_e32 v240, v244
	v_add_f32_e32 v244, v244, v240
	v_mul_f32_e32 v238, 0x3c800000, v244
	v_lshlrev_b32_e32 v240, 16, v178
	v_and_b32_e32 v241, 0xffff0000, v178
	v_sub_f32_e32 v240, v240, v238
	v_sub_f32_e32 v241, v241, v238
	v_mul_f32_e32 v245, v240, v240
	v_fmac_f32_e32 v245, v241, v241
	v_lshlrev_b32_e32 v240, 16, v179
	v_and_b32_e32 v241, 0xffff0000, v179
	v_sub_f32_e32 v240, v240, v238
	v_sub_f32_e32 v241, v241, v238
	v_fmac_f32_e32 v245, v240, v240
	v_fmac_f32_e32 v245, v241, v241
	v_lshlrev_b32_e32 v240, 16, v180
	v_and_b32_e32 v241, 0xffff0000, v180
	v_sub_f32_e32 v240, v240, v238
	v_sub_f32_e32 v241, v241, v238
	v_fmac_f32_e32 v245, v240, v240
	v_fmac_f32_e32 v245, v241, v241
	v_lshlrev_b32_e32 v240, 16, v181
	v_and_b32_e32 v241, 0xffff0000, v181
	v_sub_f32_e32 v240, v240, v238
	v_sub_f32_e32 v241, v241, v238
	v_fmac_f32_e32 v245, v240, v240
	v_fmac_f32_e32 v245, v241, v241
	v_lshlrev_b32_e32 v240, 16, v182
	v_and_b32_e32 v241, 0xffff0000, v182
	v_sub_f32_e32 v240, v240, v238
	v_sub_f32_e32 v241, v241, v238
	v_fmac_f32_e32 v245, v240, v240
	v_fmac_f32_e32 v245, v241, v241
	v_lshlrev_b32_e32 v240, 16, v183
	v_and_b32_e32 v241, 0xffff0000, v183
	v_sub_f32_e32 v240, v240, v238
	v_sub_f32_e32 v241, v241, v238
	v_fmac_f32_e32 v245, v240, v240
	v_fmac_f32_e32 v245, v241, v241
	v_lshlrev_b32_e32 v240, 16, v184
	v_and_b32_e32 v241, 0xffff0000, v184
	v_sub_f32_e32 v240, v240, v238
	v_sub_f32_e32 v241, v241, v238
	v_fmac_f32_e32 v245, v240, v240
	v_fmac_f32_e32 v245, v241, v241
	v_lshlrev_b32_e32 v240, 16, v185
	v_and_b32_e32 v241, 0xffff0000, v185
	v_sub_f32_e32 v240, v240, v238
	v_sub_f32_e32 v241, v241, v238
	v_fmac_f32_e32 v245, v240, v240
	v_fmac_f32_e32 v245, v241, v241
	v_mov_b32_e32 v240, v245
	s_nop 1
	v_permlane16_swap_b32_e32 v240, v245
	v_add_f32_e32 v245, v245, v240
	v_mov_b32_e32 v240, v245
	s_nop 1
	v_permlane32_swap_b32_e32 v240, v245
	v_add_f32_e32 v245, v245, v240
	v_mov_b32_e32 v240, 0x3a27c5ac
	v_fmamk_f32 v245, v245, 0x3c800000, v240
	v_rsq_f32_e32 v239, v245
	v_and_b32_e32 v240, 3, v248
	v_cmp_eq_u32_e32 vcc, 0, v240
	s_nop 1
	v_lshlrev_b32_e32 v240, 16, v178
	v_and_b32_e32 v244, 0xffff0000, v178
	v_sub_f32_e32 v240, v240, v238
	v_sub_f32_e32 v244, v244, v238
	v_mul_f32_e32 v240, v240, v239
	v_mul_f32_e32 v244, v244, v239
	v_fma_f32 v240, v130, v240, v146
	v_fma_f32 v244, v131, v244, v147
	v_lshlrev_b32_e32 v241, 16, v186
	v_and_b32_e32 v245, 0xffff0000, v186
	v_lshlrev_b32_e32 v243, 16, v194
	v_and_b32_e32 v246, 0xffff0000, v194
	v_cndmask_b32_e32 v243, v243, v202, vcc
	v_cndmask_b32_e32 v246, v246, v203, vcc
	v_sub_f32_e32 v243, v243, v241
	v_sub_f32_e32 v246, v246, v245
	v_fmac_f32_e32 v241, v162, v243
	v_fmac_f32_e32 v245, v163, v246
	v_fmac_f32_e32 v240, v234, v241
	v_fmac_f32_e32 v244, v234, v245
	v_mul_f32_e32 v80, v80, v240
	v_mul_f32_e32 v81, v81, v244
	v_lshlrev_b32_e32 v240, 16, v179
	v_and_b32_e32 v244, 0xffff0000, v179
	v_sub_f32_e32 v240, v240, v238
	v_sub_f32_e32 v244, v244, v238
	v_mul_f32_e32 v240, v240, v239
	v_mul_f32_e32 v244, v244, v239
	v_fma_f32 v240, v132, v240, v148
	v_fma_f32 v244, v133, v244, v149
	v_lshlrev_b32_e32 v241, 16, v187
	v_and_b32_e32 v245, 0xffff0000, v187
	v_lshlrev_b32_e32 v243, 16, v195
	v_and_b32_e32 v246, 0xffff0000, v195
	v_cndmask_b32_e32 v243, v243, v204, vcc
	v_cndmask_b32_e32 v246, v246, v205, vcc
	v_sub_f32_e32 v243, v243, v241
	v_sub_f32_e32 v246, v246, v245
	v_fmac_f32_e32 v241, v164, v243
	v_fmac_f32_e32 v245, v165, v246
	v_fmac_f32_e32 v240, v234, v241
	v_fmac_f32_e32 v244, v234, v245
	v_mul_f32_e32 v82, v82, v240
	v_mul_f32_e32 v83, v83, v244
	v_lshlrev_b32_e32 v240, 16, v180
	v_and_b32_e32 v244, 0xffff0000, v180
	v_sub_f32_e32 v240, v240, v238
	v_sub_f32_e32 v244, v244, v238
	v_mul_f32_e32 v240, v240, v239
	v_mul_f32_e32 v244, v244, v239
	v_fma_f32 v240, v134, v240, v150
	v_fma_f32 v244, v135, v244, v151
	v_lshlrev_b32_e32 v241, 16, v188
	v_and_b32_e32 v245, 0xffff0000, v188
	v_lshlrev_b32_e32 v243, 16, v196
	v_and_b32_e32 v246, 0xffff0000, v196
	v_cndmask_b32_e32 v243, v243, v206, vcc
	v_cndmask_b32_e32 v246, v246, v207, vcc
	v_sub_f32_e32 v243, v243, v241
	v_sub_f32_e32 v246, v246, v245
	v_fmac_f32_e32 v241, v166, v243
	v_fmac_f32_e32 v245, v167, v246
	v_fmac_f32_e32 v240, v234, v241
	v_fmac_f32_e32 v244, v234, v245
	v_mul_f32_e32 v84, v84, v240
	v_mul_f32_e32 v85, v85, v244
	v_lshlrev_b32_e32 v240, 16, v181
	v_and_b32_e32 v244, 0xffff0000, v181
	v_sub_f32_e32 v240, v240, v238
; __device__ __forceinline__ float bf2f(u16 h) { return __uint_as_float(((unsigned)h) << 16); }
; template <int EPI> ...
;     ...
;       for (int i = 0; i < 16; i++) {
;         const int rl = rbase + (i & 3) + 8 * (i >> 2);
;         const int row = m0 + rl;
;         float o0 = bf2f(Y[(size_t)row * 1024 + 256 + ch0]);
;         float o1 = bf2f(Y[(size_t)row * 1024 + 256 + ch1]);
;         float mean = hsum32(o0 + o1) * (1.0f / 64.0f);
;         float d0 = o0 - mean, d1 = o1 - mean;
;         float var = hsum32(d0 * d0 + d1 * d1) * (1.0f / 64.0f);
;         float rstd = rsqrtf(var + 64e-5f);
;         float pv0 = bf2f(P[(size_t)row * 2816 + 256 + 1536 + ch0]);
;         float pv1 = bf2f(P[(size_t)row * 2816 + 256 + 1536 + ch1]);
;         float pp0 = prevP(p, P, row, 1536 + ch0), pp1 = prevP(p, P, row, 1536 + ch1);
;         float vv0 = pv0 + (pp0 - pv0) * mu0, vv1 = pv1 + (pp1 - pv1) * mu1;
;         float b = bs[((size_t)row * 12 + hh) * 4 + 2];
;         float y0 = (d0 * rstd * gg0 + gb0 + b * vv0) * acc0[i];
;         float y1 = (d1 * rstd * gg1 + gb1 + b * vv1) * acc1[i];
;         Y[(size_t)row * 1024 + 256 + ch0] = f2bf(y0);
;         Y[(size_t)row * 1024 + 256 + ch1] = f2bf(y1);
;       }
	v_sub_f32_e32 v244, v244, v238
	v_mul_f32_e32 v240, v240, v239
	v_mul_f32_e32 v244, v244, v239
	v_fma_f32 v240, v136, v240, v152
	v_fma_f32 v244, v137, v244, v153
	v_lshlrev_b32_e32 v241, 16, v189
	v_and_b32_e32 v245, 0xffff0000, v189
	v_lshlrev_b32_e32 v243, 16, v197
	v_and_b32_e32 v246, 0xffff0000, v197
	v_cndmask_b32_e32 v243, v243, v208, vcc
	v_cndmask_b32_e32 v246, v246, v209, vcc
	v_sub_f32_e32 v243, v243, v241
	v_sub_f32_e32 v246, v246, v245
	v_fmac_f32_e32 v241, v168, v243
	v_fmac_f32_e32 v245, v169, v246
	v_fmac_f32_e32 v240, v234, v241
	v_fmac_f32_e32 v244, v234, v245
	v_mul_f32_e32 v86, v86, v240
	v_mul_f32_e32 v87, v87, v244
	v_cvt_pk_bf16_f32 v80, v80, v81
	v_cvt_pk_bf16_f32 v81, v82, v83
	v_cvt_pk_bf16_f32 v82, v84, v85
	v_cvt_pk_bf16_f32 v83, v86, v87
	v_add_u32_e32 v236, 0x10000, v230
	s_nop 0
	global_store_dwordx4 v236, v[80:83], s[22:23] offset:128
	v_lshlrev_b32_e32 v240, 16, v182
	v_and_b32_e32 v244, 0xffff0000, v182
	v_sub_f32_e32 v240, v240, v238
	v_sub_f32_e32 v244, v244, v238
	v_mul_f32_e32 v240, v240, v239
	v_mul_f32_e32 v244, v244, v239
	v_fma_f32 v240, v138, v240, v154
	v_fma_f32 v244, v139, v244, v155
	v_lshlrev_b32_e32 v241, 16, v190
	v_and_b32_e32 v245, 0xffff0000, v190
	v_lshlrev_b32_e32 v243, 16, v198
	v_and_b32_e32 v246, 0xffff0000, v198
	v_cndmask_b32_e32 v243, v243, v210, vcc
	v_cndmask_b32_e32 v246, v246, v211, vcc
	v_sub_f32_e32 v243, v243, v241
	v_sub_f32_e32 v246, v246, v245
	v_fmac_f32_e32 v241, v170, v243
	v_fmac_f32_e32 v245, v171, v246
	v_fmac_f32_e32 v240, v234, v241
	v_fmac_f32_e32 v244, v234, v245
	v_mul_f32_e32 v88, v88, v240
	v_mul_f32_e32 v89, v89, v244
	v_lshlrev_b32_e32 v240, 16, v183
	v_and_b32_e32 v244, 0xffff0000, v183
	v_sub_f32_e32 v240, v240, v238
	v_sub_f32_e32 v244, v244, v238
	v_mul_f32_e32 v240, v240, v239
	v_mul_f32_e32 v244, v244, v239
	v_fma_f32 v240, v140, v240, v156
	v_fma_f32 v244, v141, v244, v157
	v_lshlrev_b32_e32 v241, 16, v191
	v_and_b32_e32 v245, 0xffff0000, v191
	v_lshlrev_b32_e32 v243, 16, v199
	v_and_b32_e32 v246, 0xffff0000, v199
	v_cndmask_b32_e32 v243, v243, v212, vcc
	v_cndmask_b32_e32 v246, v246, v213, vcc
	v_sub_f32_e32 v243, v243, v241
	v_sub_f32_e32 v246, v246, v245
	v_fmac_f32_e32 v241, v172, v243
	v_fmac_f32_e32 v245, v173, v246
	v_fmac_f32_e32 v240, v234, v241
	v_fmac_f32_e32 v244, v234, v245
	v_mul_f32_e32 v90, v90, v240
	v_mul_f32_e32 v91, v91, v244
	v_lshlrev_b32_e32 v240, 16, v184
	v_and_b32_e32 v244, 0xffff0000, v184
	v_sub_f32_e32 v240, v240, v238
	v_sub_f32_e32 v244, v244, v238
	v_mul_f32_e32 v240, v240, v239
	v_mul_f32_e32 v244, v244, v239
	v_fma_f32 v240, v142, v240, v158
	v_fma_f32 v244, v143, v244, v159
	v_lshlrev_b32_e32 v241, 16, v192
	v_and_b32_e32 v245, 0xffff0000, v192
	v_lshlrev_b32_e32 v243, 16, v200
	v_and_b32_e32 v246, 0xffff0000, v200
	v_cndmask_b32_e32 v243, v243, v214, vcc
	v_cndmask_b32_e32 v246, v246, v215, vcc
	v_sub_f32_e32 v243, v243, v241
	v_sub_f32_e32 v246, v246, v245
	v_fmac_f32_e32 v241, v174, v243
	v_fmac_f32_e32 v245, v175, v246
	v_fmac_f32_e32 v240, v234, v241
	v_fmac_f32_e32 v244, v234, v245
	v_mul_f32_e32 v92, v92, v240
	v_mul_f32_e32 v93, v93, v244
	v_lshlrev_b32_e32 v240, 16, v185
	v_and_b32_e32 v244, 0xffff0000, v185
	v_sub_f32_e32 v240, v240, v238
	v_sub_f32_e32 v244, v244, v238
	v_mul_f32_e32 v240, v240, v239
	v_mul_f32_e32 v244, v244, v239
	v_fma_f32 v240, v144, v240, v160
	v_fma_f32 v244, v145, v244, v161
	v_lshlrev_b32_e32 v241, 16, v193
	v_and_b32_e32 v245, 0xffff0000, v193
	v_lshlrev_b32_e32 v243, 16, v201
	v_and_b32_e32 v246, 0xffff0000, v201
	v_cndmask_b32_e32 v243, v243, v216, vcc
	v_cndmask_b32_e32 v246, v246, v217, vcc
	v_sub_f32_e32 v243, v243, v241
	v_sub_f32_e32 v246, v246, v245
	v_fmac_f32_e32 v241, v176, v243
	v_fmac_f32_e32 v245, v177, v246
	v_fmac_f32_e32 v240, v234, v241
	v_fmac_f32_e32 v244, v234, v245
	v_mul_f32_e32 v94, v94, v240
	v_mul_f32_e32 v95, v95, v244
	v_cvt_pk_bf16_f32 v88, v88, v89
	v_cvt_pk_bf16_f32 v89, v90, v91
	v_cvt_pk_bf16_f32 v90, v92, v93
	v_cvt_pk_bf16_f32 v91, v94, v95
	v_add_u32_e32 v236, 0x10000, v230
	s_nop 0
	global_store_dwordx4 v236, v[88:91], s[22:23] offset:192
	v_add_u32_e32 v236, 0x18000, v230
	v_add_u32_e32 v237, 0x42000, v231
	v_subrev_u32_e32 v240, 0x1600, v237
	global_load_dwordx4 v[178:181], v236, s[22:23] offset:128 sc0
	global_load_dwordx4 v[182:185], v236, s[22:23] offset:192 sc0
	global_load_dwordx4 v[186:189], v237, s[96:97] offset:128 sc0
	global_load_dwordx4 v[190:193], v237, s[96:97] offset:192 sc0
	global_load_dwordx4 v[194:197], v240, s[96:97] offset:128 sc0
	global_load_dwordx4 v[198:201], v240, s[96:97] offset:192 sc0
	v_add_u32_e32 v236, 0x2400, v232
	s_nop 0
	global_load_dword v234, v236, s[96:97] offset:16
	v_add_u32_e32 v237, 0x1e000, v247
	global_load_dwordx4 v[202:205], v237, s[20:21] offset:256 sc0
	global_load_dwordx4 v[206:209], v237, s[20:21] offset:272 sc0
	global_load_dwordx4 v[210:213], v237, s[20:21] offset:384 sc0
	global_load_dwordx4 v[214:217], v237, s[20:21] offset:400 sc0
	s_waitcnt vmcnt(0)
; __device__ __forceinline__ float bf2f(u16 h) { return __uint_as_float(((unsigned)h) << 16); }
; template <int EPI> ...
;     ...
;       for (int i = 0; i < 16; i++) {
;         const int rl = rbase + (i & 3) + 8 * (i >> 2);
;         const int row = m0 + rl;
;         float o0 = bf2f(Y[(size_t)row * 1024 + 256 + ch0]);
;         float o1 = bf2f(Y[(size_t)row * 1024 + 256 + ch1]);
;         float mean = hsum32(o0 + o1) * (1.0f / 64.0f);
;         float d0 = o0 - mean, d1 = o1 - mean;
;         float var = hsum32(d0 * d0 + d1 * d1) * (1.0f / 64.0f);
;         float rstd = rsqrtf(var + 64e-5f);
;         float pv0 = bf2f(P[(size_t)row * 2816 + 256 + 1536 + ch0]);
;         float pv1 = bf2f(P[(size_t)row * 2816 + 256 + 1536 + ch1]);
;         float pp0 = prevP(p, P, row, 1536 + ch0), pp1 = prevP(p, P, row, 1536 + ch1);
;         float vv0 = pv0 + (pp0 - pv0) * mu0, vv1 = pv1 + (pp1 - pv1) * mu1;
;         float b = bs[((size_t)row * 12 + hh) * 4 + 2];
;         float y0 = (d0 * rstd * gg0 + gb0 + b * vv0) * acc0[i];
;         float y1 = (d1 * rstd * gg1 + gb1 + b * vv1) * acc1[i];
;         Y[(size_t)row * 1024 + 256 + ch0] = f2bf(y0);
;         Y[(size_t)row * 1024 + 256 + ch1] = f2bf(y1);
;       }
	v_lshlrev_b32_e32 v240, 16, v178
	v_and_b32_e32 v241, 0xffff0000, v178
	v_add_f32_e32 v244, v240, v241
	v_lshlrev_b32_e32 v240, 16, v179
	v_and_b32_e32 v241, 0xffff0000, v179
	v_add_f32_e32 v244, v244, v240
	v_add_f32_e32 v244, v244, v241
	v_lshlrev_b32_e32 v240, 16, v180
	v_and_b32_e32 v241, 0xffff0000, v180
	v_add_f32_e32 v244, v244, v240
	v_add_f32_e32 v244, v244, v241
	v_lshlrev_b32_e32 v240, 16, v181
	v_and_b32_e32 v241, 0xffff0000, v181
	v_add_f32_e32 v244, v244, v240
	v_add_f32_e32 v244, v244, v241
	v_lshlrev_b32_e32 v240, 16, v182
	v_and_b32_e32 v241, 0xffff0000, v182
	v_add_f32_e32 v244, v244, v240
	v_add_f32_e32 v244, v244, v241
	v_lshlrev_b32_e32 v240, 16, v183
	v_and_b32_e32 v241, 0xffff0000, v183
	v_add_f32_e32 v244, v244, v240
	v_add_f32_e32 v244, v244, v241
	v_lshlrev_b32_e32 v240, 16, v184
	v_and_b32_e32 v241, 0xffff0000, v184
	v_add_f32_e32 v244, v244, v240
	v_add_f32_e32 v244, v244, v241
	v_lshlrev_b32_e32 v240, 16, v185
	v_and_b32_e32 v241, 0xffff0000, v185
	v_add_f32_e32 v244, v244, v240
	v_add_f32_e32 v244, v244, v241
	v_mov_b32_e32 v240, v244
	s_nop 1
	v_permlane16_swap_b32_e32 v240, v244
	v_add_f32_e32 v244, v244, v240
	v_mov_b32_e32 v240, v244
	s_nop 1
	v_permlane32_swap_b32_e32 v240, v244
	v_add_f32_e32 v244, v244, v240
	v_mul_f32_e32 v238, 0x3c800000, v244
	v_lshlrev_b32_e32 v240, 16, v178
	v_and_b32_e32 v241, 0xffff0000, v178
	v_sub_f32_e32 v240, v240, v238
	v_sub_f32_e32 v241, v241, v238
	v_mul_f32_e32 v245, v240, v240
	v_fmac_f32_e32 v245, v241, v241
	v_lshlrev_b32_e32 v240, 16, v179
	v_and_b32_e32 v241, 0xffff0000, v179
	v_sub_f32_e32 v240, v240, v238
	v_sub_f32_e32 v241, v241, v238
	v_fmac_f32_e32 v245, v240, v240
	v_fmac_f32_e32 v245, v241, v241
	v_lshlrev_b32_e32 v240, 16, v180
	v_and_b32_e32 v241, 0xffff0000, v180
	v_sub_f32_e32 v240, v240, v238
	v_sub_f32_e32 v241, v241, v238
	v_fmac_f32_e32 v245, v240, v240
	v_fmac_f32_e32 v245, v241, v241
	v_lshlrev_b32_e32 v240, 16, v181
	v_and_b32_e32 v241, 0xffff0000, v181
	v_sub_f32_e32 v240, v240, v238
	v_sub_f32_e32 v241, v241, v238
	v_fmac_f32_e32 v245, v240, v240
	v_fmac_f32_e32 v245, v241, v241
	v_lshlrev_b32_e32 v240, 16, v182
	v_and_b32_e32 v241, 0xffff0000, v182
	v_sub_f32_e32 v240, v240, v238
	v_sub_f32_e32 v241, v241, v238
	v_fmac_f32_e32 v245, v240, v240
	v_fmac_f32_e32 v245, v241, v241
	v_lshlrev_b32_e32 v240, 16, v183
	v_and_b32_e32 v241, 0xffff0000, v183
	v_sub_f32_e32 v240, v240, v238
	v_sub_f32_e32 v241, v241, v238
	v_fmac_f32_e32 v245, v240, v240
	v_fmac_f32_e32 v245, v241, v241
	v_lshlrev_b32_e32 v240, 16, v184
	v_and_b32_e32 v241, 0xffff0000, v184
	v_sub_f32_e32 v240, v240, v238
	v_sub_f32_e32 v241, v241, v238
	v_fmac_f32_e32 v245, v240, v240
	v_fmac_f32_e32 v245, v241, v241
	v_lshlrev_b32_e32 v240, 16, v185
	v_and_b32_e32 v241, 0xffff0000, v185
	v_sub_f32_e32 v240, v240, v238
	v_sub_f32_e32 v241, v241, v238
	v_fmac_f32_e32 v245, v240, v240
	v_fmac_f32_e32 v245, v241, v241
	v_mov_b32_e32 v240, v245
	s_nop 1
	v_permlane16_swap_b32_e32 v240, v245
	v_add_f32_e32 v245, v245, v240
	v_mov_b32_e32 v240, v245
	s_nop 1
	v_permlane32_swap_b32_e32 v240, v245
	v_add_f32_e32 v245, v245, v240
	v_mov_b32_e32 v240, 0x3a27c5ac
	v_fmamk_f32 v245, v245, 0x3c800000, v240
	v_rsq_f32_e32 v239, v245
	v_and_b32_e32 v240, 3, v248
	v_cmp_eq_u32_e32 vcc, 0, v240
	s_nop 1
	v_lshlrev_b32_e32 v240, 16, v178
	v_and_b32_e32 v244, 0xffff0000, v178
	v_sub_f32_e32 v240, v240, v238
	v_sub_f32_e32 v244, v244, v238
	v_mul_f32_e32 v240, v240, v239
	v_mul_f32_e32 v244, v244, v239
	v_fma_f32 v240, v130, v240, v146
	v_fma_f32 v244, v131, v244, v147
	v_lshlrev_b32_e32 v241, 16, v186
	v_and_b32_e32 v245, 0xffff0000, v186
	v_lshlrev_b32_e32 v243, 16, v194
	v_and_b32_e32 v246, 0xffff0000, v194
	v_cndmask_b32_e32 v243, v243, v202, vcc
	v_cndmask_b32_e32 v246, v246, v203, vcc
	v_sub_f32_e32 v243, v243, v241
	v_sub_f32_e32 v246, v246, v245
	v_fmac_f32_e32 v241, v162, v243
	v_fmac_f32_e32 v245, v163, v246
	v_fmac_f32_e32 v240, v234, v241
	v_fmac_f32_e32 v244, v234, v245
	v_mul_f32_e32 v112, v112, v240
	v_mul_f32_e32 v113, v113, v244
	v_lshlrev_b32_e32 v240, 16, v179
	v_and_b32_e32 v244, 0xffff0000, v179
	v_sub_f32_e32 v240, v240, v238
	v_sub_f32_e32 v244, v244, v238
	v_mul_f32_e32 v240, v240, v239
	v_mul_f32_e32 v244, v244, v239
	v_fma_f32 v240, v132, v240, v148
	v_fma_f32 v244, v133, v244, v149
	v_lshlrev_b32_e32 v241, 16, v187
	v_and_b32_e32 v245, 0xffff0000, v187
	v_lshlrev_b32_e32 v243, 16, v195
	v_and_b32_e32 v246, 0xffff0000, v195
	v_cndmask_b32_e32 v243, v243, v204, vcc
	v_cndmask_b32_e32 v246, v246, v205, vcc
	v_sub_f32_e32 v243, v243, v241
	v_sub_f32_e32 v246, v246, v245
	v_fmac_f32_e32 v241, v164, v243
	v_fmac_f32_e32 v245, v165, v246
	v_fmac_f32_e32 v240, v234, v241
	v_fmac_f32_e32 v244, v234, v245
	v_mul_f32_e32 v114, v114, v240
	v_mul_f32_e32 v115, v115, v244
	v_lshlrev_b32_e32 v240, 16, v180
	v_and_b32_e32 v244, 0xffff0000, v180
	v_sub_f32_e32 v240, v240, v238
; __device__ __forceinline__ float bf2f(u16 h) { return __uint_as_float(((unsigned)h) << 16); }
; template <int EPI> ...
;     ...
;         float pv0 = bf2f(P[(size_t)row * 2816 + 256 + 1536 + ch0]);
;         float pv1 = bf2f(P[(size_t)row * 2816 + 256 + 1536 + ch1]);
;         float pp0 = prevP(p, P, row, 1536 + ch0), pp1 = prevP(p, P, row, 1536 + ch1);
;         float vv0 = pv0 + (pp0 - pv0) * mu0, vv1 = pv1 + (pp1 - pv1) * mu1;
;         float b = bs[((size_t)row * 12 + hh) * 4 + 2];
;         float y0 = (d0 * rstd * gg0 + gb0 + b * vv0) * acc0[i];
;         float y1 = (d1 * rstd * gg1 + gb1 + b * vv1) * acc1[i];
;         Y[(size_t)row * 1024 + 256 + ch0] = f2bf(y0);
;         Y[(size_t)row * 1024 + 256 + ch1] = f2bf(y1);
;       }
	v_sub_f32_e32 v244, v244, v238
	v_mul_f32_e32 v240, v240, v239
	v_mul_f32_e32 v244, v244, v239
	v_fma_f32 v240, v134, v240, v150
	v_fma_f32 v244, v135, v244, v151
	v_lshlrev_b32_e32 v241, 16, v188
	v_and_b32_e32 v245, 0xffff0000, v188
	v_lshlrev_b32_e32 v243, 16, v196
	v_and_b32_e32 v246, 0xffff0000, v196
	v_cndmask_b32_e32 v243, v243, v206, vcc
	v_cndmask_b32_e32 v246, v246, v207, vcc
	v_sub_f32_e32 v243, v243, v241
	v_sub_f32_e32 v246, v246, v245
	v_fmac_f32_e32 v241, v166, v243
	v_fmac_f32_e32 v245, v167, v246
	v_fmac_f32_e32 v240, v234, v241
	v_fmac_f32_e32 v244, v234, v245
	v_mul_f32_e32 v116, v116, v240
	v_mul_f32_e32 v117, v117, v244
	v_lshlrev_b32_e32 v240, 16, v181
	v_and_b32_e32 v244, 0xffff0000, v181
	v_sub_f32_e32 v240, v240, v238
	v_sub_f32_e32 v244, v244, v238
	v_mul_f32_e32 v240, v240, v239
	v_mul_f32_e32 v244, v244, v239
	v_fma_f32 v240, v136, v240, v152
	v_fma_f32 v244, v137, v244, v153
	v_lshlrev_b32_e32 v241, 16, v189
	v_and_b32_e32 v245, 0xffff0000, v189
	v_lshlrev_b32_e32 v243, 16, v197
	v_and_b32_e32 v246, 0xffff0000, v197
	v_cndmask_b32_e32 v243, v243, v208, vcc
	v_cndmask_b32_e32 v246, v246, v209, vcc
	v_sub_f32_e32 v243, v243, v241
	v_sub_f32_e32 v246, v246, v245
	v_fmac_f32_e32 v241, v168, v243
	v_fmac_f32_e32 v245, v169, v246
	v_fmac_f32_e32 v240, v234, v241
	v_fmac_f32_e32 v244, v234, v245
	v_mul_f32_e32 v118, v118, v240
	v_mul_f32_e32 v119, v119, v244
	v_cvt_pk_bf16_f32 v112, v112, v113
	v_cvt_pk_bf16_f32 v113, v114, v115
	v_cvt_pk_bf16_f32 v114, v116, v117
	v_cvt_pk_bf16_f32 v115, v118, v119
	v_add_u32_e32 v236, 0x18000, v230
	s_nop 0
	global_store_dwordx4 v236, v[112:115], s[22:23] offset:128
	v_lshlrev_b32_e32 v240, 16, v182
	v_and_b32_e32 v244, 0xffff0000, v182
	v_sub_f32_e32 v240, v240, v238
	v_sub_f32_e32 v244, v244, v238
	v_mul_f32_e32 v240, v240, v239
	v_mul_f32_e32 v244, v244, v239
	v_fma_f32 v240, v138, v240, v154
	v_fma_f32 v244, v139, v244, v155
	v_lshlrev_b32_e32 v241, 16, v190
	v_and_b32_e32 v245, 0xffff0000, v190
	v_lshlrev_b32_e32 v243, 16, v198
	v_and_b32_e32 v246, 0xffff0000, v198
	v_cndmask_b32_e32 v243, v243, v210, vcc
	v_cndmask_b32_e32 v246, v246, v211, vcc
	v_sub_f32_e32 v243, v243, v241
	v_sub_f32_e32 v246, v246, v245
	v_fmac_f32_e32 v241, v170, v243
	v_fmac_f32_e32 v245, v171, v246
	v_fmac_f32_e32 v240, v234, v241
	v_fmac_f32_e32 v244, v234, v245
	v_mul_f32_e32 v120, v120, v240
	v_mul_f32_e32 v121, v121, v244
	v_lshlrev_b32_e32 v240, 16, v183
	v_and_b32_e32 v244, 0xffff0000, v183
	v_sub_f32_e32 v240, v240, v238
	v_sub_f32_e32 v244, v244, v238
	v_mul_f32_e32 v240, v240, v239
	v_mul_f32_e32 v244, v244, v239
	v_fma_f32 v240, v140, v240, v156
	v_fma_f32 v244, v141, v244, v157
	v_lshlrev_b32_e32 v241, 16, v191
	v_and_b32_e32 v245, 0xffff0000, v191
	v_lshlrev_b32_e32 v243, 16, v199
	v_and_b32_e32 v246, 0xffff0000, v199
	v_cndmask_b32_e32 v243, v243, v212, vcc
	v_cndmask_b32_e32 v246, v246, v213, vcc
	v_sub_f32_e32 v243, v243, v241
	v_sub_f32_e32 v246, v246, v245
	v_fmac_f32_e32 v241, v172, v243
	v_fmac_f32_e32 v245, v173, v246
	v_fmac_f32_e32 v240, v234, v241
	v_fmac_f32_e32 v244, v234, v245
	v_mul_f32_e32 v122, v122, v240
	v_mul_f32_e32 v123, v123, v244
	v_lshlrev_b32_e32 v240, 16, v184
	v_and_b32_e32 v244, 0xffff0000, v184
	v_sub_f32_e32 v240, v240, v238
	v_sub_f32_e32 v244, v244, v238
	v_mul_f32_e32 v240, v240, v239
	v_mul_f32_e32 v244, v244, v239
	v_fma_f32 v240, v142, v240, v158
	v_fma_f32 v244, v143, v244, v159
	v_lshlrev_b32_e32 v241, 16, v192
	v_and_b32_e32 v245, 0xffff0000, v192
	v_lshlrev_b32_e32 v243, 16, v200
	v_and_b32_e32 v246, 0xffff0000, v200
	v_cndmask_b32_e32 v243, v243, v214, vcc
	v_cndmask_b32_e32 v246, v246, v215, vcc
	v_sub_f32_e32 v243, v243, v241
	v_sub_f32_e32 v246, v246, v245
	v_fmac_f32_e32 v241, v174, v243
	v_fmac_f32_e32 v245, v175, v246
	v_fmac_f32_e32 v240, v234, v241
	v_fmac_f32_e32 v244, v234, v245
	v_mul_f32_e32 v124, v124, v240
	v_mul_f32_e32 v125, v125, v244
	v_lshlrev_b32_e32 v240, 16, v185
	v_and_b32_e32 v244, 0xffff0000, v185
	v_sub_f32_e32 v240, v240, v238
	v_sub_f32_e32 v244, v244, v238
	v_mul_f32_e32 v240, v240, v239
	v_mul_f32_e32 v244, v244, v239
	v_fma_f32 v240, v144, v240, v160
	v_fma_f32 v244, v145, v244, v161
	v_lshlrev_b32_e32 v241, 16, v193
	v_and_b32_e32 v245, 0xffff0000, v193
	v_lshlrev_b32_e32 v243, 16, v201
	v_and_b32_e32 v246, 0xffff0000, v201
	v_cndmask_b32_e32 v243, v243, v216, vcc
	v_cndmask_b32_e32 v246, v246, v217, vcc
	v_sub_f32_e32 v243, v243, v241
	v_sub_f32_e32 v246, v246, v245
	v_fmac_f32_e32 v241, v176, v243
	v_fmac_f32_e32 v245, v177, v246
	v_fmac_f32_e32 v240, v234, v241
	v_fmac_f32_e32 v244, v234, v245
	v_mul_f32_e32 v126, v126, v240
	v_mul_f32_e32 v127, v127, v244
	v_cvt_pk_bf16_f32 v120, v120, v121
	v_cvt_pk_bf16_f32 v121, v122, v123
	v_cvt_pk_bf16_f32 v122, v124, v125
	v_cvt_pk_bf16_f32 v123, v126, v127
	v_add_u32_e32 v236, 0x18000, v230
	s_nop 0
	global_store_dwordx4 v236, v[120:123], s[22:23] offset:192

; __device__ __forceinline__ void final_phase(const Params& p) {
;   const float* part = (const float*)(p.ws + O_PART);
;   const float* g = p.in[40];
;   const int lane = threadIdx.x & 63, wave = threadIdx.x >> 6;
;   for (int row = blockIdx.x * 8 + wave; row < MT; row += gridDim.x * 8) {
;     float s = (lane < 16) ? part[(size_t)row * 16 + lane] : 0.f;
;     s = wsum64(s);
;     const float rs = rsqrtf(s * (1.0f / 1024.0f) + 1e-6f);
;     float* xr = p.out + (size_t)row * 1024;
; #pragma unroll
;     for (int i = 0; i < 4; i++) {
;       float4 v = *(float4*)(xr + i * 256 + lane * 4);
;       float4 gg = *(const float4*)(g + i * 256 + lane * 4);
;       v.x *= rs * gg.x; v.y *= rs * gg.y; v.z *= rs * gg.z; v.w *= rs * gg.w;
;       *(float4*)(xr + i * 256 + lane * 4) = v;
.LBB0_2340:
	v_lshrrev_b32_e32 v42, 6, v128
	v_and_b32_e32 v43, 63, v128
	v_readlane_b32 s1, v254, 0
	v_readfirstlane_b32 s0, v42
	v_lshlrev_b32_e32 v40, 4, v43
	v_and_b32_e32 v44, 15, v43
	v_lshlrev_b32_e32 v41, 2, v44
	v_cmp_gt_u32_e32 vcc, 16, v43
	s_lshl_b32 s1, s1, 3
	s_add_u32 s2, s1, s0
	s_lshl_b32 s12, s42, 3
	s_add_u32 s96, s96, 0x2e00100
	s_addc_u32 s97, s97, 0
	global_load_dwordx4 v[16:19], v40, s[92:93]
	global_load_dwordx4 v[20:23], v40, s[92:93] offset:1024
	global_load_dwordx4 v[24:27], v40, s[92:93] offset:2048
	global_load_dwordx4 v[28:31], v40, s[92:93] offset:3072
	s_mov_b32 s14, s2
	s_lshl_b32 s4, s2, 12
	s_add_u32 s8, s94, s4
	s_addc_u32 s9, s95, 0
	s_lshl_b32 s4, s2, 6
	s_add_u32 s6, s96, s4
	s_addc_u32 s7, s97, 0
	global_load_dwordx4 v[0:3], v40, s[8:9] sc0
	global_load_dwordx4 v[4:7], v40, s[8:9] offset:1024 sc0
	global_load_dwordx4 v[8:11], v40, s[8:9] offset:2048 sc0
	global_load_dwordx4 v[12:15], v40, s[8:9] offset:3072 sc0
	global_load_dword v32, v41, s[6:7]
	s_add_u32 s2, s2, s12
	s_mov_b32 s15, s2
	s_lshl_b32 s4, s2, 12
	s_add_u32 s10, s94, s4
	s_addc_u32 s11, s95, 0
	s_lshl_b32 s4, s2, 6
	s_add_u32 s6, s96, s4
	s_addc_u32 s7, s97, 0
	global_load_dwordx4 v[48:51], v40, s[10:11] sc0
	global_load_dwordx4 v[52:55], v40, s[10:11] offset:1024 sc0
	global_load_dwordx4 v[56:59], v40, s[10:11] offset:2048 sc0
	global_load_dwordx4 v[60:63], v40, s[10:11] offset:3072 sc0
	global_load_dword v80, v41, s[6:7]
	s_waitcnt vmcnt(5)
	s_cmp_lt_u32 s14, 16384
	s_cbranch_scc1 .Lfin_prompt_f
	v_mul_f32_e32 v42, v0, v0
	v_fmac_f32_e32 v42, v1, v1
	v_fmac_f32_e32 v42, v2, v2
	v_fmac_f32_e32 v42, v3, v3
	v_fmac_f32_e32 v42, v4, v4
	v_fmac_f32_e32 v42, v5, v5
	v_fmac_f32_e32 v42, v6, v6
	v_fmac_f32_e32 v42, v7, v7
	v_fmac_f32_e32 v42, v8, v8
	v_fmac_f32_e32 v42, v9, v9
	v_fmac_f32_e32 v42, v10, v10
	v_fmac_f32_e32 v42, v11, v11
	v_fmac_f32_e32 v42, v12, v12
	v_fmac_f32_e32 v42, v13, v13
	v_fmac_f32_e32 v42, v14, v14
	v_fmac_f32_e32 v42, v15, v15
	s_branch .Lfin_sum_f

; __device__ __forceinline__ void final_phase(const Params& p) {
;     ...
;   for (int row = blockIdx.x * 8 + wave; row < MT; row += gridDim.x * 8) {
;     float s = (lane < 16) ? part[(size_t)row * 16 + lane] : 0.f;
;     s = wsum64(s);
;     const float rs = rsqrtf(s * (1.0f / 1024.0f) + 1e-6f);
;     float* xr = p.out + (size_t)row * 1024;
; #pragma unroll
;     for (int i = 0; i < 4; i++) {
;       float4 v = *(float4*)(xr + i * 256 + lane * 4);
.Lfin_loop:
	s_mov_b32 s13, 0
	s_add_u32 s2, s2, s12
	s_cmp_ge_u32 s2, 16896
	s_cbranch_scc1 .Lfin_nomore_a
	s_mov_b32 s14, s2
	s_lshl_b32 s4, s2, 12
	s_add_u32 s8, s94, s4
	s_addc_u32 s9, s95, 0
	s_lshl_b32 s4, s2, 6
	s_add_u32 s6, s96, s4
	s_addc_u32 s7, s97, 0
	global_load_dwordx4 v[0:3], v40, s[8:9] sc0
	global_load_dwordx4 v[4:7], v40, s[8:9] offset:1024 sc0
	global_load_dwordx4 v[8:11], v40, s[8:9] offset:2048 sc0
	global_load_dwordx4 v[12:15], v40, s[8:9] offset:3072 sc0
	global_load_dword v32, v41, s[6:7]
	s_waitcnt vmcnt(9)
	s_branch .Lfin_go_a

; __device__ __forceinline__ void final_phase(const Params& p) {
;     ...
;     float s = (lane < 16) ? part[(size_t)row * 16 + lane] : 0.f;
;     s = wsum64(s);
;     const float rs = rsqrtf(s * (1.0f / 1024.0f) + 1e-6f);
;     float* xr = p.out + (size_t)row * 1024;
; #pragma unroll
;     for (int i = 0; i < 4; i++) {
;       float4 v = *(float4*)(xr + i * 256 + lane * 4);
;       float4 gg = *(const float4*)(g + i * 256 + lane * 4);
;       v.x *= rs * gg.x; v.y *= rs * gg.y; v.z *= rs * gg.z; v.w *= rs * gg.w;
;       *(float4*)(xr + i * 256 + lane * 4) = v;
;     }
.Lfin_sum_a:
	s_nop 1
	v_add_f32_dpp v42, v42, v42 quad_perm:[1,0,3,2] row_mask:0xf bank_mask:0xf
	s_nop 1
	v_add_f32_dpp v42, v42, v42 quad_perm:[2,3,0,1] row_mask:0xf bank_mask:0xf
	s_nop 1
	v_add_f32_dpp v42, v42, v42 row_half_mirror row_mask:0xf bank_mask:0xf
	s_nop 1
	v_add_f32_dpp v42, v42, v42 row_mirror row_mask:0xf bank_mask:0xf
	v_mov_b32_e32 v43, v42
	s_nop 1
	v_permlane16_swap_b32_e32 v43, v42
	v_add_f32_e32 v42, v42, v43
	v_mov_b32_e32 v43, v42
	s_nop 1
	v_permlane32_swap_b32_e32 v43, v42
	v_add_f32_e32 v42, v42, v43
	v_mov_b32_e32 v43, 0x358637bd
	v_fmamk_f32 v42, v42, 0x3a800000, v43
	v_rsq_f32_e32 v42, v42
	s_nop 0
	v_mul_f32_e32 v44, v42, v16
	v_mul_f32_e32 v48, v48, v44
	v_mul_f32_e32 v45, v42, v17
	v_mul_f32_e32 v49, v49, v45
	v_mul_f32_e32 v46, v42, v18
	v_mul_f32_e32 v50, v50, v46
	v_mul_f32_e32 v47, v42, v19
	v_mul_f32_e32 v51, v51, v47
	v_mul_f32_e32 v44, v42, v20
	v_mul_f32_e32 v52, v52, v44
	v_mul_f32_e32 v45, v42, v21
	v_mul_f32_e32 v53, v53, v45
	v_mul_f32_e32 v46, v42, v22
	v_mul_f32_e32 v54, v54, v46
	v_mul_f32_e32 v47, v42, v23
	v_mul_f32_e32 v55, v55, v47
	v_mul_f32_e32 v44, v42, v24
	v_mul_f32_e32 v56, v56, v44
	v_mul_f32_e32 v45, v42, v25
	v_mul_f32_e32 v57, v57, v45
	v_mul_f32_e32 v46, v42, v26
	v_mul_f32_e32 v58, v58, v46
	v_mul_f32_e32 v47, v42, v27
	v_mul_f32_e32 v59, v59, v47
	v_mul_f32_e32 v44, v42, v28
	v_mul_f32_e32 v60, v60, v44
	v_mul_f32_e32 v45, v42, v29
	v_mul_f32_e32 v61, v61, v45
	v_mul_f32_e32 v46, v42, v30
	v_mul_f32_e32 v62, v62, v46
	v_mul_f32_e32 v47, v42, v31
	v_mul_f32_e32 v63, v63, v47
	global_store_dwordx4 v40, v[48:51], s[10:11]
	global_store_dwordx4 v40, v[52:55], s[10:11] offset:1024
	global_store_dwordx4 v40, v[56:59], s[10:11] offset:2048
	global_store_dwordx4 v40, v[60:63], s[10:11] offset:3072
	s_cmp_eq_u32 s13, 1
	s_cbranch_scc1 .Lfin_done
	s_mov_b32 s13, 0
	s_add_u32 s2, s2, s12
	s_cmp_ge_u32 s2, 16896
	s_cbranch_scc1 .Lfin_nomore_b
	s_mov_b32 s15, s2
	s_lshl_b32 s4, s2, 12
	s_add_u32 s10, s94, s4
	s_addc_u32 s11, s95, 0
	s_lshl_b32 s4, s2, 6
	s_add_u32 s6, s96, s4
	s_addc_u32 s7, s97, 0
	global_load_dwordx4 v[48:51], v40, s[10:11] sc0
	global_load_dwordx4 v[52:55], v40, s[10:11] offset:1024 sc0
	global_load_dwordx4 v[56:59], v40, s[10:11] offset:2048 sc0
	global_load_dwordx4 v[60:63], v40, s[10:11] offset:3072 sc0
	global_load_dword v80, v41, s[6:7]
	s_waitcnt vmcnt(9)
	s_branch .Lfin_go_b
